# GEMM K-loops: the seven next-stage pointer-select scalar instructions moved from the loop head to the tail in front of the back-edge branch and barrier
# baseline (speedup 1.0000x reference)
; template <class Epi>
; __device__ __forceinline__ void gemm_phase(const int TID, const int BID, LAS unsigned char* lds, const Gemm g, const StaticOrder& S, const Epi& E) {
;     ...
;         const bool has_next = S.next(ui + 1, nxt);
;         const char* nA = has_next ? (const char*)g.A + (size_t)nxt.pm * tstepA : cA; const char* nB = has_next ? (const char*)g.Bt + (size_t)nxt.pn * tstepB : cB;
;         for (int t = 0; t < nt; t += 2) {
;             const bool last = (t == nt - 2);
;             const char* a1 = cA + (size_t)(t + 1) * kstep;
;             const char* a2 = last ? nA : cA + (size_t)(t + 2) * kstep; const char* b2 = last ? nB : cB + (size_t)(t + 2) * kstep;
;     ...
;         for (int a = 0; a < 2; ++a)
; #pragma unroll
;             for (int b = 0; b < 2; ++b)
; #pragma unroll
;                 for (int m = 0; m < 4; ++m)
; #pragma unroll
;                     for (int n = 0; n < 2; ++n) acc[a][b][m][n] = (f32x4){0.f, 0.f, 0.f, 0.f};
;         cur = nxt; cA = nA; cB = nB; ++ui;
.LBB0_798:
	s_ashr_i32 s17, s16, 31
	v_cmp_lt_i64_e32 vcc, s[18:19], v[164:165]
	s_lshl_b64 s[18:19], s[16:17], 20
	s_add_u32 s18, s84, s18
	s_addc_u32 s19, s85, s19
	s_and_b64 s[20:21], vcc, exec
	s_cselect_b32 s17, s19, s25
	s_cselect_b32 s52, s18, s24
	s_ashr_i32 s15, s14, 31
	s_lshl_b64 s[20:21], s[14:15], 20
	s_add_u32 s20, s4, s20
	s_addc_u32 s21, s30, s21
	s_and_b64 s[28:29], vcc, exec
	s_cselect_b32 s15, s21, s27
	s_cselect_b32 s53, s20, s26
	s_add_u32 s24, s24, 0x80080
	s_addc_u32 s25, s25, 0
	s_add_u32 s54, s26, 0x100
	v_mov_b32_e32 v0, 0
	s_addc_u32 s55, s27, 0
	s_mov_b32 s56, -2
	v_mov_b32_e32 v1, v0
	v_mov_b32_e32 v2, v0
	v_mov_b32_e32 v3, v0
	v_mov_b32_e32 v4, v0
	v_mov_b32_e32 v5, v0
	v_mov_b32_e32 v6, v0
	v_mov_b32_e32 v7, v0
	v_mov_b32_e32 v16, v0
	v_mov_b32_e32 v17, v0
	v_mov_b32_e32 v18, v0
	v_mov_b32_e32 v19, v0
	v_mov_b32_e32 v20, v0
	v_mov_b32_e32 v21, v0
	v_mov_b32_e32 v22, v0
	v_mov_b32_e32 v23, v0
	s_waitcnt vmcnt(0)
	v_mov_b32_e32 v32, v0
	v_mov_b32_e32 v33, v0
	v_mov_b32_e32 v34, v0
	v_mov_b32_e32 v35, v0
	v_mov_b32_e32 v36, v0
	v_mov_b32_e32 v37, v0
	v_mov_b32_e32 v38, v0
	v_mov_b32_e32 v39, v0
	v_mov_b32_e32 v48, v0
	v_mov_b32_e32 v49, v0
	v_mov_b32_e32 v50, v0
	v_mov_b32_e32 v51, v0
	v_mov_b32_e32 v52, v0
	v_mov_b32_e32 v53, v0
	v_mov_b32_e32 v54, v0
	v_mov_b32_e32 v55, v0
	v_mov_b32_e32 v8, v0
	v_mov_b32_e32 v9, v0
	v_mov_b32_e32 v10, v0
	v_mov_b32_e32 v11, v0
	v_mov_b32_e32 v12, v0
	v_mov_b32_e32 v13, v0
	v_mov_b32_e32 v14, v0
	v_mov_b32_e32 v15, v0
	v_mov_b32_e32 v24, v0
	v_mov_b32_e32 v25, v0
	v_mov_b32_e32 v26, v0
	v_mov_b32_e32 v27, v0
	v_mov_b32_e32 v28, v0
	v_mov_b32_e32 v29, v0
	v_mov_b32_e32 v30, v0
	v_mov_b32_e32 v31, v0
	v_mov_b32_e32 v40, v0
	v_mov_b32_e32 v41, v0
	v_mov_b32_e32 v42, v0
	v_mov_b32_e32 v43, v0
	v_mov_b32_e32 v44, v0
	v_mov_b32_e32 v45, v0
	v_mov_b32_e32 v46, v0
	v_mov_b32_e32 v47, v0
	v_mov_b32_e32 v56, v0
	v_mov_b32_e32 v57, v0
	v_mov_b32_e32 v58, v0
	v_mov_b32_e32 v59, v0
	v_mov_b32_e32 v60, v0
	v_mov_b32_e32 v61, v0
	v_mov_b32_e32 v62, v0
	v_mov_b32_e32 v63, v0
	v_mov_b32_e32 v64, v0
	v_mov_b32_e32 v65, v0
	v_mov_b32_e32 v66, v0
	v_mov_b32_e32 v67, v0
	v_mov_b32_e32 v68, v0
	v_mov_b32_e32 v69, v0
	v_mov_b32_e32 v70, v0
	v_mov_b32_e32 v71, v0
	v_mov_b32_e32 v80, v0
	v_mov_b32_e32 v81, v0
	v_mov_b32_e32 v82, v0
	v_mov_b32_e32 v83, v0
	v_mov_b32_e32 v84, v0
	v_mov_b32_e32 v85, v0
	v_mov_b32_e32 v86, v0
	v_mov_b32_e32 v87, v0
	v_mov_b32_e32 v96, v0
	v_mov_b32_e32 v97, v0
	v_mov_b32_e32 v98, v0
	v_mov_b32_e32 v99, v0
	v_mov_b32_e32 v100, v0
	v_mov_b32_e32 v101, v0
	v_mov_b32_e32 v102, v0
	v_mov_b32_e32 v103, v0
	v_mov_b32_e32 v112, v0
	v_mov_b32_e32 v113, v0
	v_mov_b32_e32 v114, v0
	v_mov_b32_e32 v115, v0
	v_mov_b32_e32 v116, v0
	v_mov_b32_e32 v117, v0
	v_mov_b32_e32 v118, v0
	v_mov_b32_e32 v119, v0
	v_mov_b32_e32 v72, v0
	v_mov_b32_e32 v73, v0
	v_mov_b32_e32 v74, v0
	v_mov_b32_e32 v75, v0
	v_mov_b32_e32 v76, v0
	v_mov_b32_e32 v77, v0
	v_mov_b32_e32 v78, v0
	v_mov_b32_e32 v79, v0
	v_mov_b32_e32 v88, v0
	v_mov_b32_e32 v89, v0
	v_mov_b32_e32 v90, v0
	v_mov_b32_e32 v91, v0
	v_mov_b32_e32 v92, v0
	v_mov_b32_e32 v93, v0
	v_mov_b32_e32 v94, v0
	v_mov_b32_e32 v95, v0
	v_mov_b32_e32 v104, v0
	v_mov_b32_e32 v105, v0
	v_mov_b32_e32 v106, v0
	v_mov_b32_e32 v107, v0
	v_mov_b32_e32 v108, v0
	v_mov_b32_e32 v109, v0
	v_mov_b32_e32 v110, v0
	v_mov_b32_e32 v111, v0
	v_mov_b32_e32 v120, v0
	v_mov_b32_e32 v121, v0
	v_mov_b32_e32 v122, v0
	v_mov_b32_e32 v123, v0
	v_mov_b32_e32 v124, v0
	v_mov_b32_e32 v125, v0
	v_mov_b32_e32 v126, v0
	v_mov_b32_e32 v127, v0
	s_add_u32 s26, s24, 0xfff80080
	s_addc_u32 s27, s25, -1
	s_cmp_eq_u32 s56, 28
	s_cselect_b32 s29, s17, s27
	s_cselect_b32 s28, s52, s26
	s_cselect_b32 s27, s15, s55
	s_cselect_b32 s26, s53, s54
	s_branch .LBB0_799

; #define PG8_STAGE(bufoff, gbase, voff) do { _Pragma("unroll") for (int _i = 0; _i < 2; ++_i) \
;         __builtin_amdgcn_global_load_lds((const unsigned*)((const char*)(gbase) + (voff)[_i]), (LAS unsigned*)(lds + (bufoff) + ldsw + _i * 8192), 16, 0, 0); } while (0)
; #define PG8_LDA(dst, b, h) do { _Pragma("unroll") for (int m = 0; m < 4; ++m) _Pragma("unroll") for (int k = 0; k < 2; ++k) dst[m][k] = *(const LAS bf16x8*)(lds + PG8_SA(b, h) + aoff + m * 2048 + k * 1024); } while (0)
; #define PG8_LDB(dst, b, h) do { _Pragma("unroll") for (int n = 0; n < 2; ++n) _Pragma("unroll") for (int k = 0; k < 2; ++k) dst[n][k] = *(const LAS bf16x8*)(lds + PG8_SB(b, h) + boff + n * 2048 + k * 1024); } while (0)
; #define PG8_MMA(ai, bj, At, Bt) do { __builtin_amdgcn_s_setprio(1); _Pragma("unroll") for (int m = 0; m < 4; ++m) _Pragma("unroll") for (int n = 0; n < 2; ++n) _Pragma("unroll") for (int k = 0; k < 2; ++k) \
;         acc[ai][bj][m][n] = __builtin_amdgcn_mfma_f32_16x16x32_bf16(Bt[n][k], At[m][k], acc[ai][bj][m][n], 0, 0, 0); __builtin_amdgcn_s_setprio(0); } while (0)
; #define PG8_WAIT_V(n) asm volatile("s_waitcnt vmcnt(" #n ")" ::: "memory")
; #define PG8_WAIT_L(n) asm volatile("s_waitcnt lgkmcnt(" #n ")" ::: "memory")
; #define PG8_BAR __builtin_amdgcn_s_barrier()
; template <class Epi>
; __device__ __forceinline__ void gemm_phase(const int TID, const int BID, LAS unsigned char* lds, const Gemm g, const StaticOrder& S, const Epi& E) {
;     ...
;             const bool last = (t == nt - 2);
;             const char* a1 = cA + (size_t)(t + 1) * kstep;
;             const char* a2 = last ? nA : cA + (size_t)(t + 2) * kstep; const char* b2 = last ? nB : cB + (size_t)(t + 2) * kstep;
;             const char* a3 = a2 + kstep; const char* b3 = b2 + kstep;
;             PG8_LDB(B0, 0, 0); PG8_SCHED; PG8_LDA(At, 0, 0); PG8_STAGE(PG8_SA(1, 1), a1 + hstepA, voffA);
;             PG8_WAIT_L(8); PG8_BAR; PG8_WAIT_L(0); PG8_MMA(0, 0, At, B0); PG8_BAR; PG8_SCHED;
;             PG8_LDB(B1, 0, 1); PG8_STAGE(PG8_SB(0, 0), b2, voffB);
;             PG8_BAR; PG8_WAIT_L(0); PG8_MMA(0, 1, At, B1); PG8_BAR;
;             PG8_LDA(At, 0, 1); PG8_STAGE(PG8_SA(0, 0), a2, voffA);
;             PG8_BAR; PG8_WAIT_L(0); PG8_MMA(1, 0, At, B0); PG8_BAR; PG8_SCHED;
;             PG8_STAGE(PG8_SB(0, 1), b2 + hstepB, voffB);
;             PG8_WAIT_V(6); PG8_BAR; PG8_MMA(1, 1, At, B1); PG8_BAR;
.LBB0_799:
	v_add_u32_e32 v173, s23, v170
	ds_read_b128 v[138:141], v173
	ds_read_b128 v[142:145], v173 offset:1024
	ds_read_b128 v[174:177], v173 offset:2048
	ds_read_b128 v[178:181], v173 offset:3072
	v_lshl_add_u64 v[200:201], s[24:25], 0, v[134:135]
	s_add_i32 m0, s35, 0xc000
	ds_read_b128 v[182:185], v172
	ds_read_b128 v[196:199], v172 offset:1024
	ds_read_b128 v[208:211], v172 offset:2048
	ds_read_b128 v[212:215], v172 offset:3072
	ds_read_b128 v[216:219], v172 offset:4096
	ds_read_b128 v[220:223], v172 offset:5120
	ds_read_b128 v[224:227], v172 offset:6144
	ds_read_b128 v[228:231], v172 offset:7168
	global_load_lds_dwordx4 v[200:201], off
	s_add_i32 m0, s35, 0xe000
	v_lshl_add_u64 v[200:201], s[24:25], 0, v[136:137]
	global_load_lds_dwordx4 v[200:201], off
	s_waitcnt lgkmcnt(8)
	s_barrier
	s_waitcnt lgkmcnt(0)
	s_setprio 1
	v_mfma_f32_16x16x32_bf16 v[124:127], v[138:141], v[182:185], v[124:127]
	v_mfma_f32_16x16x32_bf16 v[120:123], v[174:177], v[182:185], v[120:123]
	v_mfma_f32_16x16x32_bf16 v[108:111], v[138:141], v[208:211], v[108:111]
	v_mfma_f32_16x16x32_bf16 v[104:107], v[174:177], v[208:211], v[104:107]
	v_mfma_f32_16x16x32_bf16 v[92:95], v[138:141], v[216:219], v[92:95]
	v_mfma_f32_16x16x32_bf16 v[88:91], v[174:177], v[216:219], v[88:91]
	v_mfma_f32_16x16x32_bf16 v[76:79], v[138:141], v[224:227], v[76:79]
	v_mfma_f32_16x16x32_bf16 v[72:75], v[174:177], v[224:227], v[72:75]
	v_mfma_f32_16x16x32_bf16 v[124:127], v[142:145], v[196:199], v[124:127]
	v_mfma_f32_16x16x32_bf16 v[120:123], v[178:181], v[196:199], v[120:123]
	v_mfma_f32_16x16x32_bf16 v[108:111], v[142:145], v[212:215], v[108:111]
	v_mfma_f32_16x16x32_bf16 v[104:107], v[178:181], v[212:215], v[104:107]
	v_mfma_f32_16x16x32_bf16 v[92:95], v[142:145], v[220:223], v[92:95]
	v_mfma_f32_16x16x32_bf16 v[88:91], v[178:181], v[220:223], v[88:91]
	v_mfma_f32_16x16x32_bf16 v[76:79], v[142:145], v[228:231], v[76:79]
	v_mfma_f32_16x16x32_bf16 v[72:75], v[178:181], v[228:231], v[72:75]
	s_setprio 0
	s_barrier
	s_mov_b32 m0, s31
	v_add_u32_e32 v173, s37, v170
	v_lshl_add_u64 v[200:201], s[26:27], 0, v[160:161]
	ds_read_b128 v[232:235], v173
	ds_read_b128 v[236:239], v173 offset:1024
	ds_read_b128 v[240:243], v173 offset:2048
	ds_read_b128 v[244:247], v173 offset:3072
	global_load_lds_dwordx4 v[200:201], off
	s_mov_b32 m0, s34
	v_lshl_add_u64 v[248:249], s[26:27], 0, v[132:133]
	global_load_lds_dwordx4 v[248:249], off
	s_barrier
	s_waitcnt lgkmcnt(0)
	s_setprio 1
	v_mfma_f32_16x16x32_bf16 v[116:119], v[232:235], v[182:185], v[116:119]
	v_mfma_f32_16x16x32_bf16 v[112:115], v[240:243], v[182:185], v[112:115]
	v_mfma_f32_16x16x32_bf16 v[100:103], v[232:235], v[208:211], v[100:103]
	v_mfma_f32_16x16x32_bf16 v[96:99], v[240:243], v[208:211], v[96:99]
	v_mfma_f32_16x16x32_bf16 v[84:87], v[232:235], v[216:219], v[84:87]
	v_mfma_f32_16x16x32_bf16 v[80:83], v[240:243], v[216:219], v[80:83]
	v_mfma_f32_16x16x32_bf16 v[68:71], v[232:235], v[224:227], v[68:71]
	v_mfma_f32_16x16x32_bf16 v[64:67], v[240:243], v[224:227], v[64:67]
	v_mfma_f32_16x16x32_bf16 v[116:119], v[236:239], v[196:199], v[116:119]
	v_mfma_f32_16x16x32_bf16 v[112:115], v[244:247], v[196:199], v[112:115]
	v_mfma_f32_16x16x32_bf16 v[100:103], v[236:239], v[212:215], v[100:103]
	v_mfma_f32_16x16x32_bf16 v[96:99], v[244:247], v[212:215], v[96:99]
	v_mfma_f32_16x16x32_bf16 v[84:87], v[236:239], v[220:223], v[84:87]
	v_mfma_f32_16x16x32_bf16 v[80:83], v[244:247], v[220:223], v[80:83]
	v_mfma_f32_16x16x32_bf16 v[68:71], v[236:239], v[228:231], v[68:71]
	v_mfma_f32_16x16x32_bf16 v[64:67], v[244:247], v[228:231], v[64:67]
	s_setprio 0
	s_mov_b32 m0, s35
	v_lshl_add_u64 v[250:251], s[28:29], 0, v[128:129]
	s_barrier
	ds_read_b128 v[182:185], v172 offset:16384
	ds_read_b128 v[196:199], v172 offset:17408
	ds_read_b128 v[208:211], v172 offset:18432
	ds_read_b128 v[212:215], v172 offset:19456
	ds_read_b128 v[216:219], v172 offset:20480
	ds_read_b128 v[220:223], v172 offset:21504
	ds_read_b128 v[224:227], v172 offset:22528
	ds_read_b128 v[228:231], v172 offset:23552
	global_load_lds_dwordx4 v[250:251], off
	s_mov_b32 m0, s36
	v_lshl_add_u64 v[252:253], s[28:29], 0, v[130:131]
	global_load_lds_dwordx4 v[252:253], off
	s_barrier
	s_waitcnt lgkmcnt(0)
	s_setprio 1
	v_mfma_f32_16x16x32_bf16 v[60:63], v[138:141], v[182:185], v[60:63]
	v_mfma_f32_16x16x32_bf16 v[56:59], v[174:177], v[182:185], v[56:59]
	v_mfma_f32_16x16x32_bf16 v[44:47], v[138:141], v[208:211], v[44:47]
	v_mfma_f32_16x16x32_bf16 v[40:43], v[174:177], v[208:211], v[40:43]
	v_mfma_f32_16x16x32_bf16 v[28:31], v[138:141], v[216:219], v[28:31]
	v_mfma_f32_16x16x32_bf16 v[24:27], v[174:177], v[216:219], v[24:27]
	v_mfma_f32_16x16x32_bf16 v[12:15], v[138:141], v[224:227], v[12:15]
	v_mfma_f32_16x16x32_bf16 v[8:11], v[174:177], v[224:227], v[8:11]
	v_mfma_f32_16x16x32_bf16 v[60:63], v[142:145], v[196:199], v[60:63]
	v_mfma_f32_16x16x32_bf16 v[56:59], v[178:181], v[196:199], v[56:59]
	v_mfma_f32_16x16x32_bf16 v[44:47], v[142:145], v[212:215], v[44:47]
	v_mfma_f32_16x16x32_bf16 v[40:43], v[178:181], v[212:215], v[40:43]
	v_mfma_f32_16x16x32_bf16 v[28:31], v[142:145], v[220:223], v[28:31]
	v_mfma_f32_16x16x32_bf16 v[24:27], v[178:181], v[220:223], v[24:27]
	v_mfma_f32_16x16x32_bf16 v[12:15], v[142:145], v[228:231], v[12:15]
	v_mfma_f32_16x16x32_bf16 v[8:11], v[178:181], v[228:231], v[8:11]
	s_setprio 0
	s_barrier
	s_add_u32 s58, s26, 0x80000
	s_addc_u32 s59, s27, 0
	s_mov_b32 m0, s38
	v_lshl_add_u64 v[138:139], s[58:59], 0, v[160:161]
	global_load_lds_dwordx4 v[138:139], off
	s_mov_b32 m0, s39
	v_lshl_add_u64 v[138:139], s[58:59], 0, v[132:133]
	global_load_lds_dwordx4 v[138:139], off
	s_waitcnt vmcnt(6)
	s_barrier
; #define PG8_STAGE(bufoff, gbase, voff) do { _Pragma("unroll") for (int _i = 0; _i < 2; ++_i) \
;         __builtin_amdgcn_global_load_lds((const unsigned*)((const char*)(gbase) + (voff)[_i]), (LAS unsigned*)(lds + (bufoff) + ldsw + _i * 8192), 16, 0, 0); } while (0)
; #define PG8_LDA(dst, b, h) do { _Pragma("unroll") for (int m = 0; m < 4; ++m) _Pragma("unroll") for (int k = 0; k < 2; ++k) dst[m][k] = *(const LAS bf16x8*)(lds + PG8_SA(b, h) + aoff + m * 2048 + k * 1024); } while (0)
; #define PG8_LDB(dst, b, h) do { _Pragma("unroll") for (int n = 0; n < 2; ++n) _Pragma("unroll") for (int k = 0; k < 2; ++k) dst[n][k] = *(const LAS bf16x8*)(lds + PG8_SB(b, h) + boff + n * 2048 + k * 1024); } while (0)
; #define PG8_MMA(ai, bj, At, Bt) do { __builtin_amdgcn_s_setprio(1); _Pragma("unroll") for (int m = 0; m < 4; ++m) _Pragma("unroll") for (int n = 0; n < 2; ++n) _Pragma("unroll") for (int k = 0; k < 2; ++k) \
;         acc[ai][bj][m][n] = __builtin_amdgcn_mfma_f32_16x16x32_bf16(Bt[n][k], At[m][k], acc[ai][bj][m][n], 0, 0, 0); __builtin_amdgcn_s_setprio(0); } while (0)
; #define PG8_WAIT_V(n) asm volatile("s_waitcnt vmcnt(" #n ")" ::: "memory")
; #define PG8_WAIT_L(n) asm volatile("s_waitcnt lgkmcnt(" #n ")" ::: "memory")
; #define PG8_BAR __builtin_amdgcn_s_barrier()
; #define PG8_SCHED __builtin_amdgcn_sched_barrier(0)
; template <class Epi>
; __device__ __forceinline__ void gemm_phase(const int TID, const int BID, LAS unsigned char* lds, const Gemm g, const StaticOrder& S, const Epi& E) {
;     ...
;             PG8_WAIT_V(6); PG8_BAR; PG8_MMA(1, 1, At, B1); PG8_BAR;
;             PG8_LDB(B0, 1, 0); PG8_SCHED; PG8_LDA(At, 1, 0); PG8_STAGE(PG8_SA(0, 1), a2 + hstepA, voffA);
;             PG8_WAIT_L(8); PG8_BAR; PG8_WAIT_L(0); PG8_MMA(0, 0, At, B0); PG8_BAR; PG8_SCHED;
;             PG8_LDB(B1, 1, 1); PG8_STAGE(PG8_SB(1, 0), b3, voffB);
;             PG8_BAR; PG8_WAIT_L(0); PG8_MMA(0, 1, At, B1); PG8_BAR;
;             PG8_LDA(At, 1, 1); PG8_STAGE(PG8_SA(1, 0), a3, voffA);
;             PG8_BAR; PG8_WAIT_L(0); PG8_MMA(1, 0, At, B0); PG8_BAR; PG8_SCHED;
	s_setprio 1
	v_mfma_f32_16x16x32_bf16 v[52:55], v[232:235], v[182:185], v[52:55]
	v_mfma_f32_16x16x32_bf16 v[48:51], v[240:243], v[182:185], v[48:51]
	v_mfma_f32_16x16x32_bf16 v[36:39], v[232:235], v[208:211], v[36:39]
	v_mfma_f32_16x16x32_bf16 v[32:35], v[240:243], v[208:211], v[32:35]
	v_mfma_f32_16x16x32_bf16 v[20:23], v[232:235], v[216:219], v[20:23]
	v_mfma_f32_16x16x32_bf16 v[16:19], v[240:243], v[216:219], v[16:19]
	v_mfma_f32_16x16x32_bf16 v[4:7], v[232:235], v[224:227], v[4:7]
	v_mfma_f32_16x16x32_bf16 v[0:3], v[240:243], v[224:227], v[0:3]
	v_mfma_f32_16x16x32_bf16 v[52:55], v[236:239], v[196:199], v[52:55]
	v_mfma_f32_16x16x32_bf16 v[48:51], v[244:247], v[196:199], v[48:51]
	v_mfma_f32_16x16x32_bf16 v[36:39], v[236:239], v[212:215], v[36:39]
	v_mfma_f32_16x16x32_bf16 v[32:35], v[244:247], v[212:215], v[32:35]
	v_mfma_f32_16x16x32_bf16 v[20:23], v[236:239], v[220:223], v[20:23]
	v_mfma_f32_16x16x32_bf16 v[16:19], v[244:247], v[220:223], v[16:19]
	v_mfma_f32_16x16x32_bf16 v[4:7], v[236:239], v[228:231], v[4:7]
	v_mfma_f32_16x16x32_bf16 v[0:3], v[244:247], v[228:231], v[0:3]
	s_setprio 0
	v_add_u32_e32 v173, s42, v170
	s_barrier
	ds_read_b128 v[138:141], v173
	ds_read_b128 v[142:145], v173 offset:1024
	ds_read_b128 v[174:177], v173 offset:2048
	ds_read_b128 v[178:181], v173 offset:3072
	s_add_u32 s28, s28, 0x80000
	s_addc_u32 s29, s29, 0
	s_mov_b32 m0, s40
	v_lshl_add_u64 v[232:233], s[28:29], 0, v[128:129]
	ds_read_b128 v[182:185], v172 offset:32768
	ds_read_b128 v[196:199], v172 offset:33792
	ds_read_b128 v[208:211], v172 offset:34816
	ds_read_b128 v[212:215], v172 offset:35840
	ds_read_b128 v[216:219], v172 offset:36864
	ds_read_b128 v[220:223], v172 offset:37888
	ds_read_b128 v[224:227], v172 offset:38912
	ds_read_b128 v[228:231], v172 offset:39936
	global_load_lds_dwordx4 v[232:233], off
	s_mov_b32 m0, s41
	v_lshl_add_u64 v[232:233], s[28:29], 0, v[130:131]
	global_load_lds_dwordx4 v[232:233], off
	s_waitcnt lgkmcnt(8)
	s_barrier
	s_waitcnt lgkmcnt(0)
	s_setprio 1
	v_mfma_f32_16x16x32_bf16 v[124:127], v[138:141], v[182:185], v[124:127]
	v_mfma_f32_16x16x32_bf16 v[120:123], v[174:177], v[182:185], v[120:123]
	v_mfma_f32_16x16x32_bf16 v[108:111], v[138:141], v[208:211], v[108:111]
	v_mfma_f32_16x16x32_bf16 v[104:107], v[174:177], v[208:211], v[104:107]
	v_mfma_f32_16x16x32_bf16 v[92:95], v[138:141], v[216:219], v[92:95]
	v_mfma_f32_16x16x32_bf16 v[88:91], v[174:177], v[216:219], v[88:91]
	v_mfma_f32_16x16x32_bf16 v[76:79], v[138:141], v[224:227], v[76:79]
	v_mfma_f32_16x16x32_bf16 v[72:75], v[174:177], v[224:227], v[72:75]
	v_mfma_f32_16x16x32_bf16 v[124:127], v[142:145], v[196:199], v[124:127]
	v_mfma_f32_16x16x32_bf16 v[120:123], v[178:181], v[196:199], v[120:123]
	v_mfma_f32_16x16x32_bf16 v[108:111], v[142:145], v[212:215], v[108:111]
	v_mfma_f32_16x16x32_bf16 v[104:107], v[178:181], v[212:215], v[104:107]
	v_mfma_f32_16x16x32_bf16 v[92:95], v[142:145], v[220:223], v[92:95]
	v_mfma_f32_16x16x32_bf16 v[88:91], v[178:181], v[220:223], v[88:91]
	v_mfma_f32_16x16x32_bf16 v[76:79], v[142:145], v[228:231], v[76:79]
	v_mfma_f32_16x16x32_bf16 v[72:75], v[178:181], v[228:231], v[72:75]
	s_setprio 0
	s_barrier
	s_mov_b32 m0, s43
	v_add_u32_e32 v173, s47, v170
	v_lshl_add_u64 v[200:201], v[200:201], 0, s[90:91]
	ds_read_b128 v[232:235], v173
	ds_read_b128 v[236:239], v173 offset:1024
	ds_read_b128 v[240:243], v173 offset:2048
	ds_read_b128 v[244:247], v173 offset:3072
	global_load_lds_dwordx4 v[200:201], off
	s_mov_b32 m0, s44
	v_lshl_add_u64 v[200:201], v[248:249], 0, s[90:91]
	global_load_lds_dwordx4 v[200:201], off
	s_barrier
	s_waitcnt lgkmcnt(0)
	s_setprio 1
	v_mfma_f32_16x16x32_bf16 v[116:119], v[232:235], v[182:185], v[116:119]
	v_mfma_f32_16x16x32_bf16 v[112:115], v[240:243], v[182:185], v[112:115]
	v_mfma_f32_16x16x32_bf16 v[100:103], v[232:235], v[208:211], v[100:103]
	v_mfma_f32_16x16x32_bf16 v[96:99], v[240:243], v[208:211], v[96:99]
	v_mfma_f32_16x16x32_bf16 v[84:87], v[232:235], v[216:219], v[84:87]
	v_mfma_f32_16x16x32_bf16 v[80:83], v[240:243], v[216:219], v[80:83]
	v_mfma_f32_16x16x32_bf16 v[68:71], v[232:235], v[224:227], v[68:71]
	v_mfma_f32_16x16x32_bf16 v[64:67], v[240:243], v[224:227], v[64:67]
	v_mfma_f32_16x16x32_bf16 v[116:119], v[236:239], v[196:199], v[116:119]
	v_mfma_f32_16x16x32_bf16 v[112:115], v[244:247], v[196:199], v[112:115]
	v_mfma_f32_16x16x32_bf16 v[100:103], v[236:239], v[212:215], v[100:103]
	v_mfma_f32_16x16x32_bf16 v[96:99], v[244:247], v[212:215], v[96:99]
	v_mfma_f32_16x16x32_bf16 v[84:87], v[236:239], v[220:223], v[84:87]
	v_mfma_f32_16x16x32_bf16 v[80:83], v[244:247], v[220:223], v[80:83]
	v_mfma_f32_16x16x32_bf16 v[68:71], v[236:239], v[228:231], v[68:71]
	v_mfma_f32_16x16x32_bf16 v[64:67], v[244:247], v[228:231], v[64:67]
	s_setprio 0
	s_mov_b32 m0, s45
	v_lshl_add_u64 v[200:201], v[250:251], 0, s[90:91]
	s_barrier
	ds_read_b128 v[182:185], v172 offset:49152
	ds_read_b128 v[196:199], v172 offset:50176
	ds_read_b128 v[208:211], v172 offset:51200
	ds_read_b128 v[212:215], v172 offset:52224
	ds_read_b128 v[216:219], v172 offset:53248
	ds_read_b128 v[220:223], v172 offset:54272
	ds_read_b128 v[224:227], v172 offset:55296
	ds_read_b128 v[228:231], v172 offset:56320
	global_load_lds_dwordx4 v[200:201], off
	s_mov_b32 m0, s46
	v_lshl_add_u64 v[200:201], v[252:253], 0, s[90:91]
	global_load_lds_dwordx4 v[200:201], off
	s_barrier
; __device__ __forceinline__ unsigned cvt_pk_bf16(float lo, float hi) { unsigned r; asm volatile("v_cvt_pk_bf16_f32 %0, %1, %2" : "=v"(r) : "v"(lo), "v"(hi)); return r; }
; __device__ __forceinline__ float rinv_st(stat_t s, float invn) { return rsqrtf((float)((double)s * (1.0 / 4294967296.0)) * invn + 1e-6f); }
; #define PG8_STAGE(bufoff, gbase, voff) do { _Pragma("unroll") for (int _i = 0; _i < 2; ++_i) \
;         __builtin_amdgcn_global_load_lds((const unsigned*)((const char*)(gbase) + (voff)[_i]), (LAS unsigned*)(lds + (bufoff) + ldsw + _i * 8192), 16, 0, 0); } while (0)
; #define PG8_MMA(ai, bj, At, Bt) do { __builtin_amdgcn_s_setprio(1); _Pragma("unroll") for (int m = 0; m < 4; ++m) _Pragma("unroll") for (int n = 0; n < 2; ++n) _Pragma("unroll") for (int k = 0; k < 2; ++k) \
;         acc[ai][bj][m][n] = __builtin_amdgcn_mfma_f32_16x16x32_bf16(Bt[n][k], At[m][k], acc[ai][bj][m][n], 0, 0, 0); __builtin_amdgcn_s_setprio(0); } while (0)
; #define PG8_WAIT_V(n) asm volatile("s_waitcnt vmcnt(" #n ")" ::: "memory")
; #define PG8_BAR __builtin_amdgcn_s_barrier()
; template <class Epi>
; __device__ __forceinline__ void gemm_phase(const int TID, const int BID, LAS unsigned char* lds, const Gemm g, const StaticOrder& S, const Epi& E) {
;     ...
;             PG8_BAR; PG8_WAIT_L(0); PG8_MMA(1, 0, At, B0); PG8_BAR; PG8_SCHED;
;             PG8_STAGE(PG8_SB(1, 1), b3 + hstepB, voffB);
;             PG8_WAIT_V(6); PG8_BAR; PG8_MMA(1, 1, At, B1); PG8_BAR;
;     __device__ __forceinline__ void operator()(const f32x4 (&acc)[2][2][4][2], const Unit& u, int wr, int wc, int fr, int fq) const {
;         const int row0 = u.pm * BM + wr * 64 + fr, col0 = u.pn * BM + wc * 32 + 8 * fq;
; #pragma unroll
;         for (int ai = 0; ai < 2; ++ai)
; #pragma unroll
;             for (int m = 0; m < 4; ++m) {
;                 const int row = row0 + ai * HALF + m * 16; const float r = rinv_st(stats[row], 1.0f / 2048.0f);
;                 bf16_t* rowp = raw + (size_t)row * NINP + col0;
; #pragma unroll
;                 for (int bj = 0; bj < 2; ++bj) {
;                     const f32x4 v0 = acc[ai][bj][m][0] * r, v1 = acc[ai][bj][m][1] * r;
;                     u32x4 w; w.x = cvt_pk_bf16(v0[0], v0[1]); w.y = cvt_pk_bf16(v0[2], v0[3]); w.z = cvt_pk_bf16(v1[0], v1[1]); w.w = cvt_pk_bf16(v1[2], v1[3]);
;                     *(u32x4*)(rowp + bj * HALF) = w;
;                 }
;             }
	s_waitcnt lgkmcnt(0)
	s_setprio 1
	v_mfma_f32_16x16x32_bf16 v[60:63], v[138:141], v[182:185], v[60:63]
	v_mfma_f32_16x16x32_bf16 v[56:59], v[174:177], v[182:185], v[56:59]
	v_mfma_f32_16x16x32_bf16 v[44:47], v[138:141], v[208:211], v[44:47]
	v_mfma_f32_16x16x32_bf16 v[40:43], v[174:177], v[208:211], v[40:43]
	v_mfma_f32_16x16x32_bf16 v[28:31], v[138:141], v[216:219], v[28:31]
	v_mfma_f32_16x16x32_bf16 v[24:27], v[174:177], v[216:219], v[24:27]
	v_mfma_f32_16x16x32_bf16 v[12:15], v[138:141], v[224:227], v[12:15]
	v_mfma_f32_16x16x32_bf16 v[8:11], v[174:177], v[224:227], v[8:11]
	v_mfma_f32_16x16x32_bf16 v[60:63], v[142:145], v[196:199], v[60:63]
	v_mfma_f32_16x16x32_bf16 v[56:59], v[178:181], v[196:199], v[56:59]
	v_mfma_f32_16x16x32_bf16 v[44:47], v[142:145], v[212:215], v[44:47]
	v_mfma_f32_16x16x32_bf16 v[40:43], v[178:181], v[212:215], v[40:43]
	v_mfma_f32_16x16x32_bf16 v[28:31], v[142:145], v[220:223], v[28:31]
	v_mfma_f32_16x16x32_bf16 v[24:27], v[178:181], v[220:223], v[24:27]
	v_mfma_f32_16x16x32_bf16 v[12:15], v[142:145], v[228:231], v[12:15]
	v_mfma_f32_16x16x32_bf16 v[8:11], v[178:181], v[228:231], v[8:11]
	s_setprio 0
	s_barrier
	s_add_u32 s26, s26, 0x80080
	s_addc_u32 s27, s27, 0
	s_mov_b32 m0, s48
	v_lshl_add_u64 v[138:139], s[26:27], 0, v[160:161]
	global_load_lds_dwordx4 v[138:139], off
	s_mov_b32 m0, s49
	v_lshl_add_u64 v[138:139], s[26:27], 0, v[132:133]
	global_load_lds_dwordx4 v[138:139], off
	s_waitcnt vmcnt(6)
	s_barrier
	s_setprio 1
	v_mfma_f32_16x16x32_bf16 v[52:55], v[232:235], v[182:185], v[52:55]
	v_mfma_f32_16x16x32_bf16 v[48:51], v[240:243], v[182:185], v[48:51]
	v_mfma_f32_16x16x32_bf16 v[36:39], v[232:235], v[208:211], v[36:39]
	v_mfma_f32_16x16x32_bf16 v[32:35], v[240:243], v[208:211], v[32:35]
	v_mfma_f32_16x16x32_bf16 v[20:23], v[232:235], v[216:219], v[20:23]
	v_mfma_f32_16x16x32_bf16 v[16:19], v[240:243], v[216:219], v[16:19]
	v_mfma_f32_16x16x32_bf16 v[4:7], v[232:235], v[224:227], v[4:7]
	v_mfma_f32_16x16x32_bf16 v[0:3], v[240:243], v[224:227], v[0:3]
	v_mfma_f32_16x16x32_bf16 v[52:55], v[236:239], v[196:199], v[52:55]
	v_mfma_f32_16x16x32_bf16 v[48:51], v[244:247], v[196:199], v[48:51]
	v_mfma_f32_16x16x32_bf16 v[36:39], v[236:239], v[212:215], v[36:39]
	v_mfma_f32_16x16x32_bf16 v[32:35], v[244:247], v[212:215], v[32:35]
	v_mfma_f32_16x16x32_bf16 v[20:23], v[236:239], v[220:223], v[20:23]
	v_mfma_f32_16x16x32_bf16 v[16:19], v[244:247], v[220:223], v[16:19]
	v_mfma_f32_16x16x32_bf16 v[4:7], v[236:239], v[228:231], v[4:7]
	v_mfma_f32_16x16x32_bf16 v[0:3], v[244:247], v[228:231], v[0:3]
	s_setprio 0
	s_add_i32 s56, s56, 2
	s_add_u32 s24, s24, 0x100
	s_addc_u32 s25, s25, 0
	s_add_u32 s54, s54, 0x100
	s_addc_u32 s55, s55, 0
	s_add_u32 s26, s24, 0xfff80080
	s_addc_u32 s27, s25, -1
	s_cmp_eq_u32 s56, 28
	s_cselect_b32 s29, s17, s27
	s_cselect_b32 s28, s52, s26
	s_cselect_b32 s27, s15, s55
	s_cselect_b32 s26, s53, s54
	s_cmp_gt_u32 s56, 29
	s_cbranch_scc0 .Lrot_799
	s_barrier
	v_lshl_add_u32 v138, s22, 8, v169
	v_ashrrev_i32_e32 v139, 31, v138
	v_lshl_add_u64 v[140:141], v[138:139], 3, s[10:11]
	global_load_dwordx2 v[142:143], v[140:141], off
	global_load_dwordx2 v[208:209], v[140:141], off offset:128
	global_load_dwordx2 v[210:211], v[140:141], off offset:256
	global_load_dwordx2 v[212:213], v[140:141], off offset:384
	global_load_dwordx2 v[214:215], v[140:141], off offset:1024
	global_load_dwordx2 v[216:217], v[140:141], off offset:1152
	global_load_dwordx2 v[218:219], v[140:141], off offset:1280
	global_load_dwordx2 v[220:221], v[140:141], off offset:1408
	v_lshl_or_b32 v144, s51, 8, v171
	v_ashrrev_i32_e32 v145, 31, v144
	s_movk_i32 s15, 0x2200
	v_lshlrev_b64 v[144:145], 1, v[144:145]
	s_mov_b32 s51, s14
	s_mov_b32 s22, s16
	s_mov_b64 s[26:27], s[20:21]
	s_waitcnt vmcnt(0)
	v_cvt_f64_u32_e32 v[174:175], v143
	v_ldexp_f64 v[174:175], v[174:175], 32
	v_cvt_f64_u32_e32 v[142:143], v142
	v_add_f64 v[142:143], v[174:175], v[142:143]
	v_ldexp_f64 v[142:143], v[142:143], s93
	v_cvt_f32_f64_e32 v139, v[142:143]
	v_fmamk_f32 v139, v139, 0x3a000000, v189
	v_cmp_gt_f32_e32 vcc, s78, v139
	v_mul_f32_e32 v142, 0x4b800000, v139
	s_nop 0
	v_cndmask_b32_e32 v139, v139, v142, vcc
	v_rsq_f32_e32 v139, v139
	s_nop 0
	v_mul_f32_e32 v142, 0x45800000, v139
	v_cndmask_b32_e32 v174, v139, v142, vcc
	v_mov_b64_e32 v[142:143], s[12:13]
	v_mad_i64_i32 v[176:177], s[24:25], v138, s15, v[142:143]
	v_lshl_add_u64 v[176:177], v[176:177], 0, v[144:145]
	v_pk_mul_f32 v[126:127], v[126:127], v[174:175] op_sel_hi:[1,0]
	v_pk_mul_f32 v[124:125], v[124:125], v[174:175] op_sel_hi:[1,0]
	v_pk_mul_f32 v[178:179], v[122:123], v[174:175] op_sel_hi:[1,0]
	v_pk_mul_f32 v[122:123], v[120:121], v[174:175] op_sel_hi:[1,0]
	v_cvt_pk_bf16_f32 v120, v124, v125
	v_cvt_pk_bf16_f32 v121, v126, v127
	v_pk_mul_f32 v[116:117], v[116:117], v[174:175] op_sel_hi:[1,0]
	v_cvt_pk_bf16_f32 v122, v122, v123
	v_cvt_pk_bf16_f32 v123, v178, v179
	global_store_dwordx4 v[176:177], v[120:123], off
	v_pk_mul_f32 v[118:119], v[118:119], v[174:175] op_sel_hi:[1,0]
	s_nop 0
	v_pk_mul_f32 v[120:121], v[114:115], v[174:175] op_sel_hi:[1,0]
	v_pk_mul_f32 v[114:115], v[112:113], v[174:175] op_sel_hi:[1,0]
	v_cvt_pk_bf16_f32 v112, v116, v117
	v_cvt_pk_bf16_f32 v113, v118, v119
	s_nop 0
	v_cvt_pk_bf16_f32 v114, v114, v115
	v_cvt_pk_bf16_f32 v115, v120, v121
	global_store_dwordx4 v[176:177], v[112:115], off offset:256
	s_nop 1
	v_or_b32_e32 v112, 16, v138
	v_ashrrev_i32_e32 v113, 31, v112
	v_lshl_add_u64 v[114:115], v[112:113], 3, s[10:11]
	s_nop 1
	v_mov_b64_e32 v[114:115], v[208:209]
	v_cvt_f64_u32_e32 v[116:117], v115
	v_ldexp_f64 v[116:117], v[116:117], 32
; __device__ __forceinline__ unsigned cvt_pk_bf16(float lo, float hi) { unsigned r; asm volatile("v_cvt_pk_bf16_f32 %0, %1, %2" : "=v"(r) : "v"(lo), "v"(hi)); return r; }
; __device__ __forceinline__ float rinv_st(stat_t s, float invn) { return rsqrtf((float)((double)s * (1.0 / 4294967296.0)) * invn + 1e-6f); }
;     __device__ __forceinline__ void operator()(const f32x4 (&acc)[2][2][4][2], const Unit& u, int wr, int wc, int fr, int fq) const {
;     ...
;         for (int ai = 0; ai < 2; ++ai)
; #pragma unroll
;             for (int m = 0; m < 4; ++m) {
;                 const int row = row0 + ai * HALF + m * 16; const float r = rinv_st(stats[row], 1.0f / 2048.0f);
;                 bf16_t* rowp = raw + (size_t)row * NINP + col0;
; #pragma unroll
;                 for (int bj = 0; bj < 2; ++bj) {
;                     const f32x4 v0 = acc[ai][bj][m][0] * r, v1 = acc[ai][bj][m][1] * r;
;                     u32x4 w; w.x = cvt_pk_bf16(v0[0], v0[1]); w.y = cvt_pk_bf16(v0[2], v0[3]); w.z = cvt_pk_bf16(v1[0], v1[1]); w.w = cvt_pk_bf16(v1[2], v1[3]);
;                     *(u32x4*)(rowp + bj * HALF) = w;
;                 }
;             }
	v_cvt_f64_u32_e32 v[114:115], v114
	v_add_f64 v[114:115], v[116:117], v[114:115]
	v_ldexp_f64 v[114:115], v[114:115], s93
	v_cvt_f32_f64_e32 v113, v[114:115]
	v_fmamk_f32 v113, v113, 0x3a000000, v189
	v_cmp_gt_f32_e32 vcc, s78, v113
	v_mul_f32_e32 v114, 0x4b800000, v113
	s_nop 0
	v_cndmask_b32_e32 v113, v113, v114, vcc
	v_rsq_f32_e32 v113, v113
	s_nop 0
	v_mul_f32_e32 v114, 0x45800000, v113
	v_cndmask_b32_e32 v114, v113, v114, vcc
	v_mad_i64_i32 v[112:113], s[24:25], v112, s15, v[142:143]
	v_lshl_add_u64 v[112:113], v[112:113], 0, v[144:145]
	v_pk_mul_f32 v[110:111], v[110:111], v[114:115] op_sel_hi:[1,0]
	v_pk_mul_f32 v[108:109], v[108:109], v[114:115] op_sel_hi:[1,0]
	v_pk_mul_f32 v[116:117], v[106:107], v[114:115] op_sel_hi:[1,0]
	v_pk_mul_f32 v[106:107], v[104:105], v[114:115] op_sel_hi:[1,0]
	v_cvt_pk_bf16_f32 v104, v108, v109
	v_cvt_pk_bf16_f32 v105, v110, v111
	v_pk_mul_f32 v[100:101], v[100:101], v[114:115] op_sel_hi:[1,0]
	v_cvt_pk_bf16_f32 v106, v106, v107
	v_cvt_pk_bf16_f32 v107, v116, v117
	global_store_dwordx4 v[112:113], v[104:107], off
	v_pk_mul_f32 v[102:103], v[102:103], v[114:115] op_sel_hi:[1,0]
	s_nop 0
	v_pk_mul_f32 v[104:105], v[98:99], v[114:115] op_sel_hi:[1,0]
	v_pk_mul_f32 v[98:99], v[96:97], v[114:115] op_sel_hi:[1,0]
	v_cvt_pk_bf16_f32 v96, v100, v101
	v_cvt_pk_bf16_f32 v97, v102, v103
	s_nop 0
	v_cvt_pk_bf16_f32 v98, v98, v99
	v_cvt_pk_bf16_f32 v99, v104, v105
	global_store_dwordx4 v[112:113], v[96:99], off offset:256
	s_nop 1
	v_or_b32_e32 v96, 32, v138
	v_ashrrev_i32_e32 v97, 31, v96
	v_lshl_add_u64 v[98:99], v[96:97], 3, s[10:11]
	s_nop 1
	v_mov_b64_e32 v[98:99], v[210:211]
	v_cvt_f64_u32_e32 v[100:101], v99
	v_ldexp_f64 v[100:101], v[100:101], 32
	v_cvt_f64_u32_e32 v[98:99], v98
	v_add_f64 v[98:99], v[100:101], v[98:99]
	v_ldexp_f64 v[98:99], v[98:99], s93
	v_cvt_f32_f64_e32 v97, v[98:99]
	v_fmamk_f32 v97, v97, 0x3a000000, v189
	v_cmp_gt_f32_e32 vcc, s78, v97
	v_mul_f32_e32 v98, 0x4b800000, v97
	s_nop 0
	v_cndmask_b32_e32 v97, v97, v98, vcc
	v_rsq_f32_e32 v97, v97
	s_nop 0
	v_mul_f32_e32 v98, 0x45800000, v97
	v_cndmask_b32_e32 v98, v97, v98, vcc
	v_mad_i64_i32 v[96:97], s[24:25], v96, s15, v[142:143]
	v_lshl_add_u64 v[96:97], v[96:97], 0, v[144:145]
	v_pk_mul_f32 v[94:95], v[94:95], v[98:99] op_sel_hi:[1,0]
	v_pk_mul_f32 v[92:93], v[92:93], v[98:99] op_sel_hi:[1,0]
	v_pk_mul_f32 v[100:101], v[90:91], v[98:99] op_sel_hi:[1,0]
	v_pk_mul_f32 v[90:91], v[88:89], v[98:99] op_sel_hi:[1,0]
	v_cvt_pk_bf16_f32 v88, v92, v93
	v_cvt_pk_bf16_f32 v89, v94, v95
	v_pk_mul_f32 v[84:85], v[84:85], v[98:99] op_sel_hi:[1,0]
	v_cvt_pk_bf16_f32 v90, v90, v91
	v_cvt_pk_bf16_f32 v91, v100, v101
	global_store_dwordx4 v[96:97], v[88:91], off
	v_pk_mul_f32 v[86:87], v[86:87], v[98:99] op_sel_hi:[1,0]
	s_nop 0
	v_pk_mul_f32 v[88:89], v[82:83], v[98:99] op_sel_hi:[1,0]
	v_pk_mul_f32 v[82:83], v[80:81], v[98:99] op_sel_hi:[1,0]
	v_cvt_pk_bf16_f32 v80, v84, v85
	v_cvt_pk_bf16_f32 v81, v86, v87
	s_nop 0
	v_cvt_pk_bf16_f32 v82, v82, v83
	v_cvt_pk_bf16_f32 v83, v88, v89
	global_store_dwordx4 v[96:97], v[80:83], off offset:256
	s_nop 1
	v_or_b32_e32 v80, 48, v138
	v_ashrrev_i32_e32 v81, 31, v80
	v_lshl_add_u64 v[82:83], v[80:81], 3, s[10:11]
	s_nop 1
	v_mov_b64_e32 v[82:83], v[212:213]
	v_cvt_f64_u32_e32 v[84:85], v83
	v_ldexp_f64 v[84:85], v[84:85], 32
	v_cvt_f64_u32_e32 v[82:83], v82
	v_add_f64 v[82:83], v[84:85], v[82:83]
	v_ldexp_f64 v[82:83], v[82:83], s93
	v_cvt_f32_f64_e32 v81, v[82:83]
	v_fmamk_f32 v81, v81, 0x3a000000, v189
	v_cmp_gt_f32_e32 vcc, s78, v81
	v_mul_f32_e32 v82, 0x4b800000, v81
	s_nop 0
	v_cndmask_b32_e32 v81, v81, v82, vcc
	v_rsq_f32_e32 v81, v81
	s_nop 0
	v_mul_f32_e32 v82, 0x45800000, v81
	v_cndmask_b32_e32 v82, v81, v82, vcc
	v_mad_i64_i32 v[80:81], s[24:25], v80, s15, v[142:143]
	v_lshl_add_u64 v[80:81], v[80:81], 0, v[144:145]
	v_pk_mul_f32 v[78:79], v[78:79], v[82:83] op_sel_hi:[1,0]
	v_pk_mul_f32 v[76:77], v[76:77], v[82:83] op_sel_hi:[1,0]
	v_pk_mul_f32 v[84:85], v[74:75], v[82:83] op_sel_hi:[1,0]
	v_pk_mul_f32 v[74:75], v[72:73], v[82:83] op_sel_hi:[1,0]
	v_cvt_pk_bf16_f32 v72, v76, v77
	v_cvt_pk_bf16_f32 v73, v78, v79
	v_pk_mul_f32 v[70:71], v[70:71], v[82:83] op_sel_hi:[1,0]
	v_cvt_pk_bf16_f32 v74, v74, v75
	v_cvt_pk_bf16_f32 v75, v84, v85
	global_store_dwordx4 v[80:81], v[72:75], off
	v_pk_mul_f32 v[68:69], v[68:69], v[82:83] op_sel_hi:[1,0]
	s_nop 0
	v_pk_mul_f32 v[72:73], v[66:67], v[82:83] op_sel_hi:[1,0]
	v_pk_mul_f32 v[66:67], v[64:65], v[82:83] op_sel_hi:[1,0]
	v_cvt_pk_bf16_f32 v64, v68, v69
	v_cvt_pk_bf16_f32 v65, v70, v71
	v_add_u32_e32 v68, 0x80, v138
	v_cvt_pk_bf16_f32 v66, v66, v67
	v_cvt_pk_bf16_f32 v67, v72, v73
	global_store_dwordx4 v[80:81], v[64:67], off offset:256
	s_nop 1
	v_mov_b64_e32 v[64:65], v[214:215]
	v_cvt_f64_u32_e32 v[66:67], v65
	v_ldexp_f64 v[66:67], v[66:67], 32
	v_cvt_f64_u32_e32 v[64:65], v64
	v_add_f64 v[64:65], v[66:67], v[64:65]
	v_ldexp_f64 v[64:65], v[64:65], s93
	v_cvt_f32_f64_e32 v64, v[64:65]
	v_fmamk_f32 v64, v64, 0x3a000000, v189
	v_cmp_gt_f32_e32 vcc, s78, v64
	v_mul_f32_e32 v65, 0x4b800000, v64
	v_mad_i64_i32 v[66:67], s[24:25], v68, s15, v[142:143]
	v_cndmask_b32_e32 v64, v64, v65, vcc
	v_rsq_f32_e32 v64, v64
	v_lshl_add_u64 v[66:67], v[66:67], 0, v[144:145]
	v_mul_f32_e32 v65, 0x45800000, v64
	v_cndmask_b32_e32 v64, v64, v65, vcc
	v_pk_mul_f32 v[62:63], v[62:63], v[64:65] op_sel_hi:[1,0]
; __device__ __forceinline__ unsigned cvt_pk_bf16(float lo, float hi) { unsigned r; asm volatile("v_cvt_pk_bf16_f32 %0, %1, %2" : "=v"(r) : "v"(lo), "v"(hi)); return r; }
; __device__ __forceinline__ float rinv_st(stat_t s, float invn) { return rsqrtf((float)((double)s * (1.0 / 4294967296.0)) * invn + 1e-6f); }
; #define PG8_WAIT_V(n) asm volatile("s_waitcnt vmcnt(" #n ")" ::: "memory")
; #define PG8_BAR __builtin_amdgcn_s_barrier()
; template <class Epi>
; __device__ __forceinline__ void gemm_phase(const int TID, const int BID, LAS unsigned char* lds, const Gemm g, const StaticOrder& S, const Epi& E) {
;     ...
;         if (!has_next) break;
; #pragma unroll
;         for (int a = 0; a < 2; ++a)
; #pragma unroll
;             for (int b = 0; b < 2; ++b)
; #pragma unroll
;                 for (int m = 0; m < 4; ++m)
; #pragma unroll
;                     for (int n = 0; n < 2; ++n) acc[a][b][m][n] = (f32x4){0.f, 0.f, 0.f, 0.f};
;         cur = nxt; cA = nA; cB = nB; ++ui;
;     }
;     PG8_WAIT_V(0);
;     if (wr == 0) PG8_BAR;
;     PG8_BAR;
;     __device__ __forceinline__ void operator()(const f32x4 (&acc)[2][2][4][2], const Unit& u, int wr, int wc, int fr, int fq) const {
;     ...
;         for (int ai = 0; ai < 2; ++ai)
; #pragma unroll
;             for (int m = 0; m < 4; ++m) {
;                 const int row = row0 + ai * HALF + m * 16; const float r = rinv_st(stats[row], 1.0f / 2048.0f);
;                 bf16_t* rowp = raw + (size_t)row * NINP + col0;
; #pragma unroll
;                 for (int bj = 0; bj < 2; ++bj) {
;                     const f32x4 v0 = acc[ai][bj][m][0] * r, v1 = acc[ai][bj][m][1] * r;
;                     u32x4 w; w.x = cvt_pk_bf16(v0[0], v0[1]); w.y = cvt_pk_bf16(v0[2], v0[3]); w.z = cvt_pk_bf16(v1[0], v1[1]); w.w = cvt_pk_bf16(v1[2], v1[3]);
;                     *(u32x4*)(rowp + bj * HALF) = w;
;                 }
;             }
	v_pk_mul_f32 v[60:61], v[60:61], v[64:65] op_sel_hi:[1,0]
	v_pk_mul_f32 v[68:69], v[58:59], v[64:65] op_sel_hi:[1,0]
	v_pk_mul_f32 v[58:59], v[56:57], v[64:65] op_sel_hi:[1,0]
	v_cvt_pk_bf16_f32 v56, v60, v61
	v_cvt_pk_bf16_f32 v57, v62, v63
	v_pk_mul_f32 v[54:55], v[54:55], v[64:65] op_sel_hi:[1,0]
	v_cvt_pk_bf16_f32 v58, v58, v59
	v_cvt_pk_bf16_f32 v59, v68, v69
	global_store_dwordx4 v[66:67], v[56:59], off
	v_pk_mul_f32 v[52:53], v[52:53], v[64:65] op_sel_hi:[1,0]
	s_nop 0
	v_pk_mul_f32 v[56:57], v[50:51], v[64:65] op_sel_hi:[1,0]
	v_pk_mul_f32 v[50:51], v[48:49], v[64:65] op_sel_hi:[1,0]
	v_cvt_pk_bf16_f32 v48, v52, v53
	v_cvt_pk_bf16_f32 v49, v54, v55
	v_add_u32_e32 v52, 0x90, v138
	v_cvt_pk_bf16_f32 v50, v50, v51
	v_cvt_pk_bf16_f32 v51, v56, v57
	global_store_dwordx4 v[66:67], v[48:51], off offset:256
	s_nop 1
	v_mov_b64_e32 v[48:49], v[216:217]
	v_cvt_f64_u32_e32 v[50:51], v49
	v_ldexp_f64 v[50:51], v[50:51], 32
	v_cvt_f64_u32_e32 v[48:49], v48
	v_add_f64 v[48:49], v[50:51], v[48:49]
	v_ldexp_f64 v[48:49], v[48:49], s93
	v_cvt_f32_f64_e32 v48, v[48:49]
	v_fmamk_f32 v48, v48, 0x3a000000, v189
	v_cmp_gt_f32_e32 vcc, s78, v48
	v_mul_f32_e32 v49, 0x4b800000, v48
	v_mad_i64_i32 v[50:51], s[24:25], v52, s15, v[142:143]
	v_cndmask_b32_e32 v48, v48, v49, vcc
	v_rsq_f32_e32 v48, v48
	v_lshl_add_u64 v[50:51], v[50:51], 0, v[144:145]
	v_mul_f32_e32 v49, 0x45800000, v48
	v_cndmask_b32_e32 v48, v48, v49, vcc
	v_pk_mul_f32 v[46:47], v[46:47], v[48:49] op_sel_hi:[1,0]
	v_pk_mul_f32 v[44:45], v[44:45], v[48:49] op_sel_hi:[1,0]
	v_pk_mul_f32 v[52:53], v[42:43], v[48:49] op_sel_hi:[1,0]
	v_pk_mul_f32 v[42:43], v[40:41], v[48:49] op_sel_hi:[1,0]
	v_cvt_pk_bf16_f32 v40, v44, v45
	v_cvt_pk_bf16_f32 v41, v46, v47
	v_pk_mul_f32 v[38:39], v[38:39], v[48:49] op_sel_hi:[1,0]
	v_cvt_pk_bf16_f32 v42, v42, v43
	v_cvt_pk_bf16_f32 v43, v52, v53
	global_store_dwordx4 v[50:51], v[40:43], off
	v_pk_mul_f32 v[36:37], v[36:37], v[48:49] op_sel_hi:[1,0]
	s_nop 0
	v_pk_mul_f32 v[40:41], v[34:35], v[48:49] op_sel_hi:[1,0]
	v_pk_mul_f32 v[34:35], v[32:33], v[48:49] op_sel_hi:[1,0]
	v_cvt_pk_bf16_f32 v32, v36, v37
	v_cvt_pk_bf16_f32 v33, v38, v39
	v_add_u32_e32 v36, 0xa0, v138
	v_cvt_pk_bf16_f32 v34, v34, v35
	v_cvt_pk_bf16_f32 v35, v40, v41
	global_store_dwordx4 v[50:51], v[32:35], off offset:256
	s_nop 1
	v_mov_b64_e32 v[32:33], v[218:219]
	v_cvt_f64_u32_e32 v[34:35], v33
	v_ldexp_f64 v[34:35], v[34:35], 32
	v_cvt_f64_u32_e32 v[32:33], v32
	v_add_f64 v[32:33], v[34:35], v[32:33]
	v_ldexp_f64 v[32:33], v[32:33], s93
	v_cvt_f32_f64_e32 v32, v[32:33]
	v_fmamk_f32 v32, v32, 0x3a000000, v189
	v_cmp_gt_f32_e32 vcc, s78, v32
	v_mul_f32_e32 v33, 0x4b800000, v32
	v_mad_i64_i32 v[34:35], s[24:25], v36, s15, v[142:143]
	v_cndmask_b32_e32 v32, v32, v33, vcc
	v_rsq_f32_e32 v32, v32
	v_lshl_add_u64 v[34:35], v[34:35], 0, v[144:145]
	v_mul_f32_e32 v33, 0x45800000, v32
	v_cndmask_b32_e32 v32, v32, v33, vcc
	v_pk_mul_f32 v[30:31], v[30:31], v[32:33] op_sel_hi:[1,0]
	v_pk_mul_f32 v[28:29], v[28:29], v[32:33] op_sel_hi:[1,0]
	v_pk_mul_f32 v[36:37], v[26:27], v[32:33] op_sel_hi:[1,0]
	v_pk_mul_f32 v[26:27], v[24:25], v[32:33] op_sel_hi:[1,0]
	v_cvt_pk_bf16_f32 v24, v28, v29
	v_cvt_pk_bf16_f32 v25, v30, v31
	v_pk_mul_f32 v[22:23], v[22:23], v[32:33] op_sel_hi:[1,0]
	v_cvt_pk_bf16_f32 v26, v26, v27
	v_cvt_pk_bf16_f32 v27, v36, v37
	global_store_dwordx4 v[34:35], v[24:27], off
	v_pk_mul_f32 v[20:21], v[20:21], v[32:33] op_sel_hi:[1,0]
	s_nop 0
	v_pk_mul_f32 v[24:25], v[18:19], v[32:33] op_sel_hi:[1,0]
	v_pk_mul_f32 v[18:19], v[16:17], v[32:33] op_sel_hi:[1,0]
	v_cvt_pk_bf16_f32 v16, v20, v21
	v_cvt_pk_bf16_f32 v17, v22, v23
	v_add_u32_e32 v20, 0xb0, v138
	v_cvt_pk_bf16_f32 v18, v18, v19
	v_cvt_pk_bf16_f32 v19, v24, v25
	global_store_dwordx4 v[34:35], v[16:19], off offset:256
	s_nop 1
	v_mov_b64_e32 v[16:17], v[220:221]
	v_cvt_f64_u32_e32 v[18:19], v17
	v_ldexp_f64 v[18:19], v[18:19], 32
	v_cvt_f64_u32_e32 v[16:17], v16
	v_add_f64 v[16:17], v[18:19], v[16:17]
	v_ldexp_f64 v[16:17], v[16:17], s93
	v_cvt_f32_f64_e32 v16, v[16:17]
	v_fmamk_f32 v16, v16, 0x3a000000, v189
	v_cmp_gt_f32_e32 vcc, s78, v16
	v_mul_f32_e32 v17, 0x4b800000, v16
	v_mad_i64_i32 v[18:19], s[24:25], v20, s15, v[142:143]
	v_cndmask_b32_e32 v16, v16, v17, vcc
	v_rsq_f32_e32 v16, v16
	v_lshl_add_u64 v[18:19], v[18:19], 0, v[144:145]
	s_mov_b64 s[24:25], s[18:19]
	v_mul_f32_e32 v17, 0x45800000, v16
	v_cndmask_b32_e32 v16, v16, v17, vcc
	v_pk_mul_f32 v[14:15], v[14:15], v[16:17] op_sel_hi:[1,0]
	v_pk_mul_f32 v[12:13], v[12:13], v[16:17] op_sel_hi:[1,0]
	v_pk_mul_f32 v[20:21], v[10:11], v[16:17] op_sel_hi:[1,0]
	v_pk_mul_f32 v[10:11], v[8:9], v[16:17] op_sel_hi:[1,0]
	v_cvt_pk_bf16_f32 v8, v12, v13
	v_cvt_pk_bf16_f32 v9, v14, v15
	s_and_b64 vcc, exec, s[8:9]
	v_cvt_pk_bf16_f32 v10, v10, v11
	v_cvt_pk_bf16_f32 v11, v20, v21
	global_store_dwordx4 v[18:19], v[8:11], off
	v_pk_mul_f32 v[6:7], v[6:7], v[16:17] op_sel_hi:[1,0]
	v_pk_mul_f32 v[4:5], v[4:5], v[16:17] op_sel_hi:[1,0]
	v_pk_mul_f32 v[8:9], v[2:3], v[16:17] op_sel_hi:[1,0]
	v_pk_mul_f32 v[2:3], v[0:1], v[16:17] op_sel_hi:[1,0]
	v_cvt_pk_bf16_f32 v0, v4, v5
	v_cvt_pk_bf16_f32 v1, v6, v7
	s_nop 0
	v_cvt_pk_bf16_f32 v2, v2, v3
	v_cvt_pk_bf16_f32 v3, v8, v9
	global_store_dwordx4 v[18:19], v[0:3], off offset:256
	s_cbranch_vccz .LBB0_792
	s_waitcnt vmcnt(0)
	s_cmpk_gt_u32 s0, 0xff
	s_cbranch_scc1 .LBB0_803
	s_barrier

; template <class Epi>
; __device__ __forceinline__ void gemm_phase(const int TID, const int BID, LAS unsigned char* lds, const Gemm g, const StaticOrder& S, const Epi& E) {
;     ...
;         const bool has_next = S.next(ui + 1, nxt);
;         const char* nA = has_next ? (const char*)g.A + (size_t)nxt.pm * tstepA : cA; const char* nB = has_next ? (const char*)g.Bt + (size_t)nxt.pn * tstepB : cB;
;         for (int t = 0; t < nt; t += 2) {
;             const bool last = (t == nt - 2);
;             const char* a1 = cA + (size_t)(t + 1) * kstep;
;             const char* a2 = last ? nA : cA + (size_t)(t + 2) * kstep; const char* b2 = last ? nB : cB + (size_t)(t + 2) * kstep;
;     ...
;         for (int a = 0; a < 2; ++a)
; #pragma unroll
;             for (int b = 0; b < 2; ++b)
; #pragma unroll
;                 for (int m = 0; m < 4; ++m)
; #pragma unroll
;                     for (int n = 0; n < 2; ++n) acc[a][b][m][n] = (f32x4){0.f, 0.f, 0.f, 0.f};
;         cur = nxt; cA = nA; cB = nB; ++ui;
.LBB0_821:
	s_ashr_i32 s17, s16, 31
	v_cmp_lt_i64_e64 s[30:31], s[20:21], 32
	s_lshl_b64 s[20:21], s[16:17], 20
	s_add_u32 s20, s44, s20
	s_addc_u32 s21, s45, s21
	s_and_b64 s[22:23], s[30:31], exec
	s_cselect_b32 s17, s21, s27
	s_cselect_b32 s61, s20, s26
	s_ashr_i32 s15, s14, 31
	s_lshl_b64 s[22:23], s[14:15], 20
	s_add_u32 s22, s8, s22
	s_addc_u32 s23, s9, s23
	s_and_b64 s[30:31], s[30:31], exec
	s_cselect_b32 s15, s23, s29
	s_cselect_b32 s62, s22, s28
	s_add_u32 s26, s26, 0x80080
	s_addc_u32 s27, s27, 0
	s_add_u32 s63, s28, 0x100
	v_mov_b32_e32 v0, 0
	s_addc_u32 s64, s29, 0
	s_mov_b32 s66, -2
	v_mov_b32_e32 v1, v0
	v_mov_b32_e32 v2, v0
	v_mov_b32_e32 v3, v0
	v_mov_b32_e32 v4, v0
	v_mov_b32_e32 v5, v0
	v_mov_b32_e32 v6, v0
	v_mov_b32_e32 v7, v0
	v_mov_b32_e32 v16, v0
	v_mov_b32_e32 v17, v0
	v_mov_b32_e32 v18, v0
	v_mov_b32_e32 v19, v0
	v_mov_b32_e32 v20, v0
	v_mov_b32_e32 v21, v0
	v_mov_b32_e32 v22, v0
	v_mov_b32_e32 v23, v0
	s_waitcnt vmcnt(0)
	v_mov_b32_e32 v32, v0
	v_mov_b32_e32 v33, v0
	v_mov_b32_e32 v34, v0
	v_mov_b32_e32 v35, v0
	v_mov_b32_e32 v36, v0
	v_mov_b32_e32 v37, v0
	v_mov_b32_e32 v38, v0
	v_mov_b32_e32 v39, v0
	v_mov_b32_e32 v48, v0
	v_mov_b32_e32 v49, v0
	v_mov_b32_e32 v50, v0
	v_mov_b32_e32 v51, v0
	v_mov_b32_e32 v52, v0
	v_mov_b32_e32 v53, v0
	v_mov_b32_e32 v54, v0
	v_mov_b32_e32 v55, v0
	v_mov_b32_e32 v8, v0
	v_mov_b32_e32 v9, v0
	v_mov_b32_e32 v10, v0
	v_mov_b32_e32 v11, v0
	v_mov_b32_e32 v12, v0
	v_mov_b32_e32 v13, v0
	v_mov_b32_e32 v14, v0
	v_mov_b32_e32 v15, v0
	v_mov_b32_e32 v24, v0
	v_mov_b32_e32 v25, v0
	v_mov_b32_e32 v26, v0
	v_mov_b32_e32 v27, v0
	v_mov_b32_e32 v28, v0
	v_mov_b32_e32 v29, v0
	v_mov_b32_e32 v30, v0
	v_mov_b32_e32 v31, v0
	v_mov_b32_e32 v40, v0
	v_mov_b32_e32 v41, v0
	v_mov_b32_e32 v42, v0
	v_mov_b32_e32 v43, v0
	v_mov_b32_e32 v44, v0
	v_mov_b32_e32 v45, v0
	v_mov_b32_e32 v46, v0
	v_mov_b32_e32 v47, v0
	v_mov_b32_e32 v56, v0
	v_mov_b32_e32 v57, v0
	v_mov_b32_e32 v58, v0
	v_mov_b32_e32 v59, v0
	v_mov_b32_e32 v60, v0
	v_mov_b32_e32 v61, v0
	v_mov_b32_e32 v62, v0
	v_mov_b32_e32 v63, v0
	v_mov_b32_e32 v64, v0
	v_mov_b32_e32 v65, v0
	v_mov_b32_e32 v66, v0
	v_mov_b32_e32 v67, v0
	v_mov_b32_e32 v68, v0
	v_mov_b32_e32 v69, v0
	v_mov_b32_e32 v70, v0
	v_mov_b32_e32 v71, v0
	v_mov_b32_e32 v80, v0
	v_mov_b32_e32 v81, v0
	v_mov_b32_e32 v82, v0
	v_mov_b32_e32 v83, v0
	v_mov_b32_e32 v84, v0
	v_mov_b32_e32 v85, v0
	v_mov_b32_e32 v86, v0
	v_mov_b32_e32 v87, v0
	v_mov_b32_e32 v96, v0
	v_mov_b32_e32 v97, v0
	v_mov_b32_e32 v98, v0
	v_mov_b32_e32 v99, v0
	v_mov_b32_e32 v100, v0
	v_mov_b32_e32 v101, v0
	v_mov_b32_e32 v102, v0
	v_mov_b32_e32 v103, v0
	v_mov_b32_e32 v112, v0
	v_mov_b32_e32 v113, v0
	v_mov_b32_e32 v114, v0
	v_mov_b32_e32 v115, v0
	v_mov_b32_e32 v116, v0
	v_mov_b32_e32 v117, v0
	v_mov_b32_e32 v118, v0
	v_mov_b32_e32 v119, v0
	v_mov_b32_e32 v72, v0
	v_mov_b32_e32 v73, v0
	v_mov_b32_e32 v74, v0
	v_mov_b32_e32 v75, v0
	v_mov_b32_e32 v76, v0
	v_mov_b32_e32 v77, v0
	v_mov_b32_e32 v78, v0
	v_mov_b32_e32 v79, v0
	v_mov_b32_e32 v88, v0
	v_mov_b32_e32 v89, v0
	v_mov_b32_e32 v90, v0
	v_mov_b32_e32 v91, v0
	v_mov_b32_e32 v92, v0
	v_mov_b32_e32 v93, v0
	v_mov_b32_e32 v94, v0
	v_mov_b32_e32 v95, v0
	v_mov_b32_e32 v104, v0
	v_mov_b32_e32 v105, v0
	v_mov_b32_e32 v106, v0
	v_mov_b32_e32 v107, v0
	v_mov_b32_e32 v108, v0
	v_mov_b32_e32 v109, v0
	v_mov_b32_e32 v110, v0
	v_mov_b32_e32 v111, v0
	v_mov_b32_e32 v120, v0
	v_mov_b32_e32 v121, v0
	v_mov_b32_e32 v122, v0
	v_mov_b32_e32 v123, v0
	v_mov_b32_e32 v124, v0
	v_mov_b32_e32 v125, v0
	v_mov_b32_e32 v126, v0
	v_mov_b32_e32 v127, v0
	s_add_u32 s28, s26, 0xfff80080
	s_addc_u32 s29, s27, -1
	s_cmp_eq_u32 s66, 4
	s_cselect_b32 s31, s17, s29
	s_cselect_b32 s30, s61, s28
	s_cselect_b32 s29, s15, s64
	s_cselect_b32 s28, s62, s63
	s_branch .LBB0_822

; #define PG8_STAGE(bufoff, gbase, voff) do { _Pragma("unroll") for (int _i = 0; _i < 2; ++_i) \
;         __builtin_amdgcn_global_load_lds((const unsigned*)((const char*)(gbase) + (voff)[_i]), (LAS unsigned*)(lds + (bufoff) + ldsw + _i * 8192), 16, 0, 0); } while (0)
; #define PG8_LDA(dst, b, h) do { _Pragma("unroll") for (int m = 0; m < 4; ++m) _Pragma("unroll") for (int k = 0; k < 2; ++k) dst[m][k] = *(const LAS bf16x8*)(lds + PG8_SA(b, h) + aoff + m * 2048 + k * 1024); } while (0)
; #define PG8_LDB(dst, b, h) do { _Pragma("unroll") for (int n = 0; n < 2; ++n) _Pragma("unroll") for (int k = 0; k < 2; ++k) dst[n][k] = *(const LAS bf16x8*)(lds + PG8_SB(b, h) + boff + n * 2048 + k * 1024); } while (0)
; #define PG8_MMA(ai, bj, At, Bt) do { __builtin_amdgcn_s_setprio(1); _Pragma("unroll") for (int m = 0; m < 4; ++m) _Pragma("unroll") for (int n = 0; n < 2; ++n) _Pragma("unroll") for (int k = 0; k < 2; ++k) \
;         acc[ai][bj][m][n] = __builtin_amdgcn_mfma_f32_16x16x32_bf16(Bt[n][k], At[m][k], acc[ai][bj][m][n], 0, 0, 0); __builtin_amdgcn_s_setprio(0); } while (0)
; #define PG8_WAIT_V(n) asm volatile("s_waitcnt vmcnt(" #n ")" ::: "memory")
; #define PG8_WAIT_L(n) asm volatile("s_waitcnt lgkmcnt(" #n ")" ::: "memory")
; #define PG8_BAR __builtin_amdgcn_s_barrier()
; template <class Epi>
; __device__ __forceinline__ void gemm_phase(const int TID, const int BID, LAS unsigned char* lds, const Gemm g, const StaticOrder& S, const Epi& E) {
;     ...
;             const bool last = (t == nt - 2);
;             const char* a1 = cA + (size_t)(t + 1) * kstep;
;             const char* a2 = last ? nA : cA + (size_t)(t + 2) * kstep; const char* b2 = last ? nB : cB + (size_t)(t + 2) * kstep;
;             const char* a3 = a2 + kstep; const char* b3 = b2 + kstep;
;             PG8_LDB(B0, 0, 0); PG8_SCHED; PG8_LDA(At, 0, 0); PG8_STAGE(PG8_SA(1, 1), a1 + hstepA, voffA);
;             PG8_WAIT_L(8); PG8_BAR; PG8_WAIT_L(0); PG8_MMA(0, 0, At, B0); PG8_BAR; PG8_SCHED;
;             PG8_LDB(B1, 0, 1); PG8_STAGE(PG8_SB(0, 0), b2, voffB);
;             PG8_BAR; PG8_WAIT_L(0); PG8_MMA(0, 1, At, B1); PG8_BAR;
;             PG8_LDA(At, 0, 1); PG8_STAGE(PG8_SA(0, 0), a2, voffA);
;             PG8_BAR; PG8_WAIT_L(0); PG8_MMA(1, 0, At, B0); PG8_BAR; PG8_SCHED;
;             PG8_STAGE(PG8_SB(0, 1), b2 + hstepB, voffB);
;             PG8_WAIT_V(6); PG8_BAR; PG8_MMA(1, 1, At, B1); PG8_BAR;
.LBB0_822:
	v_add_u32_e32 v154, s36, v147
	ds_read_b128 v[134:137], v154
	ds_read_b128 v[138:141], v154 offset:1024
	ds_read_b128 v[150:153], v154 offset:2048
	ds_read_b128 v[154:157], v154 offset:3072
	v_lshl_add_u64 v[158:159], s[26:27], 0, v[130:131]
	s_add_i32 m0, s47, 0xc000
	ds_read_b128 v[166:169], v149
	ds_read_b128 v[170:173], v149 offset:1024
	ds_read_b128 v[174:177], v149 offset:2048
	ds_read_b128 v[178:181], v149 offset:3072
	ds_read_b128 v[182:185], v149 offset:4096
	ds_read_b128 v[196:199], v149 offset:5120
	ds_read_b128 v[208:211], v149 offset:6144
	ds_read_b128 v[212:215], v149 offset:7168
	global_load_lds_dwordx4 v[158:159], off
	s_add_i32 m0, s47, 0xe000
	v_lshl_add_u64 v[158:159], s[26:27], 0, v[132:133]
	global_load_lds_dwordx4 v[158:159], off
	s_waitcnt lgkmcnt(8)
	s_barrier
	s_waitcnt lgkmcnt(0)
	s_setprio 1
	v_mfma_f32_16x16x32_bf16 v[124:127], v[134:137], v[166:169], v[124:127]
	v_mfma_f32_16x16x32_bf16 v[120:123], v[150:153], v[166:169], v[120:123]
	v_mfma_f32_16x16x32_bf16 v[108:111], v[134:137], v[174:177], v[108:111]
	v_mfma_f32_16x16x32_bf16 v[104:107], v[150:153], v[174:177], v[104:107]
	v_mfma_f32_16x16x32_bf16 v[92:95], v[134:137], v[182:185], v[92:95]
	v_mfma_f32_16x16x32_bf16 v[88:91], v[150:153], v[182:185], v[88:91]
	v_mfma_f32_16x16x32_bf16 v[76:79], v[134:137], v[208:211], v[76:79]
	v_mfma_f32_16x16x32_bf16 v[72:75], v[150:153], v[208:211], v[72:75]
	v_mfma_f32_16x16x32_bf16 v[124:127], v[138:141], v[170:173], v[124:127]
	v_mfma_f32_16x16x32_bf16 v[120:123], v[154:157], v[170:173], v[120:123]
	v_mfma_f32_16x16x32_bf16 v[108:111], v[138:141], v[178:181], v[108:111]
	v_mfma_f32_16x16x32_bf16 v[104:107], v[154:157], v[178:181], v[104:107]
	v_mfma_f32_16x16x32_bf16 v[92:95], v[138:141], v[196:199], v[92:95]
	v_mfma_f32_16x16x32_bf16 v[88:91], v[154:157], v[196:199], v[88:91]
	v_mfma_f32_16x16x32_bf16 v[76:79], v[138:141], v[212:215], v[76:79]
	v_mfma_f32_16x16x32_bf16 v[72:75], v[154:157], v[212:215], v[72:75]
	s_setprio 0
	s_barrier
	v_add_u32_e32 v158, s37, v147
	s_mov_b32 m0, s25
	ds_read_b128 v[216:219], v158
	ds_read_b128 v[220:223], v158 offset:1024
	ds_read_b128 v[224:227], v158 offset:2048
	ds_read_b128 v[228:231], v158 offset:3072
	v_lshl_add_u64 v[158:159], s[28:29], 0, v[160:161]
	global_load_lds_dwordx4 v[158:159], off
	s_mov_b32 m0, s46
	v_lshl_add_u64 v[200:201], s[28:29], 0, v[128:129]
	global_load_lds_dwordx4 v[200:201], off
	s_barrier
	s_waitcnt lgkmcnt(0)
	s_setprio 1
	v_mfma_f32_16x16x32_bf16 v[116:119], v[216:219], v[166:169], v[116:119]
	v_mfma_f32_16x16x32_bf16 v[112:115], v[224:227], v[166:169], v[112:115]
	v_mfma_f32_16x16x32_bf16 v[100:103], v[216:219], v[174:177], v[100:103]
	v_mfma_f32_16x16x32_bf16 v[96:99], v[224:227], v[174:177], v[96:99]
	v_mfma_f32_16x16x32_bf16 v[84:87], v[216:219], v[182:185], v[84:87]
	v_mfma_f32_16x16x32_bf16 v[80:83], v[224:227], v[182:185], v[80:83]
	v_mfma_f32_16x16x32_bf16 v[68:71], v[216:219], v[208:211], v[68:71]
	v_mfma_f32_16x16x32_bf16 v[64:67], v[224:227], v[208:211], v[64:67]
	v_mfma_f32_16x16x32_bf16 v[116:119], v[220:223], v[170:173], v[116:119]
	v_mfma_f32_16x16x32_bf16 v[112:115], v[228:231], v[170:173], v[112:115]
	v_mfma_f32_16x16x32_bf16 v[100:103], v[220:223], v[178:181], v[100:103]
	v_mfma_f32_16x16x32_bf16 v[96:99], v[228:231], v[178:181], v[96:99]
	v_mfma_f32_16x16x32_bf16 v[84:87], v[220:223], v[196:199], v[84:87]
	v_mfma_f32_16x16x32_bf16 v[80:83], v[228:231], v[196:199], v[80:83]
	v_mfma_f32_16x16x32_bf16 v[68:71], v[220:223], v[212:215], v[68:71]
	v_mfma_f32_16x16x32_bf16 v[64:67], v[228:231], v[212:215], v[64:67]
	s_setprio 0
	s_mov_b32 m0, s47
	v_lshl_add_u64 v[232:233], s[30:31], 0, v[160:161]
	s_barrier
	ds_read_b128 v[166:169], v149 offset:16384
	ds_read_b128 v[170:173], v149 offset:17408
	ds_read_b128 v[174:177], v149 offset:18432
	ds_read_b128 v[178:181], v149 offset:19456
	ds_read_b128 v[182:185], v149 offset:20480
	ds_read_b128 v[196:199], v149 offset:21504
	ds_read_b128 v[208:211], v149 offset:22528
	ds_read_b128 v[212:215], v149 offset:23552
	global_load_lds_dwordx4 v[232:233], off
	s_mov_b32 m0, s48
	v_lshl_add_u64 v[234:235], s[30:31], 0, v[128:129]
	global_load_lds_dwordx4 v[234:235], off
	s_barrier
	s_waitcnt lgkmcnt(0)
	s_setprio 1
	v_mfma_f32_16x16x32_bf16 v[60:63], v[134:137], v[166:169], v[60:63]
	v_mfma_f32_16x16x32_bf16 v[56:59], v[150:153], v[166:169], v[56:59]
	v_mfma_f32_16x16x32_bf16 v[44:47], v[134:137], v[174:177], v[44:47]
	v_mfma_f32_16x16x32_bf16 v[40:43], v[150:153], v[174:177], v[40:43]
	v_mfma_f32_16x16x32_bf16 v[28:31], v[134:137], v[182:185], v[28:31]
	v_mfma_f32_16x16x32_bf16 v[24:27], v[150:153], v[182:185], v[24:27]
	v_mfma_f32_16x16x32_bf16 v[12:15], v[134:137], v[208:211], v[12:15]
	v_mfma_f32_16x16x32_bf16 v[8:11], v[150:153], v[208:211], v[8:11]
	v_mfma_f32_16x16x32_bf16 v[60:63], v[138:141], v[170:173], v[60:63]
	v_mfma_f32_16x16x32_bf16 v[56:59], v[154:157], v[170:173], v[56:59]
	v_mfma_f32_16x16x32_bf16 v[44:47], v[138:141], v[178:181], v[44:47]
	v_mfma_f32_16x16x32_bf16 v[40:43], v[154:157], v[178:181], v[40:43]
	v_mfma_f32_16x16x32_bf16 v[28:31], v[138:141], v[196:199], v[28:31]
	v_mfma_f32_16x16x32_bf16 v[24:27], v[154:157], v[196:199], v[24:27]
	v_mfma_f32_16x16x32_bf16 v[12:15], v[138:141], v[212:215], v[12:15]
	v_mfma_f32_16x16x32_bf16 v[8:11], v[154:157], v[212:215], v[8:11]
	s_setprio 0
	s_barrier
	s_add_u32 s74, s28, 0x80000
	s_addc_u32 s75, s29, 0
	s_mov_b32 m0, s49
	v_lshl_add_u64 v[134:135], s[74:75], 0, v[160:161]
	global_load_lds_dwordx4 v[134:135], off
	s_mov_b32 m0, s50
	v_lshl_add_u64 v[134:135], s[74:75], 0, v[128:129]
	global_load_lds_dwordx4 v[134:135], off
	s_waitcnt vmcnt(6)
	s_barrier
; #define PG8_STAGE(bufoff, gbase, voff) do { _Pragma("unroll") for (int _i = 0; _i < 2; ++_i) \
;         __builtin_amdgcn_global_load_lds((const unsigned*)((const char*)(gbase) + (voff)[_i]), (LAS unsigned*)(lds + (bufoff) + ldsw + _i * 8192), 16, 0, 0); } while (0)
; #define PG8_LDA(dst, b, h) do { _Pragma("unroll") for (int m = 0; m < 4; ++m) _Pragma("unroll") for (int k = 0; k < 2; ++k) dst[m][k] = *(const LAS bf16x8*)(lds + PG8_SA(b, h) + aoff + m * 2048 + k * 1024); } while (0)
; #define PG8_LDB(dst, b, h) do { _Pragma("unroll") for (int n = 0; n < 2; ++n) _Pragma("unroll") for (int k = 0; k < 2; ++k) dst[n][k] = *(const LAS bf16x8*)(lds + PG8_SB(b, h) + boff + n * 2048 + k * 1024); } while (0)
; #define PG8_MMA(ai, bj, At, Bt) do { __builtin_amdgcn_s_setprio(1); _Pragma("unroll") for (int m = 0; m < 4; ++m) _Pragma("unroll") for (int n = 0; n < 2; ++n) _Pragma("unroll") for (int k = 0; k < 2; ++k) \
;         acc[ai][bj][m][n] = __builtin_amdgcn_mfma_f32_16x16x32_bf16(Bt[n][k], At[m][k], acc[ai][bj][m][n], 0, 0, 0); __builtin_amdgcn_s_setprio(0); } while (0)
; #define PG8_WAIT_V(n) asm volatile("s_waitcnt vmcnt(" #n ")" ::: "memory")
; #define PG8_WAIT_L(n) asm volatile("s_waitcnt lgkmcnt(" #n ")" ::: "memory")
; #define PG8_BAR __builtin_amdgcn_s_barrier()
; #define PG8_SCHED __builtin_amdgcn_sched_barrier(0)
; template <class Epi>
; __device__ __forceinline__ void gemm_phase(const int TID, const int BID, LAS unsigned char* lds, const Gemm g, const StaticOrder& S, const Epi& E) {
;     ...
;             PG8_WAIT_V(6); PG8_BAR; PG8_MMA(1, 1, At, B1); PG8_BAR;
;             PG8_LDB(B0, 1, 0); PG8_SCHED; PG8_LDA(At, 1, 0); PG8_STAGE(PG8_SA(0, 1), a2 + hstepA, voffA);
;             PG8_WAIT_L(8); PG8_BAR; PG8_WAIT_L(0); PG8_MMA(0, 0, At, B0); PG8_BAR; PG8_SCHED;
;             PG8_LDB(B1, 1, 1); PG8_STAGE(PG8_SB(1, 0), b3, voffB);
;             PG8_BAR; PG8_WAIT_L(0); PG8_MMA(0, 1, At, B1); PG8_BAR;
;             PG8_LDA(At, 1, 1); PG8_STAGE(PG8_SA(1, 0), a3, voffA);
;             PG8_BAR; PG8_WAIT_L(0); PG8_MMA(1, 0, At, B0); PG8_BAR; PG8_SCHED;
	s_setprio 1
	v_mfma_f32_16x16x32_bf16 v[52:55], v[216:219], v[166:169], v[52:55]
	v_mfma_f32_16x16x32_bf16 v[48:51], v[224:227], v[166:169], v[48:51]
	v_mfma_f32_16x16x32_bf16 v[36:39], v[216:219], v[174:177], v[36:39]
	v_mfma_f32_16x16x32_bf16 v[32:35], v[224:227], v[174:177], v[32:35]
	v_mfma_f32_16x16x32_bf16 v[20:23], v[216:219], v[182:185], v[20:23]
	v_mfma_f32_16x16x32_bf16 v[16:19], v[224:227], v[182:185], v[16:19]
	v_mfma_f32_16x16x32_bf16 v[4:7], v[216:219], v[208:211], v[4:7]
	v_mfma_f32_16x16x32_bf16 v[0:3], v[224:227], v[208:211], v[0:3]
	v_mfma_f32_16x16x32_bf16 v[52:55], v[220:223], v[170:173], v[52:55]
	v_mfma_f32_16x16x32_bf16 v[48:51], v[228:231], v[170:173], v[48:51]
	v_mfma_f32_16x16x32_bf16 v[36:39], v[220:223], v[178:181], v[36:39]
	v_mfma_f32_16x16x32_bf16 v[32:35], v[228:231], v[178:181], v[32:35]
	v_mfma_f32_16x16x32_bf16 v[20:23], v[220:223], v[196:199], v[20:23]
	v_mfma_f32_16x16x32_bf16 v[16:19], v[228:231], v[196:199], v[16:19]
	v_mfma_f32_16x16x32_bf16 v[4:7], v[220:223], v[212:215], v[4:7]
	v_mfma_f32_16x16x32_bf16 v[0:3], v[228:231], v[212:215], v[0:3]
	s_setprio 0
	v_add_u32_e32 v154, s38, v147
	s_barrier
	ds_read_b128 v[134:137], v154
	ds_read_b128 v[138:141], v154 offset:1024
	ds_read_b128 v[150:153], v154 offset:2048
	ds_read_b128 v[154:157], v154 offset:3072
	s_add_u32 s30, s30, 0x80000
	s_addc_u32 s31, s31, 0
	s_mov_b32 m0, s51
	v_lshl_add_u64 v[216:217], s[30:31], 0, v[160:161]
	ds_read_b128 v[166:169], v149 offset:32768
	ds_read_b128 v[170:173], v149 offset:33792
	ds_read_b128 v[174:177], v149 offset:34816
	ds_read_b128 v[178:181], v149 offset:35840
	ds_read_b128 v[182:185], v149 offset:36864
	ds_read_b128 v[196:199], v149 offset:37888
	ds_read_b128 v[208:211], v149 offset:38912
	ds_read_b128 v[212:215], v149 offset:39936
	global_load_lds_dwordx4 v[216:217], off
	s_mov_b32 m0, s52
	v_lshl_add_u64 v[216:217], s[30:31], 0, v[128:129]
	global_load_lds_dwordx4 v[216:217], off
	s_waitcnt lgkmcnt(8)
	s_barrier
	s_waitcnt lgkmcnt(0)
	s_setprio 1
	v_mfma_f32_16x16x32_bf16 v[124:127], v[134:137], v[166:169], v[124:127]
	v_mfma_f32_16x16x32_bf16 v[120:123], v[150:153], v[166:169], v[120:123]
	v_mfma_f32_16x16x32_bf16 v[108:111], v[134:137], v[174:177], v[108:111]
	v_mfma_f32_16x16x32_bf16 v[104:107], v[150:153], v[174:177], v[104:107]
	v_mfma_f32_16x16x32_bf16 v[92:95], v[134:137], v[182:185], v[92:95]
	v_mfma_f32_16x16x32_bf16 v[88:91], v[150:153], v[182:185], v[88:91]
	v_mfma_f32_16x16x32_bf16 v[76:79], v[134:137], v[208:211], v[76:79]
	v_mfma_f32_16x16x32_bf16 v[72:75], v[150:153], v[208:211], v[72:75]
	v_mfma_f32_16x16x32_bf16 v[124:127], v[138:141], v[170:173], v[124:127]
	v_mfma_f32_16x16x32_bf16 v[120:123], v[154:157], v[170:173], v[120:123]
	v_mfma_f32_16x16x32_bf16 v[108:111], v[138:141], v[178:181], v[108:111]
	v_mfma_f32_16x16x32_bf16 v[104:107], v[154:157], v[178:181], v[104:107]
	v_mfma_f32_16x16x32_bf16 v[92:95], v[138:141], v[196:199], v[92:95]
	v_mfma_f32_16x16x32_bf16 v[88:91], v[154:157], v[196:199], v[88:91]
	v_mfma_f32_16x16x32_bf16 v[76:79], v[138:141], v[212:215], v[76:79]
	v_mfma_f32_16x16x32_bf16 v[72:75], v[154:157], v[212:215], v[72:75]
	s_setprio 0
	s_barrier
	s_mov_b32 m0, s53
	v_add_u32_e32 v228, s39, v147
	v_lshl_add_u64 v[158:159], v[158:159], 0, s[90:91]
	ds_read_b128 v[216:219], v228
	ds_read_b128 v[220:223], v228 offset:1024
	ds_read_b128 v[224:227], v228 offset:2048
	ds_read_b128 v[228:231], v228 offset:3072
	global_load_lds_dwordx4 v[158:159], off
	s_mov_b32 m0, s54
	v_lshl_add_u64 v[158:159], v[200:201], 0, s[90:91]
	global_load_lds_dwordx4 v[158:159], off
	s_barrier
	s_waitcnt lgkmcnt(0)
	s_setprio 1
	v_mfma_f32_16x16x32_bf16 v[116:119], v[216:219], v[166:169], v[116:119]
	v_mfma_f32_16x16x32_bf16 v[112:115], v[224:227], v[166:169], v[112:115]
	v_mfma_f32_16x16x32_bf16 v[100:103], v[216:219], v[174:177], v[100:103]
	v_mfma_f32_16x16x32_bf16 v[96:99], v[224:227], v[174:177], v[96:99]
	v_mfma_f32_16x16x32_bf16 v[84:87], v[216:219], v[182:185], v[84:87]
	v_mfma_f32_16x16x32_bf16 v[80:83], v[224:227], v[182:185], v[80:83]
	v_mfma_f32_16x16x32_bf16 v[68:71], v[216:219], v[208:211], v[68:71]
	v_mfma_f32_16x16x32_bf16 v[64:67], v[224:227], v[208:211], v[64:67]
	v_mfma_f32_16x16x32_bf16 v[116:119], v[220:223], v[170:173], v[116:119]
	v_mfma_f32_16x16x32_bf16 v[112:115], v[228:231], v[170:173], v[112:115]
	v_mfma_f32_16x16x32_bf16 v[100:103], v[220:223], v[178:181], v[100:103]
	v_mfma_f32_16x16x32_bf16 v[96:99], v[228:231], v[178:181], v[96:99]
	v_mfma_f32_16x16x32_bf16 v[84:87], v[220:223], v[196:199], v[84:87]
	v_mfma_f32_16x16x32_bf16 v[80:83], v[228:231], v[196:199], v[80:83]
	v_mfma_f32_16x16x32_bf16 v[68:71], v[220:223], v[212:215], v[68:71]
	v_mfma_f32_16x16x32_bf16 v[64:67], v[228:231], v[212:215], v[64:67]
	s_setprio 0
	s_mov_b32 m0, s55
	v_lshl_add_u64 v[158:159], v[232:233], 0, s[90:91]
	s_barrier
	ds_read_b128 v[166:169], v149 offset:49152
	ds_read_b128 v[170:173], v149 offset:50176
	ds_read_b128 v[174:177], v149 offset:51200
	ds_read_b128 v[178:181], v149 offset:52224
	ds_read_b128 v[182:185], v149 offset:53248
	ds_read_b128 v[196:199], v149 offset:54272
	ds_read_b128 v[208:211], v149 offset:55296
	ds_read_b128 v[212:215], v149 offset:56320
	global_load_lds_dwordx4 v[158:159], off
	s_mov_b32 m0, s56
	v_lshl_add_u64 v[158:159], v[234:235], 0, s[90:91]
	global_load_lds_dwordx4 v[158:159], off
	s_barrier
; __device__ __forceinline__ float rinv_st(stat_t s, float invn) { return rsqrtf((float)((double)s * (1.0 / 4294967296.0)) * invn + 1e-6f); }
; #define PG8_STAGE(bufoff, gbase, voff) do { _Pragma("unroll") for (int _i = 0; _i < 2; ++_i) \
;         __builtin_amdgcn_global_load_lds((const unsigned*)((const char*)(gbase) + (voff)[_i]), (LAS unsigned*)(lds + (bufoff) + ldsw + _i * 8192), 16, 0, 0); } while (0)
; #define PG8_MMA(ai, bj, At, Bt) do { __builtin_amdgcn_s_setprio(1); _Pragma("unroll") for (int m = 0; m < 4; ++m) _Pragma("unroll") for (int n = 0; n < 2; ++n) _Pragma("unroll") for (int k = 0; k < 2; ++k) \
;         acc[ai][bj][m][n] = __builtin_amdgcn_mfma_f32_16x16x32_bf16(Bt[n][k], At[m][k], acc[ai][bj][m][n], 0, 0, 0); __builtin_amdgcn_s_setprio(0); } while (0)
; #define PG8_WAIT_V(n) asm volatile("s_waitcnt vmcnt(" #n ")" ::: "memory")
; #define PG8_WAIT_L(n) asm volatile("s_waitcnt lgkmcnt(" #n ")" ::: "memory")
; #define PG8_BAR __builtin_amdgcn_s_barrier()
; #define PG8_SCHED __builtin_amdgcn_sched_barrier(0)
; template <class Epi>
; __device__ __forceinline__ void gemm_phase(const int TID, const int BID, LAS unsigned char* lds, const Gemm g, const StaticOrder& S, const Epi& E) {
;     ...
;             PG8_BAR; PG8_WAIT_L(0); PG8_MMA(1, 0, At, B0); PG8_BAR; PG8_SCHED;
;             PG8_STAGE(PG8_SB(1, 1), b3 + hstepB, voffB);
;             PG8_WAIT_V(6); PG8_BAR; PG8_MMA(1, 1, At, B1); PG8_BAR;
;     __device__ __forceinline__ void operator()(const f32x4 (&acc)[2][2][4][2], const Unit& u, int wr, int wc, int fr, int fq) const {
;         const int row0 = u.pm * BM + wr * 64 + fr, col0 = u.pn * BM + wc * 32 + 4 * fq;
; #pragma unroll
;         for (int ai = 0; ai < 2; ++ai)
; #pragma unroll
;             for (int m = 0; m < 4; ++m) {
;                 const int row = row0 + ai * HALF + m * 16; const float r = rinv_st(stats[row], 1.0f / 2048.0f);
;                 float* rowp = raw + (size_t)row * 256 + col0;
; #pragma unroll
;                 for (int bj = 0; bj < 2; ++bj)
; #pragma unroll
;                     for (int n = 0; n < 2; ++n) *(f32x4*)(rowp + bj * HALF + n * 16) = acc[ai][bj][m][n] * r;
	s_waitcnt lgkmcnt(0)
	s_setprio 1
	v_mfma_f32_16x16x32_bf16 v[60:63], v[134:137], v[166:169], v[60:63]
	v_mfma_f32_16x16x32_bf16 v[56:59], v[150:153], v[166:169], v[56:59]
	v_mfma_f32_16x16x32_bf16 v[44:47], v[134:137], v[174:177], v[44:47]
	v_mfma_f32_16x16x32_bf16 v[40:43], v[150:153], v[174:177], v[40:43]
	v_mfma_f32_16x16x32_bf16 v[28:31], v[134:137], v[182:185], v[28:31]
	v_mfma_f32_16x16x32_bf16 v[24:27], v[150:153], v[182:185], v[24:27]
	v_mfma_f32_16x16x32_bf16 v[12:15], v[134:137], v[208:211], v[12:15]
	v_mfma_f32_16x16x32_bf16 v[8:11], v[150:153], v[208:211], v[8:11]
	v_mfma_f32_16x16x32_bf16 v[60:63], v[138:141], v[170:173], v[60:63]
	v_mfma_f32_16x16x32_bf16 v[56:59], v[154:157], v[170:173], v[56:59]
	v_mfma_f32_16x16x32_bf16 v[44:47], v[138:141], v[178:181], v[44:47]
	v_mfma_f32_16x16x32_bf16 v[40:43], v[154:157], v[178:181], v[40:43]
	v_mfma_f32_16x16x32_bf16 v[28:31], v[138:141], v[196:199], v[28:31]
	v_mfma_f32_16x16x32_bf16 v[24:27], v[154:157], v[196:199], v[24:27]
	v_mfma_f32_16x16x32_bf16 v[12:15], v[138:141], v[212:215], v[12:15]
	v_mfma_f32_16x16x32_bf16 v[8:11], v[154:157], v[212:215], v[8:11]
	s_setprio 0
	s_barrier
	s_add_u32 s28, s28, 0x80080
	s_addc_u32 s29, s29, 0
	s_mov_b32 m0, s57
	v_lshl_add_u64 v[134:135], s[28:29], 0, v[160:161]
	global_load_lds_dwordx4 v[134:135], off
	s_mov_b32 m0, s58
	v_lshl_add_u64 v[134:135], s[28:29], 0, v[128:129]
	global_load_lds_dwordx4 v[134:135], off
	s_waitcnt vmcnt(6)
	s_barrier
	s_setprio 1
	v_mfma_f32_16x16x32_bf16 v[52:55], v[216:219], v[166:169], v[52:55]
	v_mfma_f32_16x16x32_bf16 v[48:51], v[224:227], v[166:169], v[48:51]
	v_mfma_f32_16x16x32_bf16 v[36:39], v[216:219], v[174:177], v[36:39]
	v_mfma_f32_16x16x32_bf16 v[32:35], v[224:227], v[174:177], v[32:35]
	v_mfma_f32_16x16x32_bf16 v[20:23], v[216:219], v[182:185], v[20:23]
	v_mfma_f32_16x16x32_bf16 v[16:19], v[224:227], v[182:185], v[16:19]
	v_mfma_f32_16x16x32_bf16 v[4:7], v[216:219], v[208:211], v[4:7]
	v_mfma_f32_16x16x32_bf16 v[0:3], v[224:227], v[208:211], v[0:3]
	v_mfma_f32_16x16x32_bf16 v[52:55], v[220:223], v[170:173], v[52:55]
	v_mfma_f32_16x16x32_bf16 v[48:51], v[228:231], v[170:173], v[48:51]
	v_mfma_f32_16x16x32_bf16 v[36:39], v[220:223], v[178:181], v[36:39]
	v_mfma_f32_16x16x32_bf16 v[32:35], v[228:231], v[178:181], v[32:35]
	v_mfma_f32_16x16x32_bf16 v[20:23], v[220:223], v[196:199], v[20:23]
	v_mfma_f32_16x16x32_bf16 v[16:19], v[228:231], v[196:199], v[16:19]
	v_mfma_f32_16x16x32_bf16 v[4:7], v[220:223], v[212:215], v[4:7]
	v_mfma_f32_16x16x32_bf16 v[0:3], v[228:231], v[212:215], v[0:3]
	s_setprio 0
	s_add_i32 s66, s66, 2
	s_add_u32 s26, s26, 0x100
	s_addc_u32 s27, s27, 0
	s_add_u32 s63, s63, 0x100
	s_addc_u32 s64, s64, 0
	s_add_u32 s28, s26, 0xfff80080
	s_addc_u32 s29, s27, -1
	s_cmp_eq_u32 s66, 4
	s_cselect_b32 s31, s17, s29
	s_cselect_b32 s30, s61, s28
	s_cselect_b32 s29, s15, s64
	s_cselect_b32 s28, s62, s63
	s_cmp_gt_u32 s66, 5
	s_cbranch_scc0 .Lrot_822
	s_barrier
	v_lshl_add_u32 v140, s24, 8, v145
	v_ashrrev_i32_e32 v141, 31, v140
	v_lshl_add_u64 v[136:137], v[140:141], 3, s[10:11]
	global_load_dwordx2 v[138:139], v[136:137], off
	global_load_dwordx2 v[208:209], v[136:137], off offset:128
	global_load_dwordx2 v[210:211], v[136:137], off offset:256
	global_load_dwordx2 v[212:213], v[136:137], off offset:384
	global_load_dwordx2 v[214:215], v[136:137], off offset:1024
	global_load_dwordx2 v[216:217], v[136:137], off offset:1152
	global_load_dwordx2 v[218:219], v[136:137], off offset:1280
	global_load_dwordx2 v[220:221], v[136:137], off offset:1408
	v_lshl_or_b32 v134, s60, 8, v148
	v_ashrrev_i32_e32 v135, 31, v134
	s_mov_b32 s15, 0x20000
	s_mov_b64 s[26:27], 0x20000
	s_mov_b32 s60, s14
	s_mov_b32 s24, s16
	s_mov_b64 s[28:29], s[22:23]
	s_waitcnt vmcnt(0)
	v_cvt_f64_u32_e32 v[150:151], v139
	v_ldexp_f64 v[150:151], v[150:151], 32
	v_cvt_f64_u32_e32 v[138:139], v138
	v_add_f64 v[138:139], v[150:151], v[138:139]
	v_ldexp_f64 v[138:139], v[138:139], s93
	v_cvt_f32_f64_e32 v138, v[138:139]
	v_fmamk_f32 v138, v138, 0x3a000000, v189
	v_cmp_gt_f32_e32 vcc, s78, v138
	v_mul_f32_e32 v139, 0x4b800000, v138
	s_nop 0
	v_cndmask_b32_e32 v138, v138, v139, vcc
	v_rsq_f32_e32 v138, v138
	s_nop 0
	v_mul_f32_e32 v139, 0x45800000, v138
	v_cndmask_b32_e32 v150, v138, v139, vcc
	v_lshlrev_b64 v[138:139], 10, v[140:141]
	v_lshl_add_u64 v[152:153], s[12:13], 0, v[138:139]
	v_lshlrev_b64 v[138:139], 2, v[134:135]
	v_lshl_add_u64 v[134:135], v[152:153], 0, v[138:139]
	v_pk_mul_f32 v[114:115], v[114:115], v[150:151] op_sel_hi:[1,0]
	v_pk_mul_f32 v[112:113], v[112:113], v[150:151] op_sel_hi:[1,0]
	global_store_dwordx4 v[134:135], v[112:115], off offset:576
	v_pk_mul_f32 v[126:127], v[126:127], v[150:151] op_sel_hi:[1,0]
	v_pk_mul_f32 v[124:125], v[124:125], v[150:151] op_sel_hi:[1,0]
	v_or_b32_e32 v112, 16, v140
	v_pk_mul_f32 v[122:123], v[122:123], v[150:151] op_sel_hi:[1,0]
	v_pk_mul_f32 v[120:121], v[120:121], v[150:151] op_sel_hi:[1,0]
	v_pk_mul_f32 v[118:119], v[118:119], v[150:151] op_sel_hi:[1,0]
	v_pk_mul_f32 v[116:117], v[116:117], v[150:151] op_sel_hi:[1,0]
	v_ashrrev_i32_e32 v113, 31, v112
	global_store_dwordx4 v[134:135], v[124:127], off
	global_store_dwordx4 v[134:135], v[120:123], off offset:64
	global_store_dwordx4 v[134:135], v[116:119], off offset:512
	v_lshl_add_u64 v[114:115], v[112:113], 3, s[10:11]
	s_nop 1
	v_mov_b64_e32 v[114:115], v[208:209]
	v_lshlrev_b64 v[112:113], 10, v[112:113]
	v_lshl_add_u64 v[112:113], s[12:13], 0, v[112:113]
	v_lshl_add_u64 v[112:113], v[112:113], 0, v[138:139]
	v_cvt_f64_u32_e32 v[116:117], v115
	v_ldexp_f64 v[116:117], v[116:117], 32
	v_cvt_f64_u32_e32 v[114:115], v114
; __device__ __forceinline__ float rinv_st(stat_t s, float invn) { return rsqrtf((float)((double)s * (1.0 / 4294967296.0)) * invn + 1e-6f); }
;     __device__ __forceinline__ void operator()(const f32x4 (&acc)[2][2][4][2], const Unit& u, int wr, int wc, int fr, int fq) const {
;     ...
;         for (int ai = 0; ai < 2; ++ai)
; #pragma unroll
;             for (int m = 0; m < 4; ++m) {
;                 const int row = row0 + ai * HALF + m * 16; const float r = rinv_st(stats[row], 1.0f / 2048.0f);
;                 float* rowp = raw + (size_t)row * 256 + col0;
; #pragma unroll
;                 for (int bj = 0; bj < 2; ++bj)
; #pragma unroll
;                     for (int n = 0; n < 2; ++n) *(f32x4*)(rowp + bj * HALF + n * 16) = acc[ai][bj][m][n] * r;
;             }
	v_add_f64 v[114:115], v[116:117], v[114:115]
	v_ldexp_f64 v[114:115], v[114:115], s93
	v_cvt_f32_f64_e32 v114, v[114:115]
	v_fmamk_f32 v114, v114, 0x3a000000, v189
	v_cmp_gt_f32_e32 vcc, s78, v114
	v_mul_f32_e32 v115, 0x4b800000, v114
	s_nop 0
	v_cndmask_b32_e32 v114, v114, v115, vcc
	v_rsq_f32_e32 v114, v114
	s_nop 0
	v_mul_f32_e32 v115, 0x45800000, v114
	v_cndmask_b32_e32 v114, v114, v115, vcc
	v_pk_mul_f32 v[98:99], v[98:99], v[114:115] op_sel_hi:[1,0]
	v_pk_mul_f32 v[96:97], v[96:97], v[114:115] op_sel_hi:[1,0]
	global_store_dwordx4 v[112:113], v[96:99], off offset:576
	v_pk_mul_f32 v[110:111], v[110:111], v[114:115] op_sel_hi:[1,0]
	v_pk_mul_f32 v[108:109], v[108:109], v[114:115] op_sel_hi:[1,0]
	v_or_b32_e32 v96, 32, v140
	v_pk_mul_f32 v[106:107], v[106:107], v[114:115] op_sel_hi:[1,0]
	v_pk_mul_f32 v[104:105], v[104:105], v[114:115] op_sel_hi:[1,0]
	v_pk_mul_f32 v[102:103], v[102:103], v[114:115] op_sel_hi:[1,0]
	v_pk_mul_f32 v[100:101], v[100:101], v[114:115] op_sel_hi:[1,0]
	v_ashrrev_i32_e32 v97, 31, v96
	global_store_dwordx4 v[112:113], v[108:111], off
	global_store_dwordx4 v[112:113], v[104:107], off offset:64
	global_store_dwordx4 v[112:113], v[100:103], off offset:512
	v_lshl_add_u64 v[98:99], v[96:97], 3, s[10:11]
	s_nop 1
	v_mov_b64_e32 v[98:99], v[210:211]
	v_lshlrev_b64 v[96:97], 10, v[96:97]
	v_lshl_add_u64 v[96:97], s[12:13], 0, v[96:97]
	v_lshl_add_u64 v[96:97], v[96:97], 0, v[138:139]
	v_cvt_f64_u32_e32 v[100:101], v99
	v_ldexp_f64 v[100:101], v[100:101], 32
	v_cvt_f64_u32_e32 v[98:99], v98
	v_add_f64 v[98:99], v[100:101], v[98:99]
	v_ldexp_f64 v[98:99], v[98:99], s93
	v_cvt_f32_f64_e32 v98, v[98:99]
	v_fmamk_f32 v98, v98, 0x3a000000, v189
	v_cmp_gt_f32_e32 vcc, s78, v98
	v_mul_f32_e32 v99, 0x4b800000, v98
	s_nop 0
	v_cndmask_b32_e32 v98, v98, v99, vcc
	v_rsq_f32_e32 v98, v98
	s_nop 0
	v_mul_f32_e32 v99, 0x45800000, v98
	v_cndmask_b32_e32 v98, v98, v99, vcc
	v_pk_mul_f32 v[82:83], v[82:83], v[98:99] op_sel_hi:[1,0]
	v_pk_mul_f32 v[80:81], v[80:81], v[98:99] op_sel_hi:[1,0]
	global_store_dwordx4 v[96:97], v[80:83], off offset:576
	v_pk_mul_f32 v[94:95], v[94:95], v[98:99] op_sel_hi:[1,0]
	v_pk_mul_f32 v[92:93], v[92:93], v[98:99] op_sel_hi:[1,0]
	v_or_b32_e32 v80, 48, v140
	v_pk_mul_f32 v[90:91], v[90:91], v[98:99] op_sel_hi:[1,0]
	v_pk_mul_f32 v[88:89], v[88:89], v[98:99] op_sel_hi:[1,0]
	v_pk_mul_f32 v[86:87], v[86:87], v[98:99] op_sel_hi:[1,0]
	v_pk_mul_f32 v[84:85], v[84:85], v[98:99] op_sel_hi:[1,0]
	v_ashrrev_i32_e32 v81, 31, v80
	global_store_dwordx4 v[96:97], v[92:95], off
	global_store_dwordx4 v[96:97], v[88:91], off offset:64
	global_store_dwordx4 v[96:97], v[84:87], off offset:512
	v_lshl_add_u64 v[82:83], v[80:81], 3, s[10:11]
	s_nop 1
	v_mov_b64_e32 v[82:83], v[212:213]
	v_lshlrev_b64 v[80:81], 10, v[80:81]
	v_lshl_add_u64 v[80:81], s[12:13], 0, v[80:81]
	v_lshl_add_u64 v[80:81], v[80:81], 0, v[138:139]
	v_cvt_f64_u32_e32 v[84:85], v83
	v_ldexp_f64 v[84:85], v[84:85], 32
	v_cvt_f64_u32_e32 v[82:83], v82
	v_add_f64 v[82:83], v[84:85], v[82:83]
	v_ldexp_f64 v[82:83], v[82:83], s93
	v_cvt_f32_f64_e32 v82, v[82:83]
	v_fmamk_f32 v82, v82, 0x3a000000, v189
	v_cmp_gt_f32_e32 vcc, s78, v82
	v_mul_f32_e32 v83, 0x4b800000, v82
	s_nop 0
	v_cndmask_b32_e32 v82, v82, v83, vcc
	v_rsq_f32_e32 v82, v82
	s_nop 0
	v_mul_f32_e32 v83, 0x45800000, v82
	v_cndmask_b32_e32 v82, v82, v83, vcc
	v_pk_mul_f32 v[78:79], v[78:79], v[82:83] op_sel_hi:[1,0]
	v_pk_mul_f32 v[76:77], v[76:77], v[82:83] op_sel_hi:[1,0]
	v_pk_mul_f32 v[74:75], v[74:75], v[82:83] op_sel_hi:[1,0]
	v_pk_mul_f32 v[72:73], v[72:73], v[82:83] op_sel_hi:[1,0]
	v_pk_mul_f32 v[70:71], v[70:71], v[82:83] op_sel_hi:[1,0]
	v_pk_mul_f32 v[68:69], v[68:69], v[82:83] op_sel_hi:[1,0]
	v_pk_mul_f32 v[66:67], v[66:67], v[82:83] op_sel_hi:[1,0]
	v_pk_mul_f32 v[64:65], v[64:65], v[82:83] op_sel_hi:[1,0]
	global_store_dwordx4 v[80:81], v[76:79], off
	global_store_dwordx4 v[80:81], v[72:75], off offset:64
	global_store_dwordx4 v[80:81], v[68:71], off offset:512
	global_store_dwordx4 v[80:81], v[64:67], off offset:576
	s_nop 1
	v_mov_b64_e32 v[64:65], v[214:215]
	v_cvt_f64_u32_e32 v[66:67], v65
	v_ldexp_f64 v[66:67], v[66:67], 32
	v_cvt_f64_u32_e32 v[64:65], v64
	v_add_f64 v[64:65], v[66:67], v[64:65]
	v_ldexp_f64 v[64:65], v[64:65], s93
	v_cvt_f32_f64_e32 v64, v[64:65]
	v_fmamk_f32 v64, v64, 0x3a000000, v189
	v_cmp_gt_f32_e32 vcc, s78, v64
	v_mul_f32_e32 v65, 0x4b800000, v64
	v_lshl_add_u64 v[66:67], v[134:135], 0, s[26:27]
	v_cndmask_b32_e32 v64, v64, v65, vcc
	v_rsq_f32_e32 v64, v64
	s_mov_b64 s[26:27], 0x24000
	v_mul_f32_e32 v65, 0x45800000, v64
	v_cndmask_b32_e32 v64, v64, v65, vcc
	v_add_co_u32_e32 v68, vcc, s15, v134
	v_pk_mul_f32 v[62:63], v[62:63], v[64:65] op_sel_hi:[1,0]
	v_pk_mul_f32 v[60:61], v[60:61], v[64:65] op_sel_hi:[1,0]
	v_addc_co_u32_e32 v69, vcc, 0, v135, vcc
; __device__ __forceinline__ float rinv_st(stat_t s, float invn) { return rsqrtf((float)((double)s * (1.0 / 4294967296.0)) * invn + 1e-6f); }
; #define PG8_WAIT_V(n) asm volatile("s_waitcnt vmcnt(" #n ")" ::: "memory")
; #define PG8_BAR __builtin_amdgcn_s_barrier()
; template <class Epi>
; __device__ __forceinline__ void gemm_phase(const int TID, const int BID, LAS unsigned char* lds, const Gemm g, const StaticOrder& S, const Epi& E) {
;     ...
;     PG8_WAIT_V(0);
;     if (wr == 0) PG8_BAR;
;     PG8_BAR;
;     __device__ __forceinline__ void operator()(const f32x4 (&acc)[2][2][4][2], const Unit& u, int wr, int wc, int fr, int fq) const {
;     ...
;         for (int ai = 0; ai < 2; ++ai)
; #pragma unroll
;             for (int m = 0; m < 4; ++m) {
;                 const int row = row0 + ai * HALF + m * 16; const float r = rinv_st(stats[row], 1.0f / 2048.0f);
;                 float* rowp = raw + (size_t)row * 256 + col0;
; #pragma unroll
;                 for (int bj = 0; bj < 2; ++bj)
; #pragma unroll
;                     for (int n = 0; n < 2; ++n) *(f32x4*)(rowp + bj * HALF + n * 16) = acc[ai][bj][m][n] * r;
;             }
	v_pk_mul_f32 v[58:59], v[58:59], v[64:65] op_sel_hi:[1,0]
	v_pk_mul_f32 v[56:57], v[56:57], v[64:65] op_sel_hi:[1,0]
	v_pk_mul_f32 v[54:55], v[54:55], v[64:65] op_sel_hi:[1,0]
	v_pk_mul_f32 v[52:53], v[52:53], v[64:65] op_sel_hi:[1,0]
	v_pk_mul_f32 v[50:51], v[50:51], v[64:65] op_sel_hi:[1,0]
	v_pk_mul_f32 v[48:49], v[48:49], v[64:65] op_sel_hi:[1,0]
	global_store_dwordx4 v[68:69], v[60:63], off
	global_store_dwordx4 v[66:67], v[56:59], off offset:64
	global_store_dwordx4 v[66:67], v[52:55], off offset:512
	global_store_dwordx4 v[66:67], v[48:51], off offset:576
	s_nop 1
	v_mov_b64_e32 v[48:49], v[216:217]
	s_mov_b32 s15, 0x24000
	v_cvt_f64_u32_e32 v[50:51], v49
	v_ldexp_f64 v[50:51], v[50:51], 32
	v_cvt_f64_u32_e32 v[48:49], v48
	v_add_f64 v[48:49], v[50:51], v[48:49]
	v_ldexp_f64 v[48:49], v[48:49], s93
	v_cvt_f32_f64_e32 v48, v[48:49]
	v_fmamk_f32 v48, v48, 0x3a000000, v189
	v_cmp_gt_f32_e32 vcc, s78, v48
	v_mul_f32_e32 v49, 0x4b800000, v48
	v_lshl_add_u64 v[50:51], v[134:135], 0, s[26:27]
	v_cndmask_b32_e32 v48, v48, v49, vcc
	v_rsq_f32_e32 v48, v48
	s_mov_b64 s[26:27], 0x28000
	v_mul_f32_e32 v49, 0x45800000, v48
	v_cndmask_b32_e32 v48, v48, v49, vcc
	v_add_co_u32_e32 v52, vcc, s15, v134
	v_pk_mul_f32 v[46:47], v[46:47], v[48:49] op_sel_hi:[1,0]
	v_pk_mul_f32 v[44:45], v[44:45], v[48:49] op_sel_hi:[1,0]
	v_addc_co_u32_e32 v53, vcc, 0, v135, vcc
	v_pk_mul_f32 v[42:43], v[42:43], v[48:49] op_sel_hi:[1,0]
	v_pk_mul_f32 v[40:41], v[40:41], v[48:49] op_sel_hi:[1,0]
	v_pk_mul_f32 v[38:39], v[38:39], v[48:49] op_sel_hi:[1,0]
	v_pk_mul_f32 v[36:37], v[36:37], v[48:49] op_sel_hi:[1,0]
	v_pk_mul_f32 v[34:35], v[34:35], v[48:49] op_sel_hi:[1,0]
	v_pk_mul_f32 v[32:33], v[32:33], v[48:49] op_sel_hi:[1,0]
	global_store_dwordx4 v[52:53], v[44:47], off
	global_store_dwordx4 v[50:51], v[40:43], off offset:64
	global_store_dwordx4 v[50:51], v[36:39], off offset:512
	global_store_dwordx4 v[50:51], v[32:35], off offset:576
	s_nop 1
	v_mov_b64_e32 v[32:33], v[218:219]
	s_mov_b32 s15, 0x28000
	v_cvt_f64_u32_e32 v[34:35], v33
	v_ldexp_f64 v[34:35], v[34:35], 32
	v_cvt_f64_u32_e32 v[32:33], v32
	v_add_f64 v[32:33], v[34:35], v[32:33]
	v_ldexp_f64 v[32:33], v[32:33], s93
	v_cvt_f32_f64_e32 v32, v[32:33]
	v_fmamk_f32 v32, v32, 0x3a000000, v189
	v_cmp_gt_f32_e32 vcc, s78, v32
	v_mul_f32_e32 v33, 0x4b800000, v32
	v_lshl_add_u64 v[34:35], v[134:135], 0, s[26:27]
	v_cndmask_b32_e32 v32, v32, v33, vcc
	v_rsq_f32_e32 v32, v32
	s_mov_b64 s[26:27], 0x2c000
	v_mul_f32_e32 v33, 0x45800000, v32
	v_cndmask_b32_e32 v32, v32, v33, vcc
	v_add_co_u32_e32 v36, vcc, s15, v134
	v_pk_mul_f32 v[30:31], v[30:31], v[32:33] op_sel_hi:[1,0]
	v_pk_mul_f32 v[28:29], v[28:29], v[32:33] op_sel_hi:[1,0]
	v_addc_co_u32_e32 v37, vcc, 0, v135, vcc
	v_pk_mul_f32 v[26:27], v[26:27], v[32:33] op_sel_hi:[1,0]
	v_pk_mul_f32 v[24:25], v[24:25], v[32:33] op_sel_hi:[1,0]
	v_pk_mul_f32 v[22:23], v[22:23], v[32:33] op_sel_hi:[1,0]
	v_pk_mul_f32 v[20:21], v[20:21], v[32:33] op_sel_hi:[1,0]
	v_pk_mul_f32 v[18:19], v[18:19], v[32:33] op_sel_hi:[1,0]
	v_pk_mul_f32 v[16:17], v[16:17], v[32:33] op_sel_hi:[1,0]
	global_store_dwordx4 v[36:37], v[28:31], off
	global_store_dwordx4 v[34:35], v[24:27], off offset:64
	global_store_dwordx4 v[34:35], v[20:23], off offset:512
	global_store_dwordx4 v[34:35], v[16:19], off offset:576
	s_nop 1
	v_mov_b64_e32 v[16:17], v[220:221]
	s_mov_b32 s15, 0x2c000
	v_cvt_f64_u32_e32 v[18:19], v17
	v_ldexp_f64 v[18:19], v[18:19], 32
	v_cvt_f64_u32_e32 v[16:17], v16
	v_add_f64 v[16:17], v[18:19], v[16:17]
	v_ldexp_f64 v[16:17], v[16:17], s93
	v_cvt_f32_f64_e32 v16, v[16:17]
	v_fmamk_f32 v16, v16, 0x3a000000, v189
	v_cmp_gt_f32_e32 vcc, s78, v16
	v_mul_f32_e32 v17, 0x4b800000, v16
	v_lshl_add_u64 v[18:19], v[134:135], 0, s[26:27]
	v_cndmask_b32_e32 v16, v16, v17, vcc
	v_rsq_f32_e32 v16, v16
	s_mov_b64 s[26:27], s[20:21]
	v_mul_f32_e32 v17, 0x45800000, v16
	v_cndmask_b32_e32 v16, v16, v17, vcc
	v_add_co_u32_e32 v20, vcc, s15, v134
	v_pk_mul_f32 v[14:15], v[14:15], v[16:17] op_sel_hi:[1,0]
	s_nop 0
	v_addc_co_u32_e32 v21, vcc, 0, v135, vcc
	v_pk_mul_f32 v[12:13], v[12:13], v[16:17] op_sel_hi:[1,0]
	v_pk_mul_f32 v[10:11], v[10:11], v[16:17] op_sel_hi:[1,0]
	v_pk_mul_f32 v[8:9], v[8:9], v[16:17] op_sel_hi:[1,0]
	v_pk_mul_f32 v[6:7], v[6:7], v[16:17] op_sel_hi:[1,0]
	v_pk_mul_f32 v[4:5], v[4:5], v[16:17] op_sel_hi:[1,0]
	v_pk_mul_f32 v[2:3], v[2:3], v[16:17] op_sel_hi:[1,0]
	v_pk_mul_f32 v[0:1], v[0:1], v[16:17] op_sel_hi:[1,0]
	s_and_b64 vcc, exec, s[18:19]
	global_store_dwordx4 v[20:21], v[12:15], off
	global_store_dwordx4 v[18:19], v[8:11], off offset:64
	global_store_dwordx4 v[18:19], v[4:7], off offset:512
	global_store_dwordx4 v[18:19], v[0:3], off offset:576
	s_cbranch_vccz .LBB0_815
	s_waitcnt vmcnt(0)
	s_cmpk_gt_u32 s42, 0xff
	s_cbranch_scc1 .LBB0_805
	s_barrier
	s_branch .LBB0_805

; template <class Epi>
; __device__ __forceinline__ void gemm_phase(const int TID, const int BID, LAS unsigned char* lds, const Gemm g, const StaticOrder& S, const Epi& E) {
;     ...
;         const bool has_next = S.next(ui + 1, nxt);
;         const char* nA = has_next ? (const char*)g.A + (size_t)nxt.pm * tstepA : cA; const char* nB = has_next ? (const char*)g.Bt + (size_t)nxt.pn * tstepB : cB;
;         for (int t = 0; t < nt; t += 2) {
;             const bool last = (t == nt - 2);
;             const char* a1 = cA + (size_t)(t + 1) * kstep;
;             const char* a2 = last ? nA : cA + (size_t)(t + 2) * kstep; const char* b2 = last ? nB : cB + (size_t)(t + 2) * kstep;
;     ...
;         for (int a = 0; a < 2; ++a)
; #pragma unroll
;             for (int b = 0; b < 2; ++b)
; #pragma unroll
;                 for (int m = 0; m < 4; ++m)
; #pragma unroll
;                     for (int n = 0; n < 2; ++n) acc[a][b][m][n] = (f32x4){0.f, 0.f, 0.f, 0.f};
;         cur = nxt; cA = nA; cB = nB; ++ui;
.LBB0_863:
	s_ashr_i32 s23, s22, 31
	s_lshl_b64 s[0:1], s[22:23], 20
	v_cmp_lt_i64_e32 vcc, s[24:25], v[164:165]
	s_add_u32 s24, s84, s0
	s_addc_u32 s25, s85, s1
	s_and_b64 s[0:1], vcc, exec
	s_cselect_b32 s0, s25, s35
	s_cselect_b32 s1, s24, s34
	s_ashr_i32 s21, s20, 31
	s_lshl_b64 s[26:27], s[20:21], 20
	s_add_u32 s26, s41, s26
	s_addc_u32 s27, s42, s27
	s_and_b64 s[38:39], vcc, exec
	s_cselect_b32 s4, s27, s37
	s_cselect_b32 s21, s26, s36
	s_add_u32 s34, s34, 0x80080
	s_addc_u32 s35, s35, 0
	s_add_u32 s23, s36, 0x100
	v_mov_b32_e32 v0, 0
	s_addc_u32 s29, s37, 0
	s_mov_b32 s31, -2
	s_waitcnt lgkmcnt(0)
	v_mov_b32_e32 v1, v0
	v_mov_b32_e32 v2, v0
	v_mov_b32_e32 v3, v0
	v_mov_b32_e32 v4, v0
	v_mov_b32_e32 v5, v0
	v_mov_b32_e32 v6, v0
	v_mov_b32_e32 v7, v0
	v_mov_b32_e32 v24, v0
	v_mov_b32_e32 v25, v0
	v_mov_b32_e32 v26, v0
	v_mov_b32_e32 v27, v0
	v_mov_b32_e32 v28, v0
	v_mov_b32_e32 v29, v0
	v_mov_b32_e32 v30, v0
	v_mov_b32_e32 v31, v0
	v_mov_b32_e32 v48, v0
	v_mov_b32_e32 v49, v0
	v_mov_b32_e32 v50, v0
	v_mov_b32_e32 v51, v0
	v_mov_b32_e32 v52, v0
	v_mov_b32_e32 v53, v0
	v_mov_b32_e32 v54, v0
	v_mov_b32_e32 v55, v0
	v_mov_b32_e32 v64, v0
	v_mov_b32_e32 v65, v0
	v_mov_b32_e32 v66, v0
	v_mov_b32_e32 v67, v0
	v_mov_b32_e32 v68, v0
	v_mov_b32_e32 v69, v0
	v_mov_b32_e32 v70, v0
	v_mov_b32_e32 v71, v0
	v_mov_b32_e32 v16, v0
	v_mov_b32_e32 v17, v0
	v_mov_b32_e32 v18, v0
	v_mov_b32_e32 v19, v0
	v_mov_b32_e32 v20, v0
	v_mov_b32_e32 v21, v0
	v_mov_b32_e32 v22, v0
	v_mov_b32_e32 v23, v0
	v_mov_b32_e32 v40, v0
	v_mov_b32_e32 v41, v0
	v_mov_b32_e32 v42, v0
	v_mov_b32_e32 v43, v0
	v_mov_b32_e32 v44, v0
	v_mov_b32_e32 v45, v0
	v_mov_b32_e32 v46, v0
	v_mov_b32_e32 v47, v0
	v_mov_b32_e32 v56, v0
	v_mov_b32_e32 v57, v0
	v_mov_b32_e32 v58, v0
	v_mov_b32_e32 v59, v0
	v_mov_b32_e32 v60, v0
	v_mov_b32_e32 v61, v0
	v_mov_b32_e32 v62, v0
	v_mov_b32_e32 v63, v0
	v_mov_b32_e32 v72, v0
	v_mov_b32_e32 v73, v0
	v_mov_b32_e32 v74, v0
	v_mov_b32_e32 v75, v0
	v_mov_b32_e32 v76, v0
	v_mov_b32_e32 v77, v0
	v_mov_b32_e32 v78, v0
	v_mov_b32_e32 v79, v0
	v_mov_b32_e32 v80, v0
	v_mov_b32_e32 v81, v0
	v_mov_b32_e32 v82, v0
	v_mov_b32_e32 v83, v0
	v_mov_b32_e32 v84, v0
	v_mov_b32_e32 v85, v0
	v_mov_b32_e32 v86, v0
	v_mov_b32_e32 v87, v0
	v_mov_b32_e32 v96, v0
	v_mov_b32_e32 v97, v0
	v_mov_b32_e32 v98, v0
	v_mov_b32_e32 v99, v0
	v_mov_b32_e32 v100, v0
	v_mov_b32_e32 v101, v0
	v_mov_b32_e32 v102, v0
	v_mov_b32_e32 v103, v0
	v_mov_b32_e32 v112, v0
	v_mov_b32_e32 v113, v0
	v_mov_b32_e32 v114, v0
	v_mov_b32_e32 v115, v0
	v_mov_b32_e32 v116, v0
	v_mov_b32_e32 v117, v0
	v_mov_b32_e32 v118, v0
	v_mov_b32_e32 v119, v0
	v_mov_b32_e32 v128, v0
	v_mov_b32_e32 v129, v0
	v_mov_b32_e32 v130, v0
	v_mov_b32_e32 v131, v0
	v_mov_b32_e32 v132, v0
	v_mov_b32_e32 v133, v0
	v_mov_b32_e32 v134, v0
	v_mov_b32_e32 v135, v0
	v_mov_b32_e32 v88, v0
	v_mov_b32_e32 v89, v0
	v_mov_b32_e32 v90, v0
	v_mov_b32_e32 v91, v0
	v_mov_b32_e32 v92, v0
	v_mov_b32_e32 v93, v0
	v_mov_b32_e32 v94, v0
	v_mov_b32_e32 v95, v0
	v_mov_b32_e32 v104, v0
	v_mov_b32_e32 v105, v0
	v_mov_b32_e32 v106, v0
	v_mov_b32_e32 v107, v0
	v_mov_b32_e32 v108, v0
	v_mov_b32_e32 v109, v0
	v_mov_b32_e32 v110, v0
	v_mov_b32_e32 v111, v0
	v_mov_b32_e32 v120, v0
	v_mov_b32_e32 v121, v0
	v_mov_b32_e32 v122, v0
	v_mov_b32_e32 v123, v0
	v_mov_b32_e32 v124, v0
	v_mov_b32_e32 v125, v0
	v_mov_b32_e32 v126, v0
	v_mov_b32_e32 v127, v0
	v_mov_b32_e32 v136, v0
	v_mov_b32_e32 v137, v0
	v_mov_b32_e32 v138, v0
	v_mov_b32_e32 v139, v0
	v_mov_b32_e32 v140, v0
	v_mov_b32_e32 v141, v0
	v_mov_b32_e32 v142, v0
	v_mov_b32_e32 v143, v0
	s_add_u32 s36, s34, 0xfff80080
	s_addc_u32 s37, s35, -1
	s_cmp_eq_u32 s31, 28
	s_cselect_b32 s39, s0, s37
	s_cselect_b32 s38, s1, s36
	s_cselect_b32 s37, s4, s29
	s_cselect_b32 s36, s21, s23
	s_branch .LBB0_864

; #define PG8_STAGE(bufoff, gbase, voff) do { _Pragma("unroll") for (int _i = 0; _i < 2; ++_i) \
;         __builtin_amdgcn_global_load_lds((const unsigned*)((const char*)(gbase) + (voff)[_i]), (LAS unsigned*)(lds + (bufoff) + ldsw + _i * 8192), 16, 0, 0); } while (0)
; #define PG8_LDA(dst, b, h) do { _Pragma("unroll") for (int m = 0; m < 4; ++m) _Pragma("unroll") for (int k = 0; k < 2; ++k) dst[m][k] = *(const LAS bf16x8*)(lds + PG8_SA(b, h) + aoff + m * 2048 + k * 1024); } while (0)
; #define PG8_LDB(dst, b, h) do { _Pragma("unroll") for (int n = 0; n < 2; ++n) _Pragma("unroll") for (int k = 0; k < 2; ++k) dst[n][k] = *(const LAS bf16x8*)(lds + PG8_SB(b, h) + boff + n * 2048 + k * 1024); } while (0)
; #define PG8_MMA(ai, bj, At, Bt) do { __builtin_amdgcn_s_setprio(1); _Pragma("unroll") for (int m = 0; m < 4; ++m) _Pragma("unroll") for (int n = 0; n < 2; ++n) _Pragma("unroll") for (int k = 0; k < 2; ++k) \
;         acc[ai][bj][m][n] = __builtin_amdgcn_mfma_f32_16x16x32_bf16(Bt[n][k], At[m][k], acc[ai][bj][m][n], 0, 0, 0); __builtin_amdgcn_s_setprio(0); } while (0)
; #define PG8_WAIT_V(n) asm volatile("s_waitcnt vmcnt(" #n ")" ::: "memory")
; #define PG8_WAIT_L(n) asm volatile("s_waitcnt lgkmcnt(" #n ")" ::: "memory")
; #define PG8_BAR __builtin_amdgcn_s_barrier()
; template <class Epi>
; __device__ __forceinline__ void gemm_phase(const int TID, const int BID, LAS unsigned char* lds, const Gemm g, const StaticOrder& S, const Epi& E) {
;     ...
;             const bool last = (t == nt - 2);
;             const char* a1 = cA + (size_t)(t + 1) * kstep;
;             const char* a2 = last ? nA : cA + (size_t)(t + 2) * kstep; const char* b2 = last ? nB : cB + (size_t)(t + 2) * kstep;
;             const char* a3 = a2 + kstep; const char* b3 = b2 + kstep;
;             PG8_LDB(B0, 0, 0); PG8_SCHED; PG8_LDA(At, 0, 0); PG8_STAGE(PG8_SA(1, 1), a1 + hstepA, voffA);
;             PG8_WAIT_L(8); PG8_BAR; PG8_WAIT_L(0); PG8_MMA(0, 0, At, B0); PG8_BAR; PG8_SCHED;
;             PG8_LDB(B1, 0, 1); PG8_STAGE(PG8_SB(0, 0), b2, voffB);
;             PG8_BAR; PG8_WAIT_L(0); PG8_MMA(0, 1, At, B1); PG8_BAR;
;             PG8_LDA(At, 0, 1); PG8_STAGE(PG8_SA(0, 0), a2, voffA);
;             PG8_BAR; PG8_WAIT_L(0); PG8_MMA(1, 0, At, B0); PG8_BAR; PG8_SCHED;
;             PG8_STAGE(PG8_SB(0, 1), b2 + hstepB, voffB);
;             PG8_WAIT_V(6); PG8_BAR; PG8_MMA(1, 1, At, B1); PG8_BAR;
.LBB0_864:
	v_add_u32_e32 v36, s43, v172
	ds_read_b128 v[8:11], v36
	ds_read_b128 v[12:15], v36 offset:1024
	ds_read_b128 v[32:35], v36 offset:2048
	ds_read_b128 v[36:39], v36 offset:3072
	v_lshl_add_u64 v[158:159], s[34:35], 0, v[150:151]
	s_add_i32 m0, s46, 0xc000
	ds_read_b128 v[154:157], v174
	ds_read_b128 v[176:179], v174 offset:1024
	ds_read_b128 v[180:183], v174 offset:2048
	ds_read_b128 v[196:199], v174 offset:3072
	ds_read_b128 v[208:211], v174 offset:4096
	ds_read_b128 v[212:215], v174 offset:5120
	ds_read_b128 v[216:219], v174 offset:6144
	ds_read_b128 v[220:223], v174 offset:7168
	global_load_lds_dwordx4 v[158:159], off
	s_add_i32 m0, s46, 0xe000
	v_lshl_add_u64 v[158:159], s[34:35], 0, v[152:153]
	global_load_lds_dwordx4 v[158:159], off
	s_waitcnt lgkmcnt(8)
	s_barrier
	s_waitcnt lgkmcnt(0)
	s_setprio 1
	v_mfma_f32_16x16x32_bf16 v[140:143], v[8:11], v[154:157], v[140:143]
	v_mfma_f32_16x16x32_bf16 v[136:139], v[32:35], v[154:157], v[136:139]
	v_mfma_f32_16x16x32_bf16 v[124:127], v[8:11], v[180:183], v[124:127]
	v_mfma_f32_16x16x32_bf16 v[120:123], v[32:35], v[180:183], v[120:123]
	v_mfma_f32_16x16x32_bf16 v[108:111], v[8:11], v[208:211], v[108:111]
	v_mfma_f32_16x16x32_bf16 v[104:107], v[32:35], v[208:211], v[104:107]
	v_mfma_f32_16x16x32_bf16 v[92:95], v[8:11], v[216:219], v[92:95]
	v_mfma_f32_16x16x32_bf16 v[88:91], v[32:35], v[216:219], v[88:91]
	v_mfma_f32_16x16x32_bf16 v[140:143], v[12:15], v[176:179], v[140:143]
	v_mfma_f32_16x16x32_bf16 v[136:139], v[36:39], v[176:179], v[136:139]
	v_mfma_f32_16x16x32_bf16 v[124:127], v[12:15], v[196:199], v[124:127]
	v_mfma_f32_16x16x32_bf16 v[120:123], v[36:39], v[196:199], v[120:123]
	v_mfma_f32_16x16x32_bf16 v[108:111], v[12:15], v[212:215], v[108:111]
	v_mfma_f32_16x16x32_bf16 v[104:107], v[36:39], v[212:215], v[104:107]
	v_mfma_f32_16x16x32_bf16 v[92:95], v[12:15], v[220:223], v[92:95]
	v_mfma_f32_16x16x32_bf16 v[88:91], v[36:39], v[220:223], v[88:91]
	s_setprio 0
	s_barrier
	v_add_u32_e32 v158, s48, v172
	s_mov_b32 m0, s44
	ds_read_b128 v[224:227], v158
	ds_read_b128 v[228:231], v158 offset:1024
	ds_read_b128 v[232:235], v158 offset:2048
	ds_read_b128 v[236:239], v158 offset:3072
	v_lshl_add_u64 v[158:159], s[36:37], 0, v[160:161]
	global_load_lds_dwordx4 v[158:159], off
	s_mov_b32 m0, s45
	v_lshl_add_u64 v[166:167], s[36:37], 0, v[148:149]
	global_load_lds_dwordx4 v[166:167], off
	s_barrier
	s_waitcnt lgkmcnt(0)
	s_setprio 1
	v_mfma_f32_16x16x32_bf16 v[132:135], v[224:227], v[154:157], v[132:135]
	v_mfma_f32_16x16x32_bf16 v[128:131], v[232:235], v[154:157], v[128:131]
	v_mfma_f32_16x16x32_bf16 v[116:119], v[224:227], v[180:183], v[116:119]
	v_mfma_f32_16x16x32_bf16 v[112:115], v[232:235], v[180:183], v[112:115]
	v_mfma_f32_16x16x32_bf16 v[100:103], v[224:227], v[208:211], v[100:103]
	v_mfma_f32_16x16x32_bf16 v[96:99], v[232:235], v[208:211], v[96:99]
	v_mfma_f32_16x16x32_bf16 v[84:87], v[224:227], v[216:219], v[84:87]
	v_mfma_f32_16x16x32_bf16 v[80:83], v[232:235], v[216:219], v[80:83]
	v_mfma_f32_16x16x32_bf16 v[132:135], v[228:231], v[176:179], v[132:135]
	v_mfma_f32_16x16x32_bf16 v[128:131], v[236:239], v[176:179], v[128:131]
	v_mfma_f32_16x16x32_bf16 v[116:119], v[228:231], v[196:199], v[116:119]
	v_mfma_f32_16x16x32_bf16 v[112:115], v[236:239], v[196:199], v[112:115]
	v_mfma_f32_16x16x32_bf16 v[100:103], v[228:231], v[212:215], v[100:103]
	v_mfma_f32_16x16x32_bf16 v[96:99], v[236:239], v[212:215], v[96:99]
	v_mfma_f32_16x16x32_bf16 v[84:87], v[228:231], v[220:223], v[84:87]
	v_mfma_f32_16x16x32_bf16 v[80:83], v[236:239], v[220:223], v[80:83]
	s_setprio 0
	s_mov_b32 m0, s46
	v_lshl_add_u64 v[170:171], s[38:39], 0, v[144:145]
	s_barrier
	ds_read_b128 v[154:157], v174 offset:16384
	ds_read_b128 v[176:179], v174 offset:17408
	ds_read_b128 v[180:183], v174 offset:18432
	ds_read_b128 v[196:199], v174 offset:19456
	ds_read_b128 v[208:211], v174 offset:20480
	ds_read_b128 v[212:215], v174 offset:21504
	ds_read_b128 v[216:219], v174 offset:22528
	ds_read_b128 v[220:223], v174 offset:23552
	global_load_lds_dwordx4 v[170:171], off
	s_mov_b32 m0, s47
	v_lshl_add_u64 v[184:185], s[38:39], 0, v[146:147]
	global_load_lds_dwordx4 v[184:185], off
	s_barrier
	s_waitcnt lgkmcnt(0)
	s_setprio 1
	v_mfma_f32_16x16x32_bf16 v[76:79], v[8:11], v[154:157], v[76:79]
	v_mfma_f32_16x16x32_bf16 v[72:75], v[32:35], v[154:157], v[72:75]
	v_mfma_f32_16x16x32_bf16 v[60:63], v[8:11], v[180:183], v[60:63]
	v_mfma_f32_16x16x32_bf16 v[56:59], v[32:35], v[180:183], v[56:59]
	v_mfma_f32_16x16x32_bf16 v[44:47], v[8:11], v[208:211], v[44:47]
	v_mfma_f32_16x16x32_bf16 v[40:43], v[32:35], v[208:211], v[40:43]
	v_mfma_f32_16x16x32_bf16 v[8:11], v[8:11], v[216:219], v[20:23]
	v_mfma_f32_16x16x32_bf16 v[76:79], v[12:15], v[176:179], v[76:79]
	v_mfma_f32_16x16x32_bf16 v[72:75], v[36:39], v[176:179], v[72:75]
	v_mfma_f32_16x16x32_bf16 v[60:63], v[12:15], v[196:199], v[60:63]
	v_mfma_f32_16x16x32_bf16 v[56:59], v[36:39], v[196:199], v[56:59]
	v_mfma_f32_16x16x32_bf16 v[44:47], v[12:15], v[212:215], v[44:47]
	v_mfma_f32_16x16x32_bf16 v[40:43], v[36:39], v[212:215], v[40:43]
	v_mfma_f32_16x16x32_bf16 v[8:11], v[12:15], v[220:223], v[8:11]
	v_mfma_f32_16x16x32_bf16 v[12:15], v[32:35], v[216:219], v[16:19]
	v_mfma_f32_16x16x32_bf16 v[12:15], v[36:39], v[220:223], v[12:15]
	s_setprio 0
	s_barrier
	s_add_u32 s66, s36, 0x80000
	s_addc_u32 s67, s37, 0
	s_mov_b32 m0, s49
	v_lshl_add_u64 v[16:17], s[66:67], 0, v[160:161]
	global_load_lds_dwordx4 v[16:17], off
	s_mov_b32 m0, s50
	v_lshl_add_u64 v[16:17], s[66:67], 0, v[148:149]
	global_load_lds_dwordx4 v[16:17], off
	s_waitcnt vmcnt(6)
	s_barrier
; #define PG8_STAGE(bufoff, gbase, voff) do { _Pragma("unroll") for (int _i = 0; _i < 2; ++_i) \
;         __builtin_amdgcn_global_load_lds((const unsigned*)((const char*)(gbase) + (voff)[_i]), (LAS unsigned*)(lds + (bufoff) + ldsw + _i * 8192), 16, 0, 0); } while (0)
; #define PG8_LDA(dst, b, h) do { _Pragma("unroll") for (int m = 0; m < 4; ++m) _Pragma("unroll") for (int k = 0; k < 2; ++k) dst[m][k] = *(const LAS bf16x8*)(lds + PG8_SA(b, h) + aoff + m * 2048 + k * 1024); } while (0)
; #define PG8_LDB(dst, b, h) do { _Pragma("unroll") for (int n = 0; n < 2; ++n) _Pragma("unroll") for (int k = 0; k < 2; ++k) dst[n][k] = *(const LAS bf16x8*)(lds + PG8_SB(b, h) + boff + n * 2048 + k * 1024); } while (0)
; #define PG8_WAIT_V(n) asm volatile("s_waitcnt vmcnt(" #n ")" ::: "memory")
; #define PG8_WAIT_L(n) asm volatile("s_waitcnt lgkmcnt(" #n ")" ::: "memory")
; #define PG8_BAR __builtin_amdgcn_s_barrier()
; #define PG8_SCHED __builtin_amdgcn_sched_barrier(0)
; template <class Epi>
; __device__ __forceinline__ void gemm_phase(const int TID, const int BID, LAS unsigned char* lds, const Gemm g, const StaticOrder& S, const Epi& E) {
;     ...
;             PG8_LDB(B0, 0, 0); PG8_SCHED; PG8_LDA(At, 0, 0); PG8_STAGE(PG8_SA(1, 1), a1 + hstepA, voffA);
;             PG8_WAIT_L(8); PG8_BAR; PG8_WAIT_L(0); PG8_MMA(0, 0, At, B0); PG8_BAR; PG8_SCHED;
;             PG8_LDB(B1, 0, 1); PG8_STAGE(PG8_SB(0, 0), b2, voffB);
;             PG8_BAR; PG8_WAIT_L(0); PG8_MMA(0, 1, At, B1); PG8_BAR;
;             PG8_LDA(At, 0, 1); PG8_STAGE(PG8_SA(0, 0), a2, voffA);
;             PG8_BAR; PG8_WAIT_L(0); PG8_MMA(1, 0, At, B0); PG8_BAR; PG8_SCHED;
;             PG8_STAGE(PG8_SB(0, 1), b2 + hstepB, voffB);
;             PG8_WAIT_V(6); PG8_BAR; PG8_MMA(1, 1, At, B1); PG8_BAR;
;             PG8_LDB(B0, 1, 0); PG8_SCHED; PG8_LDA(At, 1, 0); PG8_STAGE(PG8_SA(0, 1), a2 + hstepA, voffA);
;             PG8_WAIT_L(8); PG8_BAR; PG8_WAIT_L(0); PG8_MMA(0, 0, At, B0); PG8_BAR; PG8_SCHED;
;             PG8_LDB(B1, 1, 1); PG8_STAGE(PG8_SB(1, 0), b3, voffB);
;             PG8_BAR; PG8_WAIT_L(0); PG8_MMA(0, 1, At, B1); PG8_BAR;
;             PG8_LDA(At, 1, 1); PG8_STAGE(PG8_SA(1, 0), a3, voffA);
;             PG8_BAR; PG8_WAIT_L(0); PG8_MMA(1, 0, At, B0); PG8_BAR; PG8_SCHED;
;             PG8_STAGE(PG8_SB(1, 1), b3 + hstepB, voffB);
;             PG8_WAIT_V(6); PG8_BAR; PG8_MMA(1, 1, At, B1); PG8_BAR;
	s_setprio 1
	v_mfma_f32_16x16x32_bf16 v[16:19], v[224:227], v[154:157], v[68:71]
	v_mfma_f32_16x16x32_bf16 v[32:35], v[228:231], v[176:179], v[16:19]
	v_mfma_f32_16x16x32_bf16 v[16:19], v[232:235], v[154:157], v[64:67]
	v_mfma_f32_16x16x32_bf16 v[36:39], v[236:239], v[176:179], v[16:19]
	v_mfma_f32_16x16x32_bf16 v[16:19], v[224:227], v[180:183], v[52:55]
	v_mfma_f32_16x16x32_bf16 v[52:55], v[228:231], v[196:199], v[16:19]
	v_mfma_f32_16x16x32_bf16 v[16:19], v[232:235], v[180:183], v[48:51]
	v_mfma_f32_16x16x32_bf16 v[48:51], v[236:239], v[196:199], v[16:19]
	v_mfma_f32_16x16x32_bf16 v[16:19], v[224:227], v[208:211], v[28:31]
	v_mfma_f32_16x16x32_bf16 v[28:31], v[228:231], v[212:215], v[16:19]
	v_mfma_f32_16x16x32_bf16 v[16:19], v[232:235], v[208:211], v[24:27]
	v_mfma_f32_16x16x32_bf16 v[4:7], v[224:227], v[216:219], v[4:7]
	v_mfma_f32_16x16x32_bf16 v[0:3], v[232:235], v[216:219], v[0:3]
	v_mfma_f32_16x16x32_bf16 v[24:27], v[236:239], v[212:215], v[16:19]
	v_mfma_f32_16x16x32_bf16 v[4:7], v[228:231], v[220:223], v[4:7]
	v_mfma_f32_16x16x32_bf16 v[0:3], v[236:239], v[220:223], v[0:3]
	s_setprio 0
	v_add_u32_e32 v68, s53, v172
	s_barrier
	ds_read_b128 v[16:19], v68
	ds_read_b128 v[20:23], v68 offset:1024
	ds_read_b128 v[64:67], v68 offset:2048
	ds_read_b128 v[68:71], v68 offset:3072
	s_add_u32 s38, s38, 0x80000
	s_addc_u32 s39, s39, 0
	s_mov_b32 m0, s51
	v_lshl_add_u64 v[200:201], s[38:39], 0, v[144:145]
	ds_read_b128 v[154:157], v174 offset:32768
	ds_read_b128 v[176:179], v174 offset:33792
	ds_read_b128 v[180:183], v174 offset:34816
	ds_read_b128 v[196:199], v174 offset:35840
	ds_read_b128 v[208:211], v174 offset:36864
	ds_read_b128 v[212:215], v174 offset:37888
	ds_read_b128 v[216:219], v174 offset:38912
	ds_read_b128 v[220:223], v174 offset:39936
	global_load_lds_dwordx4 v[200:201], off
	s_mov_b32 m0, s52
	v_lshl_add_u64 v[200:201], s[38:39], 0, v[146:147]
	global_load_lds_dwordx4 v[200:201], off
	s_waitcnt lgkmcnt(8)
	s_barrier
	s_waitcnt lgkmcnt(0)
	s_setprio 1
	v_mfma_f32_16x16x32_bf16 v[140:143], v[16:19], v[154:157], v[140:143]
	v_mfma_f32_16x16x32_bf16 v[136:139], v[64:67], v[154:157], v[136:139]
	v_mfma_f32_16x16x32_bf16 v[124:127], v[16:19], v[180:183], v[124:127]
	v_mfma_f32_16x16x32_bf16 v[120:123], v[64:67], v[180:183], v[120:123]
	v_mfma_f32_16x16x32_bf16 v[108:111], v[16:19], v[208:211], v[108:111]
	v_mfma_f32_16x16x32_bf16 v[104:107], v[64:67], v[208:211], v[104:107]
	v_mfma_f32_16x16x32_bf16 v[92:95], v[16:19], v[216:219], v[92:95]
	v_mfma_f32_16x16x32_bf16 v[88:91], v[64:67], v[216:219], v[88:91]
	v_mfma_f32_16x16x32_bf16 v[140:143], v[20:23], v[176:179], v[140:143]
	v_mfma_f32_16x16x32_bf16 v[136:139], v[68:71], v[176:179], v[136:139]
	v_mfma_f32_16x16x32_bf16 v[124:127], v[20:23], v[196:199], v[124:127]
	v_mfma_f32_16x16x32_bf16 v[120:123], v[68:71], v[196:199], v[120:123]
	v_mfma_f32_16x16x32_bf16 v[108:111], v[20:23], v[212:215], v[108:111]
	v_mfma_f32_16x16x32_bf16 v[104:107], v[68:71], v[212:215], v[104:107]
	v_mfma_f32_16x16x32_bf16 v[92:95], v[20:23], v[220:223], v[92:95]
	v_mfma_f32_16x16x32_bf16 v[88:91], v[68:71], v[220:223], v[88:91]
	s_setprio 0
	s_barrier
	s_mov_b32 m0, s54
	v_add_u32_e32 v168, s58, v172
	v_lshl_add_u64 v[158:159], v[158:159], 0, s[90:91]
	ds_read_b128 v[224:227], v168
	ds_read_b128 v[228:231], v168 offset:1024
	ds_read_b128 v[232:235], v168 offset:2048
	ds_read_b128 v[236:239], v168 offset:3072
	global_load_lds_dwordx4 v[158:159], off
	s_mov_b32 m0, s55
	v_lshl_add_u64 v[158:159], v[166:167], 0, s[90:91]
	global_load_lds_dwordx4 v[158:159], off
	s_barrier
	s_waitcnt lgkmcnt(0)
	s_setprio 1
	v_mfma_f32_16x16x32_bf16 v[132:135], v[224:227], v[154:157], v[132:135]
	v_mfma_f32_16x16x32_bf16 v[128:131], v[232:235], v[154:157], v[128:131]
	v_mfma_f32_16x16x32_bf16 v[116:119], v[224:227], v[180:183], v[116:119]
	v_mfma_f32_16x16x32_bf16 v[112:115], v[232:235], v[180:183], v[112:115]
	v_mfma_f32_16x16x32_bf16 v[100:103], v[224:227], v[208:211], v[100:103]
	v_mfma_f32_16x16x32_bf16 v[96:99], v[232:235], v[208:211], v[96:99]
	v_mfma_f32_16x16x32_bf16 v[84:87], v[224:227], v[216:219], v[84:87]
	v_mfma_f32_16x16x32_bf16 v[80:83], v[232:235], v[216:219], v[80:83]
	v_mfma_f32_16x16x32_bf16 v[132:135], v[228:231], v[176:179], v[132:135]
	v_mfma_f32_16x16x32_bf16 v[128:131], v[236:239], v[176:179], v[128:131]
	v_mfma_f32_16x16x32_bf16 v[116:119], v[228:231], v[196:199], v[116:119]
	v_mfma_f32_16x16x32_bf16 v[112:115], v[236:239], v[196:199], v[112:115]
	v_mfma_f32_16x16x32_bf16 v[100:103], v[228:231], v[212:215], v[100:103]
	v_mfma_f32_16x16x32_bf16 v[96:99], v[236:239], v[212:215], v[96:99]
	v_mfma_f32_16x16x32_bf16 v[84:87], v[228:231], v[220:223], v[84:87]
	v_mfma_f32_16x16x32_bf16 v[80:83], v[236:239], v[220:223], v[80:83]
	s_setprio 0
	s_mov_b32 m0, s56
	v_lshl_add_u64 v[158:159], v[170:171], 0, s[90:91]
	s_barrier
	ds_read_b128 v[154:157], v174 offset:49152
	ds_read_b128 v[176:179], v174 offset:50176
	ds_read_b128 v[180:183], v174 offset:51200
	ds_read_b128 v[196:199], v174 offset:52224
	ds_read_b128 v[208:211], v174 offset:53248
	ds_read_b128 v[212:215], v174 offset:54272
	ds_read_b128 v[216:219], v174 offset:55296
	ds_read_b128 v[220:223], v174 offset:56320
	global_load_lds_dwordx4 v[158:159], off
	s_mov_b32 m0, s57
	v_lshl_add_u64 v[158:159], v[184:185], 0, s[90:91]
	global_load_lds_dwordx4 v[158:159], off
	s_barrier
; __device__ __forceinline__ float rinv_st(stat_t s, float invn) { return rsqrtf((float)((double)s * (1.0 / 4294967296.0)) * invn + 1e-6f); }
; #define PG8_LDA(dst, b, h) do { _Pragma("unroll") for (int m = 0; m < 4; ++m) _Pragma("unroll") for (int k = 0; k < 2; ++k) dst[m][k] = *(const LAS bf16x8*)(lds + PG8_SA(b, h) + aoff + m * 2048 + k * 1024); } while (0)
; template <class Epi>
; __device__ __forceinline__ void gemm_phase(const int TID, const int BID, LAS unsigned char* lds, const Gemm g, const StaticOrder& S, const Epi& E) {
;     ...
;             PG8_WAIT_V(6); PG8_BAR; PG8_MMA(1, 1, At, B1); PG8_BAR;
;             PG8_LDB(B0, 1, 0); PG8_SCHED; PG8_LDA(At, 1, 0); PG8_STAGE(PG8_SA(0, 1), a2 + hstepA, voffA);
;             PG8_WAIT_L(8); PG8_BAR; PG8_WAIT_L(0); PG8_MMA(0, 0, At, B0); PG8_BAR; PG8_SCHED;
;             PG8_LDB(B1, 1, 1); PG8_STAGE(PG8_SB(1, 0), b3, voffB);
;             PG8_BAR; PG8_WAIT_L(0); PG8_MMA(0, 1, At, B1); PG8_BAR;
;             PG8_LDA(At, 1, 1); PG8_STAGE(PG8_SA(1, 0), a3, voffA);
;             PG8_BAR; PG8_WAIT_L(0); PG8_MMA(1, 0, At, B0); PG8_BAR; PG8_SCHED;
;             PG8_STAGE(PG8_SB(1, 1), b3 + hstepB, voffB);
;             PG8_WAIT_V(6); PG8_BAR; PG8_MMA(1, 1, At, B1); PG8_BAR;
;     __device__ __forceinline__ void operator()(const f32x4 (&acc)[2][2][4][2], const Unit& u, int wr, int wc, int fr, int fq) const {
;         const int row0 = u.pm * BM + wr * 64 + fr, col0 = u.pn * BM + wc * 32 + 8 * fq;
;         f32x4 bv[2][2];
; #pragma unroll
;         for (int bj = 0; bj < 2; ++bj)
; #pragma unroll
;             for (int n = 0; n < 2; ++n) bv[bj][n] = *(const f32x4*)(bias + col0 + bj * HALF + 4 * n);
;         const bool isv = u.pn >= 8;
; #pragma unroll
;         for (int ai = 0; ai < 2; ++ai)
; #pragma unroll
;             for (int m = 0; m < 4; ++m) {
;                 const int row = row0 + ai * HALF + m * 16; const float r = rinv_st(stats[row], 1.0f / 2048.0f);
;                 bf16_t* rowp = uv + (size_t)row * 4096 + col0; float ss = 0.f;
; #pragma unroll
;                 for (int bj = 0; bj < 2; ++bj) {
;                     const f32x4 v0 = acc[ai][bj][m][0] * r + bv[bj][0], v1 = acc[ai][bj][m][1] * r + bv[bj][1];
;                     const f32x2 a = gelu_pk((f32x2){v0[0], v0[1]}), b = gelu_pk((f32x2){v0[2], v0[3]}), c = gelu_pk((f32x2){v1[0], v1[1]}), d = gelu_pk((f32x2){v1[2], v1[3]});
	s_waitcnt lgkmcnt(0)
	s_setprio 1
	v_mfma_f32_16x16x32_bf16 v[76:79], v[16:19], v[154:157], v[76:79]
	v_mfma_f32_16x16x32_bf16 v[60:63], v[16:19], v[180:183], v[60:63]
	v_mfma_f32_16x16x32_bf16 v[44:47], v[16:19], v[208:211], v[44:47]
	v_mfma_f32_16x16x32_bf16 v[8:11], v[16:19], v[216:219], v[8:11]
	v_mfma_f32_16x16x32_bf16 v[76:79], v[20:23], v[176:179], v[76:79]
	v_mfma_f32_16x16x32_bf16 v[72:75], v[64:67], v[154:157], v[72:75]
	v_mfma_f32_16x16x32_bf16 v[60:63], v[20:23], v[196:199], v[60:63]
	v_mfma_f32_16x16x32_bf16 v[56:59], v[64:67], v[180:183], v[56:59]
	v_mfma_f32_16x16x32_bf16 v[44:47], v[20:23], v[212:215], v[44:47]
	v_mfma_f32_16x16x32_bf16 v[40:43], v[64:67], v[208:211], v[40:43]
	v_mfma_f32_16x16x32_bf16 v[20:23], v[20:23], v[220:223], v[8:11]
	v_mfma_f32_16x16x32_bf16 v[8:11], v[64:67], v[216:219], v[12:15]
	v_mfma_f32_16x16x32_bf16 v[72:75], v[68:71], v[176:179], v[72:75]
	v_mfma_f32_16x16x32_bf16 v[56:59], v[68:71], v[196:199], v[56:59]
	v_mfma_f32_16x16x32_bf16 v[40:43], v[68:71], v[212:215], v[40:43]
	v_mfma_f32_16x16x32_bf16 v[16:19], v[68:71], v[220:223], v[8:11]
	s_setprio 0
	s_barrier
	s_add_u32 s36, s36, 0x80080
	s_addc_u32 s37, s37, 0
	s_mov_b32 m0, s59
	v_lshl_add_u64 v[8:9], s[36:37], 0, v[160:161]
	global_load_lds_dwordx4 v[8:9], off
	s_mov_b32 m0, s60
	v_lshl_add_u64 v[8:9], s[36:37], 0, v[148:149]
	global_load_lds_dwordx4 v[8:9], off
	s_waitcnt vmcnt(6)
	s_barrier
	s_setprio 1
	v_mfma_f32_16x16x32_bf16 v[8:11], v[224:227], v[154:157], v[32:35]
	v_mfma_f32_16x16x32_bf16 v[68:71], v[228:231], v[176:179], v[8:11]
	v_mfma_f32_16x16x32_bf16 v[8:11], v[232:235], v[154:157], v[36:39]
	v_mfma_f32_16x16x32_bf16 v[64:67], v[236:239], v[176:179], v[8:11]
	v_mfma_f32_16x16x32_bf16 v[8:11], v[224:227], v[180:183], v[52:55]
	v_mfma_f32_16x16x32_bf16 v[52:55], v[228:231], v[196:199], v[8:11]
	v_mfma_f32_16x16x32_bf16 v[8:11], v[232:235], v[180:183], v[48:51]
	v_mfma_f32_16x16x32_bf16 v[48:51], v[236:239], v[196:199], v[8:11]
	v_mfma_f32_16x16x32_bf16 v[8:11], v[224:227], v[208:211], v[28:31]
	v_mfma_f32_16x16x32_bf16 v[28:31], v[228:231], v[212:215], v[8:11]
	v_mfma_f32_16x16x32_bf16 v[8:11], v[232:235], v[208:211], v[24:27]
	v_mfma_f32_16x16x32_bf16 v[4:7], v[224:227], v[216:219], v[4:7]
	v_mfma_f32_16x16x32_bf16 v[0:3], v[232:235], v[216:219], v[0:3]
	v_mfma_f32_16x16x32_bf16 v[24:27], v[236:239], v[212:215], v[8:11]
	v_mfma_f32_16x16x32_bf16 v[4:7], v[228:231], v[220:223], v[4:7]
	v_mfma_f32_16x16x32_bf16 v[0:3], v[236:239], v[220:223], v[0:3]
	s_setprio 0
	s_add_i32 s31, s31, 2
	s_add_u32 s34, s34, 0x100
	s_addc_u32 s35, s35, 0
	s_add_u32 s23, s23, 0x100
	s_addc_u32 s29, s29, 0
	s_add_u32 s36, s34, 0xfff80080
	s_addc_u32 s37, s35, -1
	s_cmp_eq_u32 s31, 28
	s_cselect_b32 s39, s0, s37
	s_cselect_b32 s38, s1, s36
	s_cselect_b32 s37, s4, s29
	s_cselect_b32 s36, s21, s23
	s_cmp_gt_u32 s31, 29
	s_cbranch_scc0 .Lrot_864
	s_barrier
	v_readlane_b32 s0, v254, 32
	v_readlane_b32 s1, v254, 33
	s_load_dwordx2 s[0:1], s[0:1], 0x50
	v_lshl_or_b32 v154, s30, 8, v173
	v_lshl_add_u32 v156, s28, 8, v169
	v_ashrrev_i32_e32 v155, 31, v154
	v_ashrrev_i32_e32 v157, 31, v156
	s_waitcnt lgkmcnt(0)
	v_lshl_add_u64 v[12:13], v[154:155], 2, s[0:1]
	v_lshl_add_u64 v[158:159], v[156:157], 3, s[16:17]
	global_load_dwordx4 v[32:35], v[12:13], off offset:16
	global_load_dwordx4 v[36:39], v[12:13], off
	global_load_dwordx4 v[8:11], v[12:13], off offset:528
	s_nop 0
	global_load_dwordx4 v[12:15], v[12:13], off offset:512
	s_cmp_gt_i32 s30, 7
	global_load_dwordx2 v[166:167], v[158:159], off
	global_load_dwordx2 v[208:209], v[158:159], off offset:128
	global_load_dwordx2 v[210:211], v[158:159], off offset:256
	global_load_dwordx2 v[212:213], v[158:159], off offset:384
	global_load_dwordx2 v[214:215], v[158:159], off offset:1024
	global_load_dwordx2 v[216:217], v[158:159], off offset:1152
	global_load_dwordx2 v[218:219], v[158:159], off offset:1280
	global_load_dwordx2 v[220:221], v[158:159], off offset:1408
	s_mov_b32 s30, 0xbf38aa3b
	s_cselect_b64 s[0:1], -1, 0
	s_and_b64 s[28:29], s[8:9], s[0:1]
	s_mov_b32 s0, 0xbe11a98e
	s_mov_b32 s4, 0x3e027906
	s_waitcnt vmcnt(0)
	v_cvt_f64_u32_e32 v[170:171], v167
	v_ldexp_f64 v[170:171], v[170:171], 32
	v_cvt_f64_u32_e32 v[166:167], v166
	v_add_f64 v[166:167], v[170:171], v[166:167]
	v_ldexp_f64 v[166:167], v[166:167], s93
	v_cvt_f32_f64_e32 v166, v[166:167]
	v_fmamk_f32 v166, v166, 0x3a000000, v189
	v_cmp_gt_f32_e32 vcc, s78, v166
	v_mul_f32_e32 v167, 0x4b800000, v166
	s_nop 0
	v_cndmask_b32_e32 v166, v166, v167, vcc
	v_rsq_f32_e32 v166, v166
	s_nop 0
	v_mul_f32_e32 v167, 0x45800000, v166
	v_cndmask_b32_e32 v168, v166, v167, vcc
	v_pk_fma_f32 v[170:171], v[140:141], v[168:169], v[36:37] op_sel_hi:[1,0,1]
	v_pk_fma_f32 v[140:141], v[136:137], v[168:169], v[32:33] op_sel_hi:[1,0,1]
	v_and_b32_e32 v137, 0x7fffffff, v171
	v_and_b32_e32 v136, 0x7fffffff, v170
	v_pk_fma_f32 v[136:137], v[136:137], s[64:65], 1.0 op_sel_hi:[1,0,0]
	v_pk_mul_f32 v[180:181], v[170:171], v[170:171]
	v_rcp_f32_e32 v176, v136
	v_rcp_f32_e32 v177, v137
	v_mov_b64_e32 v[136:137], s[80:81]
	v_pk_mul_f32 v[180:181], v[180:181], s[30:31] op_sel_hi:[1,0]
	v_cmp_gt_f32_e32 vcc, 0, v170
	v_pk_fma_f32 v[178:179], v[176:177], s[74:75], v[136:137] op_sel_hi:[1,0,0]
	v_exp_f32_e32 v180, v180
	v_pk_fma_f32 v[178:179], v[176:177], v[178:179], s[86:87] op_sel_hi:[1,1,0]
	v_exp_f32_e32 v181, v181
	v_pk_fma_f32 v[178:179], v[176:177], v[178:179], s[0:1] op_sel_hi:[1,1,0]
	v_pk_fma_f32 v[142:143], v[142:143], v[168:169], v[38:39] op_sel_hi:[1,0,1]
	v_pk_fma_f32 v[178:179], v[176:177], v[178:179], s[4:5] op_sel_hi:[1,1,0]
; __device__ __forceinline__ unsigned cvt_pk_bf16(float lo, float hi) { unsigned r; asm volatile("v_cvt_pk_bf16_f32 %0, %1, %2" : "=v"(r) : "v"(lo), "v"(hi)); return r; }
; __device__ __forceinline__ float rinv_st(stat_t s, float invn) { return rsqrtf((float)((double)s * (1.0 / 4294967296.0)) * invn + 1e-6f); }
; __device__ __forceinline__ f32x2 gelu_pk(f32x2 v) {
;     const f32x2 av = __builtin_elementwise_abs(v), d = av * 0.2316418882f + 1.0f;
;     f32x2 t; t.x = __builtin_amdgcn_rcpf(d.x); t.y = __builtin_amdgcn_rcpf(d.y);
;     f32x2 q = t * 0.5307027145f + (-0.7265760135f); q = q * t + 0.7107068705f; q = q * t + (-0.142248368f); q = q * t + 0.127414796f; q = q * t;
;     const f32x2 s = (v * v) * (-0.72134752044f);
;     f32x2 e; e.x = __builtin_amdgcn_exp2f(s.x); e.y = __builtin_amdgcn_exp2f(s.y);
;     const f32x2 m = v * (q * e), r = v - m;
;     f32x2 o; o.x = v.x < 0.f ? m.x : r.x; o.y = v.y < 0.f ? m.y : r.y; return o;
;     __device__ __forceinline__ void operator()(const f32x4 (&acc)[2][2][4][2], const Unit& u, int wr, int wc, int fr, int fq) const {
;     ...
;                 const int row = row0 + ai * HALF + m * 16; const float r = rinv_st(stats[row], 1.0f / 2048.0f);
;                 bf16_t* rowp = uv + (size_t)row * 4096 + col0; float ss = 0.f;
; #pragma unroll
;                 for (int bj = 0; bj < 2; ++bj) {
;                     const f32x4 v0 = acc[ai][bj][m][0] * r + bv[bj][0], v1 = acc[ai][bj][m][1] * r + bv[bj][1];
;                     const f32x2 a = gelu_pk((f32x2){v0[0], v0[1]}), b = gelu_pk((f32x2){v0[2], v0[3]}), c = gelu_pk((f32x2){v1[0], v1[1]}), d = gelu_pk((f32x2){v1[2], v1[3]});
;                     ss += a.x * a.x + a.y * a.y + b.x * b.x + b.y * b.y + c.x * c.x + c.y * c.y + d.x * d.x + d.y * d.y;
;                     u32x4 w; w.x = cvt_pk_bf16(a.x, a.y); w.y = cvt_pk_bf16(b.x, b.y); w.z = cvt_pk_bf16(c.x, c.y); w.w = cvt_pk_bf16(d.x, d.y);
;                     *(u32x4*)(rowp + bj * HALF) = w;
	v_pk_fma_f32 v[138:139], v[138:139], v[168:169], v[34:35] op_sel_hi:[1,0,1]
	v_pk_mul_f32 v[176:177], v[176:177], v[178:179]
	v_pk_mul_f32 v[178:179], v[142:143], v[142:143]
	v_pk_mul_f32 v[176:177], v[180:181], v[176:177]
	v_pk_mul_f32 v[178:179], v[178:179], s[30:31] op_sel_hi:[1,0]
	v_pk_mul_f32 v[180:181], v[170:171], v[176:177]
	v_pk_fma_f32 v[176:177], v[170:171], v[176:177], v[170:171] neg_lo:[1,0,0] neg_hi:[1,0,0]
	v_exp_f32_e32 v178, v178
	v_cndmask_b32_e32 v170, v176, v180, vcc
	v_cmp_gt_f32_e32 vcc, 0, v171
	v_and_b32_e32 v176, 0x7fffffff, v142
	v_exp_f32_e32 v179, v179
	v_cndmask_b32_e32 v171, v177, v181, vcc
	v_and_b32_e32 v177, 0x7fffffff, v143
	v_pk_fma_f32 v[176:177], v[176:177], s[64:65], 1.0 op_sel_hi:[1,0,0]
	v_cmp_gt_f32_e32 vcc, 0, v142
	v_rcp_f32_e32 v176, v176
	v_rcp_f32_e32 v177, v177
	v_lshlrev_b64 v[166:167], 13, v[156:157]
	v_lshl_add_u64 v[166:167], s[14:15], 0, v[166:167]
	v_lshl_add_u64 v[166:167], v[154:155], 1, v[166:167]
	v_pk_fma_f32 v[180:181], v[176:177], s[74:75], v[136:137] op_sel_hi:[1,0,0]
	v_pk_fma_f32 v[132:133], v[132:133], v[168:169], v[12:13] op_sel_hi:[1,0,1]
	v_pk_fma_f32 v[180:181], v[176:177], v[180:181], s[86:87] op_sel_hi:[1,1,0]
	v_pk_fma_f32 v[134:135], v[134:135], v[168:169], v[14:15] op_sel_hi:[1,0,1]
	v_pk_fma_f32 v[180:181], v[176:177], v[180:181], s[0:1] op_sel_hi:[1,1,0]
	v_pk_fma_f32 v[128:129], v[128:129], v[168:169], v[8:9] op_sel_hi:[1,0,1]
	v_pk_fma_f32 v[180:181], v[176:177], v[180:181], s[4:5] op_sel_hi:[1,1,0]
	v_pk_fma_f32 v[130:131], v[130:131], v[168:169], v[10:11] op_sel_hi:[1,0,1]
	v_pk_mul_f32 v[176:177], v[176:177], v[180:181]
	s_nop 0
	v_pk_mul_f32 v[176:177], v[178:179], v[176:177]
	s_nop 0
	v_pk_mul_f32 v[178:179], v[142:143], v[176:177]
	v_pk_fma_f32 v[176:177], v[142:143], v[176:177], v[142:143] neg_lo:[1,0,0] neg_hi:[1,0,0]
	v_and_b32_e32 v142, 0x7fffffff, v140
	v_cndmask_b32_e32 v175, v176, v178, vcc
	v_cmp_gt_f32_e32 vcc, 0, v143
	v_and_b32_e32 v143, 0x7fffffff, v141
	v_pk_fma_f32 v[142:143], v[142:143], s[64:65], 1.0 op_sel_hi:[1,0,0]
	v_cndmask_b32_e32 v180, v177, v179, vcc
	v_rcp_f32_e32 v142, v142
	v_rcp_f32_e32 v143, v143
	v_pk_mul_f32 v[178:179], v[140:141], v[140:141]
	v_cmp_gt_f32_e32 vcc, 0, v140
	v_pk_mul_f32 v[178:179], v[178:179], s[30:31] op_sel_hi:[1,0]
	v_pk_fma_f32 v[176:177], v[142:143], s[74:75], v[136:137] op_sel_hi:[1,0,0]
	v_exp_f32_e32 v178, v178
	v_pk_fma_f32 v[176:177], v[142:143], v[176:177], s[86:87] op_sel_hi:[1,1,0]
	v_exp_f32_e32 v179, v179
	v_pk_fma_f32 v[176:177], v[142:143], v[176:177], s[0:1] op_sel_hi:[1,1,0]
	s_nop 0
	v_pk_fma_f32 v[176:177], v[142:143], v[176:177], s[4:5] op_sel_hi:[1,1,0]
	s_nop 0
	v_pk_mul_f32 v[142:143], v[142:143], v[176:177]
	v_pk_mul_f32 v[176:177], v[138:139], v[138:139]
	v_pk_mul_f32 v[142:143], v[178:179], v[142:143]
	s_nop 0
	v_pk_mul_f32 v[178:179], v[140:141], v[142:143]
	v_pk_fma_f32 v[142:143], v[140:141], v[142:143], v[140:141] neg_lo:[1,0,0] neg_hi:[1,0,0]
	v_and_b32_e32 v140, 0x7fffffff, v138
	v_cndmask_b32_e32 v178, v142, v178, vcc
	v_cmp_gt_f32_e32 vcc, 0, v141
	v_and_b32_e32 v141, 0x7fffffff, v139
	v_pk_fma_f32 v[140:141], v[140:141], s[64:65], 1.0 op_sel_hi:[1,0,0]
	v_cndmask_b32_e32 v179, v143, v179, vcc
	v_rcp_f32_e32 v140, v140
	v_rcp_f32_e32 v141, v141
	v_cmp_gt_f32_e32 vcc, 0, v138
	v_pk_fma_f32 v[142:143], v[140:141], s[74:75], v[136:137] op_sel_hi:[1,0,0]
	s_nop 0
	v_pk_fma_f32 v[142:143], v[140:141], v[142:143], s[86:87] op_sel_hi:[1,1,0]
	s_nop 0
	v_pk_fma_f32 v[142:143], v[140:141], v[142:143], s[0:1] op_sel_hi:[1,1,0]
	s_nop 0
	v_pk_fma_f32 v[142:143], v[140:141], v[142:143], s[4:5] op_sel_hi:[1,1,0]
	s_nop 0
	v_pk_mul_f32 v[140:141], v[140:141], v[142:143]
	v_pk_mul_f32 v[142:143], v[176:177], s[30:31] op_sel_hi:[1,0]
	v_mul_f32_e32 v176, v171, v171
	v_exp_f32_e32 v142, v142
	v_exp_f32_e32 v143, v143
	v_fmac_f32_e32 v176, v170, v170
	v_fmac_f32_e32 v176, v175, v175
	v_fmac_f32_e32 v176, v180, v180
	v_pk_mul_f32 v[140:141], v[142:143], v[140:141]
	v_fmac_f32_e32 v176, v178, v178
	v_pk_mul_f32 v[142:143], v[138:139], v[140:141]
	v_pk_fma_f32 v[140:141], v[138:139], v[140:141], v[138:139] neg_lo:[1,0,0] neg_hi:[1,0,0]
	v_fmac_f32_e32 v176, v179, v179
	v_cndmask_b32_e32 v142, v140, v142, vcc
	v_cmp_gt_f32_e32 vcc, 0, v139
	v_fmac_f32_e32 v176, v142, v142
	v_cvt_pk_bf16_f32 v138, v170, v171
	v_cvt_pk_bf16_f32 v139, v175, v180
	v_cvt_pk_bf16_f32 v140, v178, v179
	s_nop 0
	v_cndmask_b32_e32 v141, v141, v143, vcc
	v_fmac_f32_e32 v176, v141, v141
	v_cvt_pk_bf16_f32 v141, v142, v141
	global_store_dwordx4 v[166:167], v[138:141], off
	v_pk_mul_f32 v[142:143], v[132:133], v[132:133]
	v_cmp_gt_f32_e32 vcc, 0, v132
	v_and_b32_e32 v139, 0x7fffffff, v133
	v_and_b32_e32 v138, 0x7fffffff, v132
	v_pk_fma_f32 v[138:139], v[138:139], s[64:65], 1.0 op_sel_hi:[1,0,0]
	v_pk_mul_f32 v[142:143], v[142:143], s[30:31] op_sel_hi:[1,0]
	v_rcp_f32_e32 v138, v138
	v_rcp_f32_e32 v139, v139
	v_exp_f32_e32 v142, v142
	v_exp_f32_e32 v143, v143
	v_pk_fma_f32 v[140:141], v[138:139], s[74:75], v[136:137] op_sel_hi:[1,0,0]
	s_nop 0
	v_pk_fma_f32 v[140:141], v[138:139], v[140:141], s[86:87] op_sel_hi:[1,1,0]
	s_nop 0
	v_pk_fma_f32 v[140:141], v[138:139], v[140:141], s[0:1] op_sel_hi:[1,1,0]
	s_nop 0
; __device__ __forceinline__ unsigned cvt_pk_bf16(float lo, float hi) { unsigned r; asm volatile("v_cvt_pk_bf16_f32 %0, %1, %2" : "=v"(r) : "v"(lo), "v"(hi)); return r; }
; __device__ __forceinline__ void stat_add(stat_t* p, float ss) { __hip_atomic_fetch_add(p, (stat_t)((double)ss * 4294967296.0), __ATOMIC_RELAXED, __HIP_MEMORY_SCOPE_AGENT); }
; __device__ __forceinline__ f32x2 gelu_pk(f32x2 v) {
;     const f32x2 av = __builtin_elementwise_abs(v), d = av * 0.2316418882f + 1.0f;
;     f32x2 t; t.x = __builtin_amdgcn_rcpf(d.x); t.y = __builtin_amdgcn_rcpf(d.y);
;     f32x2 q = t * 0.5307027145f + (-0.7265760135f); q = q * t + 0.7107068705f; q = q * t + (-0.142248368f); q = q * t + 0.127414796f; q = q * t;
;     const f32x2 s = (v * v) * (-0.72134752044f);
;     f32x2 e; e.x = __builtin_amdgcn_exp2f(s.x); e.y = __builtin_amdgcn_exp2f(s.y);
;     const f32x2 m = v * (q * e), r = v - m;
;     f32x2 o; o.x = v.x < 0.f ? m.x : r.x; o.y = v.y < 0.f ? m.y : r.y; return o;
;     __device__ __forceinline__ void operator()(const f32x4 (&acc)[2][2][4][2], const Unit& u, int wr, int wc, int fr, int fq) const {
;     ...
;                     const f32x4 v0 = acc[ai][bj][m][0] * r + bv[bj][0], v1 = acc[ai][bj][m][1] * r + bv[bj][1];
;                     const f32x2 a = gelu_pk((f32x2){v0[0], v0[1]}), b = gelu_pk((f32x2){v0[2], v0[3]}), c = gelu_pk((f32x2){v1[0], v1[1]}), d = gelu_pk((f32x2){v1[2], v1[3]});
;                     ss += a.x * a.x + a.y * a.y + b.x * b.x + b.y * b.y + c.x * c.x + c.y * c.y + d.x * d.x + d.y * d.y;
;                     u32x4 w; w.x = cvt_pk_bf16(a.x, a.y); w.y = cvt_pk_bf16(b.x, b.y); w.z = cvt_pk_bf16(c.x, c.y); w.w = cvt_pk_bf16(d.x, d.y);
;                     *(u32x4*)(rowp + bj * HALF) = w;
;                 }
;                 ss += __shfl_xor(ss, 16); ss += __shfl_xor(ss, 32);
;                 if (isv && fq == 0) stat_add(stats_v + row, ss);
	v_pk_fma_f32 v[140:141], v[138:139], v[140:141], s[4:5] op_sel_hi:[1,1,0]
	s_nop 0
	v_pk_mul_f32 v[138:139], v[138:139], v[140:141]
	v_pk_mul_f32 v[140:141], v[134:135], v[134:135]
	v_pk_mul_f32 v[138:139], v[142:143], v[138:139]
	s_nop 0
	v_pk_mul_f32 v[142:143], v[132:133], v[138:139]
	v_pk_fma_f32 v[138:139], v[132:133], v[138:139], v[132:133] neg_lo:[1,0,0] neg_hi:[1,0,0]
	v_and_b32_e32 v132, 0x7fffffff, v134
	v_cndmask_b32_e32 v142, v138, v142, vcc
	v_cmp_gt_f32_e32 vcc, 0, v133
	v_and_b32_e32 v133, 0x7fffffff, v135
	v_pk_fma_f32 v[132:133], v[132:133], s[64:65], 1.0 op_sel_hi:[1,0,0]
	v_cndmask_b32_e32 v143, v139, v143, vcc
	v_rcp_f32_e32 v132, v132
	v_rcp_f32_e32 v133, v133
	v_cmp_gt_f32_e32 vcc, 0, v134
	v_pk_fma_f32 v[138:139], v[132:133], s[74:75], v[136:137] op_sel_hi:[1,0,0]
	s_nop 0
	v_pk_fma_f32 v[138:139], v[132:133], v[138:139], s[86:87] op_sel_hi:[1,1,0]
	s_nop 0
	v_pk_fma_f32 v[138:139], v[132:133], v[138:139], s[0:1] op_sel_hi:[1,1,0]
	s_nop 0
	v_pk_fma_f32 v[138:139], v[132:133], v[138:139], s[4:5] op_sel_hi:[1,1,0]
	s_nop 0
	v_pk_mul_f32 v[132:133], v[132:133], v[138:139]
	v_pk_mul_f32 v[138:139], v[140:141], s[30:31] op_sel_hi:[1,0]
	s_nop 0
	v_exp_f32_e32 v138, v138
	v_exp_f32_e32 v139, v139
	s_nop 0
	v_pk_mul_f32 v[132:133], v[138:139], v[132:133]
	s_nop 0
	v_pk_mul_f32 v[138:139], v[134:135], v[132:133]
	v_pk_fma_f32 v[132:133], v[134:135], v[132:133], v[134:135] neg_lo:[1,0,0] neg_hi:[1,0,0]
	s_nop 0
	v_cndmask_b32_e32 v140, v132, v138, vcc
	v_cmp_gt_f32_e32 vcc, 0, v135
	v_and_b32_e32 v132, 0x7fffffff, v128
	s_nop 0
	v_cndmask_b32_e32 v141, v133, v139, vcc
	v_and_b32_e32 v133, 0x7fffffff, v129
	v_pk_fma_f32 v[132:133], v[132:133], s[64:65], 1.0 op_sel_hi:[1,0,0]
	v_pk_mul_f32 v[138:139], v[128:129], v[128:129]
	v_rcp_f32_e32 v132, v132
	v_rcp_f32_e32 v133, v133
	v_pk_mul_f32 v[138:139], v[138:139], s[30:31] op_sel_hi:[1,0]
	v_cmp_gt_f32_e32 vcc, 0, v128
	v_exp_f32_e32 v138, v138
	v_pk_fma_f32 v[134:135], v[132:133], s[74:75], v[136:137] op_sel_hi:[1,0,0]
	v_exp_f32_e32 v139, v139
	v_pk_fma_f32 v[134:135], v[132:133], v[134:135], s[86:87] op_sel_hi:[1,1,0]
	s_nop 0
	v_pk_fma_f32 v[134:135], v[132:133], v[134:135], s[0:1] op_sel_hi:[1,1,0]
	s_nop 0
	v_pk_fma_f32 v[134:135], v[132:133], v[134:135], s[4:5] op_sel_hi:[1,1,0]
	s_nop 0
	v_pk_mul_f32 v[132:133], v[132:133], v[134:135]
	v_pk_mul_f32 v[134:135], v[130:131], v[130:131]
	v_pk_mul_f32 v[132:133], v[138:139], v[132:133]
	s_nop 0
	v_pk_mul_f32 v[138:139], v[128:129], v[132:133]
	v_pk_fma_f32 v[132:133], v[128:129], v[132:133], v[128:129] neg_lo:[1,0,0] neg_hi:[1,0,0]
	v_and_b32_e32 v128, 0x7fffffff, v130
	v_cndmask_b32_e32 v138, v132, v138, vcc
	v_cmp_gt_f32_e32 vcc, 0, v129
	v_and_b32_e32 v129, 0x7fffffff, v131
	v_pk_fma_f32 v[128:129], v[128:129], s[64:65], 1.0 op_sel_hi:[1,0,0]
	v_cndmask_b32_e32 v139, v133, v139, vcc
	v_rcp_f32_e32 v128, v128
	v_rcp_f32_e32 v129, v129
	v_cmp_gt_f32_e32 vcc, 0, v130
	v_pk_fma_f32 v[132:133], v[128:129], s[74:75], v[136:137] op_sel_hi:[1,0,0]
	s_nop 0
	v_pk_fma_f32 v[132:133], v[128:129], v[132:133], s[86:87] op_sel_hi:[1,1,0]
	s_nop 0
	v_pk_fma_f32 v[132:133], v[128:129], v[132:133], s[0:1] op_sel_hi:[1,1,0]
	s_nop 0
	v_pk_fma_f32 v[132:133], v[128:129], v[132:133], s[4:5] op_sel_hi:[1,1,0]
	s_nop 0
	v_pk_mul_f32 v[128:129], v[128:129], v[132:133]
	v_pk_mul_f32 v[132:133], v[134:135], s[30:31] op_sel_hi:[1,0]
	s_nop 0
	v_exp_f32_e32 v132, v132
	v_exp_f32_e32 v133, v133
	s_nop 0
	v_pk_mul_f32 v[128:129], v[132:133], v[128:129]
	s_nop 0
	v_pk_mul_f32 v[132:133], v[130:131], v[128:129]
	v_pk_fma_f32 v[128:129], v[130:131], v[128:129], v[130:131] neg_lo:[1,0,0] neg_hi:[1,0,0]
	s_nop 0
	v_cndmask_b32_e32 v132, v128, v132, vcc
	v_mul_f32_e32 v128, v143, v143
	v_fmac_f32_e32 v128, v142, v142
	v_fmac_f32_e32 v128, v140, v140
	v_fmac_f32_e32 v128, v141, v141
	v_fmac_f32_e32 v128, v138, v138
	v_cmp_gt_f32_e32 vcc, 0, v131
	v_fmac_f32_e32 v128, v139, v139
	v_fmac_f32_e32 v128, v132, v132
	v_cndmask_b32_e32 v131, v129, v133, vcc
	v_fmac_f32_e32 v128, v131, v131
	v_add_f32_e32 v134, v176, v128
	v_cvt_pk_bf16_f32 v128, v142, v143
	v_cvt_pk_bf16_f32 v129, v140, v141
	v_cvt_pk_bf16_f32 v130, v138, v139
	v_cvt_pk_bf16_f32 v131, v132, v131
	global_store_dwordx4 v[166:167], v[128:131], off offset:256
	s_nop 1
	v_and_b32_e32 v129, 64, v190
	v_xor_b32_e32 v128, 16, v190
	v_add_u32_e32 v129, 64, v129
	v_cmp_lt_i32_e32 vcc, v128, v129
	v_xor_b32_e32 v130, 32, v190
	s_nop 0
	v_cndmask_b32_e32 v128, v190, v128, vcc
	v_lshlrev_b32_e32 v133, 2, v128
	ds_bpermute_b32 v128, v133, v134
	v_cmp_lt_i32_e32 vcc, v130, v129
	s_waitcnt lgkmcnt(0)
	v_add_f32_e32 v128, v134, v128
	v_cndmask_b32_e32 v129, v190, v130, vcc
	v_lshlrev_b32_e32 v134, 2, v129
	ds_bpermute_b32 v129, v134, v128
	s_and_saveexec_b64 s[30:31], s[28:29]
	s_cbranch_execz .LBB0_867
	s_waitcnt lgkmcnt(0)
	v_add_f32_e32 v128, v128, v129
	v_cvt_f64_f32_e32 v[128:129], v128
	v_ldexp_f64 v[128:129], v[128:129], 32
	v_trunc_f64_e32 v[128:129], v[128:129]
	v_ldexp_f64 v[136:137], v[128:129], s93
	v_floor_f64_e32 v[136:137], v[136:137]
	v_fmac_f64_e32 v[128:129], 0xc1f00000, v[136:137]
	v_lshl_add_u64 v[130:131], v[156:157], 3, s[18:19]
	v_cvt_u32_f64_e32 v128, v[128:129]
	v_cvt_u32_f64_e32 v129, v[136:137]
	global_atomic_add_x2 v[130:131], v[128:129], off

; template <class Epi>
; __device__ __forceinline__ void gemm_phase(const int TID, const int BID, LAS unsigned char* lds, const Gemm g, const StaticOrder& S, const Epi& E) {
;     ...
;         const char* nA = has_next ? (const char*)g.A + (size_t)nxt.pm * tstepA : cA; const char* nB = has_next ? (const char*)g.Bt + (size_t)nxt.pn * tstepB : cB;
;         for (int t = 0; t < nt; t += 2) {
;             const bool last = (t == nt - 2);
;             const char* a1 = cA + (size_t)(t + 1) * kstep;
;             const char* a2 = last ? nA : cA + (size_t)(t + 2) * kstep; const char* b2 = last ? nB : cB + (size_t)(t + 2) * kstep;
;             const char* a3 = a2 + kstep; const char* b3 = b2 + kstep;
;     ...
; #pragma unroll
;         for (int a = 0; a < 2; ++a)
; #pragma unroll
;             for (int b = 0; b < 2; ++b)
; #pragma unroll
;                 for (int m = 0; m < 4; ++m)
; #pragma unroll
;                     for (int n = 0; n < 2; ++n) acc[a][b][m][n] = (f32x4){0.f, 0.f, 0.f, 0.f};
;         cur = nxt; cA = nA; cB = nB; ++ui;
.LBB0_924:
	s_ashr_i32 s19, s18, 31
	v_mov_b64_e32 v[0:1], 0x400
	s_lshl_b64 s[22:23], s[18:19], 20
	v_cmp_lt_i64_e32 vcc, s[26:27], v[0:1]
	s_add_u32 s26, s84, s22
	s_addc_u32 s27, s85, s23
	s_and_b64 s[22:23], vcc, exec
	s_cselect_b32 s1, s27, s35
	s_cselect_b32 s4, s26, s34
	s_ashr_i32 s17, s16, 31
	s_lshl_b64 s[22:23], s[16:17], 20
	s_add_u32 s28, s44, s22
	s_addc_u32 s29, s45, s23
	s_and_b64 s[22:23], vcc, exec
	s_cselect_b32 s17, s29, s37
	s_cselect_b32 s19, s28, s36
	s_add_u32 s34, s34, 0x80080
	s_addc_u32 s35, s35, 0
	s_add_u32 s22, s36, 0x100
	v_mov_b32_e32 v0, 0
	s_addc_u32 s23, s37, 0
	s_mov_b32 s64, -2
	v_mov_b32_e32 v1, v0
	v_mov_b32_e32 v2, v0
	v_mov_b32_e32 v3, v0
	v_mov_b32_e32 v4, v0
	v_mov_b32_e32 v5, v0
	v_mov_b32_e32 v6, v0
	v_mov_b32_e32 v7, v0
	v_mov_b32_e32 v16, v0
	v_mov_b32_e32 v17, v0
	v_mov_b32_e32 v18, v0
	v_mov_b32_e32 v19, v0
	v_mov_b32_e32 v20, v0
	v_mov_b32_e32 v21, v0
	v_mov_b32_e32 v22, v0
	v_mov_b32_e32 v23, v0
	v_mov_b32_e32 v32, v0
	v_mov_b32_e32 v33, v0
	v_mov_b32_e32 v34, v0
	v_mov_b32_e32 v35, v0
	v_mov_b32_e32 v36, v0
	v_mov_b32_e32 v37, v0
	v_mov_b32_e32 v38, v0
	v_mov_b32_e32 v39, v0
	v_mov_b32_e32 v48, v0
	v_mov_b32_e32 v49, v0
	v_mov_b32_e32 v50, v0
	v_mov_b32_e32 v51, v0
	v_mov_b32_e32 v52, v0
	v_mov_b32_e32 v53, v0
	v_mov_b32_e32 v54, v0
	v_mov_b32_e32 v55, v0
	v_mov_b32_e32 v8, v0
	v_mov_b32_e32 v9, v0
	v_mov_b32_e32 v10, v0
	v_mov_b32_e32 v11, v0
	v_mov_b32_e32 v12, v0
	v_mov_b32_e32 v13, v0
	v_mov_b32_e32 v14, v0
	v_mov_b32_e32 v15, v0
	v_mov_b32_e32 v24, v0
	v_mov_b32_e32 v25, v0
	v_mov_b32_e32 v26, v0
	v_mov_b32_e32 v27, v0
	v_mov_b32_e32 v28, v0
	v_mov_b32_e32 v29, v0
	v_mov_b32_e32 v30, v0
	v_mov_b32_e32 v31, v0
	v_mov_b32_e32 v40, v0
	v_mov_b32_e32 v41, v0
	v_mov_b32_e32 v42, v0
	v_mov_b32_e32 v43, v0
	v_mov_b32_e32 v44, v0
	v_mov_b32_e32 v45, v0
	v_mov_b32_e32 v46, v0
	v_mov_b32_e32 v47, v0
	v_mov_b32_e32 v56, v0
	v_mov_b32_e32 v57, v0
	v_mov_b32_e32 v58, v0
	v_mov_b32_e32 v59, v0
	v_mov_b32_e32 v60, v0
	v_mov_b32_e32 v61, v0
	v_mov_b32_e32 v62, v0
	v_mov_b32_e32 v63, v0
	v_mov_b32_e32 v64, v0
	v_mov_b32_e32 v65, v0
	v_mov_b32_e32 v66, v0
	v_mov_b32_e32 v67, v0
	v_mov_b32_e32 v68, v0
	v_mov_b32_e32 v69, v0
	v_mov_b32_e32 v70, v0
	v_mov_b32_e32 v71, v0
	v_mov_b32_e32 v80, v0
	v_mov_b32_e32 v81, v0
	v_mov_b32_e32 v82, v0
	v_mov_b32_e32 v83, v0
	v_mov_b32_e32 v84, v0
	v_mov_b32_e32 v85, v0
	v_mov_b32_e32 v86, v0
	v_mov_b32_e32 v87, v0
	v_mov_b32_e32 v96, v0
	v_mov_b32_e32 v97, v0
	v_mov_b32_e32 v98, v0
	v_mov_b32_e32 v99, v0
	v_mov_b32_e32 v100, v0
	v_mov_b32_e32 v101, v0
	v_mov_b32_e32 v102, v0
	v_mov_b32_e32 v103, v0
	v_mov_b32_e32 v112, v0
	v_mov_b32_e32 v113, v0
	v_mov_b32_e32 v114, v0
	v_mov_b32_e32 v115, v0
	v_mov_b32_e32 v116, v0
	v_mov_b32_e32 v117, v0
	v_mov_b32_e32 v118, v0
	v_mov_b32_e32 v119, v0
	v_mov_b32_e32 v72, v0
	v_mov_b32_e32 v73, v0
	v_mov_b32_e32 v74, v0
	v_mov_b32_e32 v75, v0
	v_mov_b32_e32 v76, v0
	v_mov_b32_e32 v77, v0
	v_mov_b32_e32 v78, v0
	v_mov_b32_e32 v79, v0
	v_mov_b32_e32 v88, v0
	v_mov_b32_e32 v89, v0
	v_mov_b32_e32 v90, v0
	v_mov_b32_e32 v91, v0
	v_mov_b32_e32 v92, v0
	v_mov_b32_e32 v93, v0
	v_mov_b32_e32 v94, v0
	v_mov_b32_e32 v95, v0
	v_mov_b32_e32 v104, v0
	v_mov_b32_e32 v105, v0
	v_mov_b32_e32 v106, v0
	v_mov_b32_e32 v107, v0
	v_mov_b32_e32 v108, v0
	v_mov_b32_e32 v109, v0
	v_mov_b32_e32 v110, v0
	v_mov_b32_e32 v111, v0
	v_mov_b32_e32 v120, v0
	v_mov_b32_e32 v121, v0
	v_mov_b32_e32 v122, v0
	v_mov_b32_e32 v123, v0
	v_mov_b32_e32 v124, v0
	v_mov_b32_e32 v125, v0
	v_mov_b32_e32 v126, v0
	v_mov_b32_e32 v127, v0
	s_add_u32 s36, s34, 0xfff80080
	s_addc_u32 s37, s35, -1
	s_cmp_eq_u32 s64, 28
	s_cselect_b32 s39, s1, s37
	s_cselect_b32 s38, s4, s36
	s_cselect_b32 s37, s17, s23
	s_cselect_b32 s36, s19, s22
	s_branch .LBB0_925

; #define PG8_STAGE(bufoff, gbase, voff) do { _Pragma("unroll") for (int _i = 0; _i < 2; ++_i) \
;         __builtin_amdgcn_global_load_lds((const unsigned*)((const char*)(gbase) + (voff)[_i]), (LAS unsigned*)(lds + (bufoff) + ldsw + _i * 8192), 16, 0, 0); } while (0)
; #define PG8_LDA(dst, b, h) do { _Pragma("unroll") for (int m = 0; m < 4; ++m) _Pragma("unroll") for (int k = 0; k < 2; ++k) dst[m][k] = *(const LAS bf16x8*)(lds + PG8_SA(b, h) + aoff + m * 2048 + k * 1024); } while (0)
; #define PG8_LDB(dst, b, h) do { _Pragma("unroll") for (int n = 0; n < 2; ++n) _Pragma("unroll") for (int k = 0; k < 2; ++k) dst[n][k] = *(const LAS bf16x8*)(lds + PG8_SB(b, h) + boff + n * 2048 + k * 1024); } while (0)
; #define PG8_MMA(ai, bj, At, Bt) do { __builtin_amdgcn_s_setprio(1); _Pragma("unroll") for (int m = 0; m < 4; ++m) _Pragma("unroll") for (int n = 0; n < 2; ++n) _Pragma("unroll") for (int k = 0; k < 2; ++k) \
;         acc[ai][bj][m][n] = __builtin_amdgcn_mfma_f32_16x16x32_bf16(Bt[n][k], At[m][k], acc[ai][bj][m][n], 0, 0, 0); __builtin_amdgcn_s_setprio(0); } while (0)
; #define PG8_WAIT_V(n) asm volatile("s_waitcnt vmcnt(" #n ")" ::: "memory")
; #define PG8_WAIT_L(n) asm volatile("s_waitcnt lgkmcnt(" #n ")" ::: "memory")
; template <class Epi>
; __device__ __forceinline__ void gemm_phase(const int TID, const int BID, LAS unsigned char* lds, const Gemm g, const StaticOrder& S, const Epi& E) {
;     ...
;         for (int t = 0; t < nt; t += 2) {
;             const bool last = (t == nt - 2);
;             const char* a1 = cA + (size_t)(t + 1) * kstep;
;             const char* a2 = last ? nA : cA + (size_t)(t + 2) * kstep; const char* b2 = last ? nB : cB + (size_t)(t + 2) * kstep;
;             const char* a3 = a2 + kstep; const char* b3 = b2 + kstep;
;             PG8_LDB(B0, 0, 0); PG8_SCHED; PG8_LDA(At, 0, 0); PG8_STAGE(PG8_SA(1, 1), a1 + hstepA, voffA);
;             PG8_WAIT_L(8); PG8_BAR; PG8_WAIT_L(0); PG8_MMA(0, 0, At, B0); PG8_BAR; PG8_SCHED;
;             PG8_LDB(B1, 0, 1); PG8_STAGE(PG8_SB(0, 0), b2, voffB);
;             PG8_BAR; PG8_WAIT_L(0); PG8_MMA(0, 1, At, B1); PG8_BAR;
;             PG8_LDA(At, 0, 1); PG8_STAGE(PG8_SA(0, 0), a2, voffA);
;             PG8_BAR; PG8_WAIT_L(0); PG8_MMA(1, 0, At, B0); PG8_BAR; PG8_SCHED;
;             PG8_STAGE(PG8_SB(0, 1), b2 + hstepB, voffB);
;             PG8_WAIT_V(6); PG8_BAR; PG8_MMA(1, 1, At, B1); PG8_BAR;
.LBB0_925:
	v_add_u32_e32 v154, s31, v147
	ds_read_b128 v[138:141], v154
	ds_read_b128 v[142:145], v154 offset:1024
	ds_read_b128 v[150:153], v154 offset:2048
	ds_read_b128 v[154:157], v154 offset:3072
	v_lshl_add_u64 v[158:159], s[34:35], 0, v[134:135]
	s_add_i32 m0, s48, 0xc000
	ds_read_b128 v[166:169], v149
	ds_read_b128 v[170:173], v149 offset:1024
	ds_read_b128 v[174:177], v149 offset:2048
	ds_read_b128 v[178:181], v149 offset:3072
	ds_read_b128 v[182:185], v149 offset:4096
	ds_read_b128 v[196:199], v149 offset:5120
	ds_read_b128 v[208:211], v149 offset:6144
	ds_read_b128 v[212:215], v149 offset:7168
	global_load_lds_dwordx4 v[158:159], off
	s_add_i32 m0, s48, 0xe000
	v_lshl_add_u64 v[158:159], s[34:35], 0, v[136:137]
	global_load_lds_dwordx4 v[158:159], off
	s_waitcnt lgkmcnt(8)
	s_barrier
	s_waitcnt lgkmcnt(0)
	s_setprio 1
	v_mfma_f32_16x16x32_bf16 v[124:127], v[138:141], v[166:169], v[124:127]
	v_mfma_f32_16x16x32_bf16 v[120:123], v[150:153], v[166:169], v[120:123]
	v_mfma_f32_16x16x32_bf16 v[108:111], v[138:141], v[174:177], v[108:111]
	v_mfma_f32_16x16x32_bf16 v[104:107], v[150:153], v[174:177], v[104:107]
	v_mfma_f32_16x16x32_bf16 v[92:95], v[138:141], v[182:185], v[92:95]
	v_mfma_f32_16x16x32_bf16 v[88:91], v[150:153], v[182:185], v[88:91]
	v_mfma_f32_16x16x32_bf16 v[76:79], v[138:141], v[208:211], v[76:79]
	v_mfma_f32_16x16x32_bf16 v[72:75], v[150:153], v[208:211], v[72:75]
	v_mfma_f32_16x16x32_bf16 v[124:127], v[142:145], v[170:173], v[124:127]
	v_mfma_f32_16x16x32_bf16 v[120:123], v[154:157], v[170:173], v[120:123]
	v_mfma_f32_16x16x32_bf16 v[108:111], v[142:145], v[178:181], v[108:111]
	v_mfma_f32_16x16x32_bf16 v[104:107], v[154:157], v[178:181], v[104:107]
	v_mfma_f32_16x16x32_bf16 v[92:95], v[142:145], v[196:199], v[92:95]
	v_mfma_f32_16x16x32_bf16 v[88:91], v[154:157], v[196:199], v[88:91]
	v_mfma_f32_16x16x32_bf16 v[76:79], v[142:145], v[212:215], v[76:79]
	v_mfma_f32_16x16x32_bf16 v[72:75], v[154:157], v[212:215], v[72:75]
	s_setprio 0
	s_barrier
	v_add_u32_e32 v158, s50, v147
	s_mov_b32 m0, s46
	ds_read_b128 v[216:219], v158
	ds_read_b128 v[220:223], v158 offset:1024
	ds_read_b128 v[224:227], v158 offset:2048
	ds_read_b128 v[228:231], v158 offset:3072
	v_lshl_add_u64 v[158:159], s[36:37], 0, v[160:161]
	global_load_lds_dwordx4 v[158:159], off
	s_mov_b32 m0, s47
	v_lshl_add_u64 v[200:201], s[36:37], 0, v[132:133]
	global_load_lds_dwordx4 v[200:201], off
	s_barrier
	s_waitcnt lgkmcnt(0)
	s_setprio 1
	v_mfma_f32_16x16x32_bf16 v[116:119], v[216:219], v[166:169], v[116:119]
	v_mfma_f32_16x16x32_bf16 v[112:115], v[224:227], v[166:169], v[112:115]
	v_mfma_f32_16x16x32_bf16 v[100:103], v[216:219], v[174:177], v[100:103]
	v_mfma_f32_16x16x32_bf16 v[96:99], v[224:227], v[174:177], v[96:99]
	v_mfma_f32_16x16x32_bf16 v[84:87], v[216:219], v[182:185], v[84:87]
	v_mfma_f32_16x16x32_bf16 v[80:83], v[224:227], v[182:185], v[80:83]
	v_mfma_f32_16x16x32_bf16 v[68:71], v[216:219], v[208:211], v[68:71]
	v_mfma_f32_16x16x32_bf16 v[64:67], v[224:227], v[208:211], v[64:67]
	v_mfma_f32_16x16x32_bf16 v[116:119], v[220:223], v[170:173], v[116:119]
	v_mfma_f32_16x16x32_bf16 v[112:115], v[228:231], v[170:173], v[112:115]
	v_mfma_f32_16x16x32_bf16 v[100:103], v[220:223], v[178:181], v[100:103]
	v_mfma_f32_16x16x32_bf16 v[96:99], v[228:231], v[178:181], v[96:99]
	v_mfma_f32_16x16x32_bf16 v[84:87], v[220:223], v[196:199], v[84:87]
	v_mfma_f32_16x16x32_bf16 v[80:83], v[228:231], v[196:199], v[80:83]
	v_mfma_f32_16x16x32_bf16 v[68:71], v[220:223], v[212:215], v[68:71]
	v_mfma_f32_16x16x32_bf16 v[64:67], v[228:231], v[212:215], v[64:67]
	s_setprio 0
	s_mov_b32 m0, s48
	v_lshl_add_u64 v[232:233], s[38:39], 0, v[128:129]
	s_barrier
	ds_read_b128 v[166:169], v149 offset:16384
	ds_read_b128 v[170:173], v149 offset:17408
	ds_read_b128 v[174:177], v149 offset:18432
	ds_read_b128 v[178:181], v149 offset:19456
	ds_read_b128 v[182:185], v149 offset:20480
	ds_read_b128 v[196:199], v149 offset:21504
	ds_read_b128 v[208:211], v149 offset:22528
	ds_read_b128 v[212:215], v149 offset:23552
	global_load_lds_dwordx4 v[232:233], off
	s_mov_b32 m0, s49
	v_lshl_add_u64 v[234:235], s[38:39], 0, v[130:131]
	global_load_lds_dwordx4 v[234:235], off
	s_barrier
	s_waitcnt lgkmcnt(0)
	s_setprio 1
	v_mfma_f32_16x16x32_bf16 v[60:63], v[138:141], v[166:169], v[60:63]
	v_mfma_f32_16x16x32_bf16 v[56:59], v[150:153], v[166:169], v[56:59]
	v_mfma_f32_16x16x32_bf16 v[44:47], v[138:141], v[174:177], v[44:47]
	v_mfma_f32_16x16x32_bf16 v[40:43], v[150:153], v[174:177], v[40:43]
	v_mfma_f32_16x16x32_bf16 v[28:31], v[138:141], v[182:185], v[28:31]
	v_mfma_f32_16x16x32_bf16 v[24:27], v[150:153], v[182:185], v[24:27]
	v_mfma_f32_16x16x32_bf16 v[12:15], v[138:141], v[208:211], v[12:15]
	v_mfma_f32_16x16x32_bf16 v[8:11], v[150:153], v[208:211], v[8:11]
	v_mfma_f32_16x16x32_bf16 v[60:63], v[142:145], v[170:173], v[60:63]
	v_mfma_f32_16x16x32_bf16 v[56:59], v[154:157], v[170:173], v[56:59]
	v_mfma_f32_16x16x32_bf16 v[44:47], v[142:145], v[178:181], v[44:47]
	v_mfma_f32_16x16x32_bf16 v[40:43], v[154:157], v[178:181], v[40:43]
	v_mfma_f32_16x16x32_bf16 v[28:31], v[142:145], v[196:199], v[28:31]
	v_mfma_f32_16x16x32_bf16 v[24:27], v[154:157], v[196:199], v[24:27]
	v_mfma_f32_16x16x32_bf16 v[12:15], v[142:145], v[212:215], v[12:15]
	v_mfma_f32_16x16x32_bf16 v[8:11], v[154:157], v[212:215], v[8:11]
	s_setprio 0
	s_barrier
	s_add_u32 s66, s36, 0x80000
	s_addc_u32 s67, s37, 0
	s_mov_b32 m0, s51
	v_lshl_add_u64 v[138:139], s[66:67], 0, v[160:161]
	global_load_lds_dwordx4 v[138:139], off
	s_mov_b32 m0, s52
	v_lshl_add_u64 v[138:139], s[66:67], 0, v[132:133]
	global_load_lds_dwordx4 v[138:139], off
	s_waitcnt vmcnt(6)
	s_barrier
; #define PG8_STAGE(bufoff, gbase, voff) do { _Pragma("unroll") for (int _i = 0; _i < 2; ++_i) \
;         __builtin_amdgcn_global_load_lds((const unsigned*)((const char*)(gbase) + (voff)[_i]), (LAS unsigned*)(lds + (bufoff) + ldsw + _i * 8192), 16, 0, 0); } while (0)
; #define PG8_LDA(dst, b, h) do { _Pragma("unroll") for (int m = 0; m < 4; ++m) _Pragma("unroll") for (int k = 0; k < 2; ++k) dst[m][k] = *(const LAS bf16x8*)(lds + PG8_SA(b, h) + aoff + m * 2048 + k * 1024); } while (0)
; #define PG8_LDB(dst, b, h) do { _Pragma("unroll") for (int n = 0; n < 2; ++n) _Pragma("unroll") for (int k = 0; k < 2; ++k) dst[n][k] = *(const LAS bf16x8*)(lds + PG8_SB(b, h) + boff + n * 2048 + k * 1024); } while (0)
; #define PG8_MMA(ai, bj, At, Bt) do { __builtin_amdgcn_s_setprio(1); _Pragma("unroll") for (int m = 0; m < 4; ++m) _Pragma("unroll") for (int n = 0; n < 2; ++n) _Pragma("unroll") for (int k = 0; k < 2; ++k) \
;         acc[ai][bj][m][n] = __builtin_amdgcn_mfma_f32_16x16x32_bf16(Bt[n][k], At[m][k], acc[ai][bj][m][n], 0, 0, 0); __builtin_amdgcn_s_setprio(0); } while (0)
; #define PG8_WAIT_V(n) asm volatile("s_waitcnt vmcnt(" #n ")" ::: "memory")
; #define PG8_WAIT_L(n) asm volatile("s_waitcnt lgkmcnt(" #n ")" ::: "memory")
; #define PG8_BAR __builtin_amdgcn_s_barrier()
; #define PG8_SCHED __builtin_amdgcn_sched_barrier(0)
; template <class Epi>
; __device__ __forceinline__ void gemm_phase(const int TID, const int BID, LAS unsigned char* lds, const Gemm g, const StaticOrder& S, const Epi& E) {
;     ...
;             PG8_WAIT_V(6); PG8_BAR; PG8_MMA(1, 1, At, B1); PG8_BAR;
;             PG8_LDB(B0, 1, 0); PG8_SCHED; PG8_LDA(At, 1, 0); PG8_STAGE(PG8_SA(0, 1), a2 + hstepA, voffA);
;             PG8_WAIT_L(8); PG8_BAR; PG8_WAIT_L(0); PG8_MMA(0, 0, At, B0); PG8_BAR; PG8_SCHED;
;             PG8_LDB(B1, 1, 1); PG8_STAGE(PG8_SB(1, 0), b3, voffB);
;             PG8_BAR; PG8_WAIT_L(0); PG8_MMA(0, 1, At, B1); PG8_BAR;
;             PG8_LDA(At, 1, 1); PG8_STAGE(PG8_SA(1, 0), a3, voffA);
;             PG8_BAR; PG8_WAIT_L(0); PG8_MMA(1, 0, At, B0); PG8_BAR; PG8_SCHED;
;             PG8_STAGE(PG8_SB(1, 1), b3 + hstepB, voffB);
;             PG8_WAIT_V(6); PG8_BAR; PG8_MMA(1, 1, At, B1); PG8_BAR;
	s_setprio 1
	v_mfma_f32_16x16x32_bf16 v[52:55], v[216:219], v[166:169], v[52:55]
	v_mfma_f32_16x16x32_bf16 v[48:51], v[224:227], v[166:169], v[48:51]
	v_mfma_f32_16x16x32_bf16 v[36:39], v[216:219], v[174:177], v[36:39]
	v_mfma_f32_16x16x32_bf16 v[32:35], v[224:227], v[174:177], v[32:35]
	v_mfma_f32_16x16x32_bf16 v[20:23], v[216:219], v[182:185], v[20:23]
	v_mfma_f32_16x16x32_bf16 v[16:19], v[224:227], v[182:185], v[16:19]
	v_mfma_f32_16x16x32_bf16 v[4:7], v[216:219], v[208:211], v[4:7]
	v_mfma_f32_16x16x32_bf16 v[0:3], v[224:227], v[208:211], v[0:3]
	v_mfma_f32_16x16x32_bf16 v[52:55], v[220:223], v[170:173], v[52:55]
	v_mfma_f32_16x16x32_bf16 v[48:51], v[228:231], v[170:173], v[48:51]
	v_mfma_f32_16x16x32_bf16 v[36:39], v[220:223], v[178:181], v[36:39]
	v_mfma_f32_16x16x32_bf16 v[32:35], v[228:231], v[178:181], v[32:35]
	v_mfma_f32_16x16x32_bf16 v[20:23], v[220:223], v[196:199], v[20:23]
	v_mfma_f32_16x16x32_bf16 v[16:19], v[228:231], v[196:199], v[16:19]
	v_mfma_f32_16x16x32_bf16 v[4:7], v[220:223], v[212:215], v[4:7]
	v_mfma_f32_16x16x32_bf16 v[0:3], v[228:231], v[212:215], v[0:3]
	s_setprio 0
	v_add_u32_e32 v154, s55, v147
	s_barrier
	ds_read_b128 v[138:141], v154
	ds_read_b128 v[142:145], v154 offset:1024
	ds_read_b128 v[150:153], v154 offset:2048
	ds_read_b128 v[154:157], v154 offset:3072
	s_add_u32 s38, s38, 0x80000
	s_addc_u32 s39, s39, 0
	s_mov_b32 m0, s53
	v_lshl_add_u64 v[216:217], s[38:39], 0, v[128:129]
	ds_read_b128 v[166:169], v149 offset:32768
	ds_read_b128 v[170:173], v149 offset:33792
	ds_read_b128 v[174:177], v149 offset:34816
	ds_read_b128 v[178:181], v149 offset:35840
	ds_read_b128 v[182:185], v149 offset:36864
	ds_read_b128 v[196:199], v149 offset:37888
	ds_read_b128 v[208:211], v149 offset:38912
	ds_read_b128 v[212:215], v149 offset:39936
	global_load_lds_dwordx4 v[216:217], off
	s_mov_b32 m0, s54
	v_lshl_add_u64 v[216:217], s[38:39], 0, v[130:131]
	global_load_lds_dwordx4 v[216:217], off
	s_waitcnt lgkmcnt(8)
	s_barrier
	s_waitcnt lgkmcnt(0)
	s_setprio 1
	v_mfma_f32_16x16x32_bf16 v[124:127], v[138:141], v[166:169], v[124:127]
	v_mfma_f32_16x16x32_bf16 v[120:123], v[150:153], v[166:169], v[120:123]
	v_mfma_f32_16x16x32_bf16 v[108:111], v[138:141], v[174:177], v[108:111]
	v_mfma_f32_16x16x32_bf16 v[104:107], v[150:153], v[174:177], v[104:107]
	v_mfma_f32_16x16x32_bf16 v[92:95], v[138:141], v[182:185], v[92:95]
	v_mfma_f32_16x16x32_bf16 v[88:91], v[150:153], v[182:185], v[88:91]
	v_mfma_f32_16x16x32_bf16 v[76:79], v[138:141], v[208:211], v[76:79]
	v_mfma_f32_16x16x32_bf16 v[72:75], v[150:153], v[208:211], v[72:75]
	v_mfma_f32_16x16x32_bf16 v[124:127], v[142:145], v[170:173], v[124:127]
	v_mfma_f32_16x16x32_bf16 v[120:123], v[154:157], v[170:173], v[120:123]
	v_mfma_f32_16x16x32_bf16 v[108:111], v[142:145], v[178:181], v[108:111]
	v_mfma_f32_16x16x32_bf16 v[104:107], v[154:157], v[178:181], v[104:107]
	v_mfma_f32_16x16x32_bf16 v[92:95], v[142:145], v[196:199], v[92:95]
	v_mfma_f32_16x16x32_bf16 v[88:91], v[154:157], v[196:199], v[88:91]
	v_mfma_f32_16x16x32_bf16 v[76:79], v[142:145], v[212:215], v[76:79]
	v_mfma_f32_16x16x32_bf16 v[72:75], v[154:157], v[212:215], v[72:75]
	s_setprio 0
	s_barrier
	s_mov_b32 m0, s56
	v_add_u32_e32 v228, s60, v147
	v_lshl_add_u64 v[158:159], v[158:159], 0, s[90:91]
	ds_read_b128 v[216:219], v228
	ds_read_b128 v[220:223], v228 offset:1024
	ds_read_b128 v[224:227], v228 offset:2048
	ds_read_b128 v[228:231], v228 offset:3072
	global_load_lds_dwordx4 v[158:159], off
	s_mov_b32 m0, s57
	v_lshl_add_u64 v[158:159], v[200:201], 0, s[90:91]
	global_load_lds_dwordx4 v[158:159], off
	s_barrier
	s_waitcnt lgkmcnt(0)
	s_setprio 1
	v_mfma_f32_16x16x32_bf16 v[116:119], v[216:219], v[166:169], v[116:119]
	v_mfma_f32_16x16x32_bf16 v[112:115], v[224:227], v[166:169], v[112:115]
	v_mfma_f32_16x16x32_bf16 v[100:103], v[216:219], v[174:177], v[100:103]
	v_mfma_f32_16x16x32_bf16 v[96:99], v[224:227], v[174:177], v[96:99]
	v_mfma_f32_16x16x32_bf16 v[84:87], v[216:219], v[182:185], v[84:87]
	v_mfma_f32_16x16x32_bf16 v[80:83], v[224:227], v[182:185], v[80:83]
	v_mfma_f32_16x16x32_bf16 v[68:71], v[216:219], v[208:211], v[68:71]
	v_mfma_f32_16x16x32_bf16 v[64:67], v[224:227], v[208:211], v[64:67]
	v_mfma_f32_16x16x32_bf16 v[116:119], v[220:223], v[170:173], v[116:119]
	v_mfma_f32_16x16x32_bf16 v[112:115], v[228:231], v[170:173], v[112:115]
	v_mfma_f32_16x16x32_bf16 v[100:103], v[220:223], v[178:181], v[100:103]
	v_mfma_f32_16x16x32_bf16 v[96:99], v[228:231], v[178:181], v[96:99]
	v_mfma_f32_16x16x32_bf16 v[84:87], v[220:223], v[196:199], v[84:87]
	v_mfma_f32_16x16x32_bf16 v[80:83], v[228:231], v[196:199], v[80:83]
	v_mfma_f32_16x16x32_bf16 v[68:71], v[220:223], v[212:215], v[68:71]
	v_mfma_f32_16x16x32_bf16 v[64:67], v[228:231], v[212:215], v[64:67]
	s_setprio 0
	s_mov_b32 m0, s58
	v_lshl_add_u64 v[158:159], v[232:233], 0, s[90:91]
	s_barrier
	ds_read_b128 v[166:169], v149 offset:49152
	ds_read_b128 v[170:173], v149 offset:50176
	ds_read_b128 v[174:177], v149 offset:51200
	ds_read_b128 v[178:181], v149 offset:52224
	ds_read_b128 v[182:185], v149 offset:53248
	ds_read_b128 v[196:199], v149 offset:54272
	ds_read_b128 v[208:211], v149 offset:55296
	ds_read_b128 v[212:215], v149 offset:56320
	global_load_lds_dwordx4 v[158:159], off
	s_mov_b32 m0, s59
	v_lshl_add_u64 v[158:159], v[234:235], 0, s[90:91]
	global_load_lds_dwordx4 v[158:159], off
	s_barrier
; __device__ __forceinline__ unsigned cvt_pk_bf16(float lo, float hi) { unsigned r; asm volatile("v_cvt_pk_bf16_f32 %0, %1, %2" : "=v"(r) : "v"(lo), "v"(hi)); return r; }
; __device__ __forceinline__ float rinv_st(stat_t s, float invn) { return rsqrtf((float)((double)s * (1.0 / 4294967296.0)) * invn + 1e-6f); }
; #define PG8_STAGE(bufoff, gbase, voff) do { _Pragma("unroll") for (int _i = 0; _i < 2; ++_i) \
;         __builtin_amdgcn_global_load_lds((const unsigned*)((const char*)(gbase) + (voff)[_i]), (LAS unsigned*)(lds + (bufoff) + ldsw + _i * 8192), 16, 0, 0); } while (0)
; #define PG8_WAIT_V(n) asm volatile("s_waitcnt vmcnt(" #n ")" ::: "memory")
; template <class Epi>
; __device__ __forceinline__ void gemm_phase(const int TID, const int BID, LAS unsigned char* lds, const Gemm g, const StaticOrder& S, const Epi& E) {
;     ...
;             PG8_WAIT_L(8); PG8_BAR; PG8_WAIT_L(0); PG8_MMA(0, 0, At, B0); PG8_BAR; PG8_SCHED;
;             PG8_LDB(B1, 1, 1); PG8_STAGE(PG8_SB(1, 0), b3, voffB);
;             PG8_BAR; PG8_WAIT_L(0); PG8_MMA(0, 1, At, B1); PG8_BAR;
;             PG8_LDA(At, 1, 1); PG8_STAGE(PG8_SA(1, 0), a3, voffA);
;             PG8_BAR; PG8_WAIT_L(0); PG8_MMA(1, 0, At, B0); PG8_BAR; PG8_SCHED;
;             PG8_STAGE(PG8_SB(1, 1), b3 + hstepB, voffB);
;             PG8_WAIT_V(6); PG8_BAR; PG8_MMA(1, 1, At, B1); PG8_BAR;
;     __device__ __forceinline__ void operator()(const f32x4 (&acc)[2][2][4][2], const Unit& u, int wr, int wc, int fr, int fq) const {
;         const int row0 = u.pm * BM + wr * 64 + fr, col0 = u.pn * BM + wc * 32 + 8 * fq;
; #pragma unroll
;         for (int ai = 0; ai < 2; ++ai)
; #pragma unroll
;             for (int m = 0; m < 4; ++m) {
;                 const int row = row0 + ai * HALF + m * 16; const float r = rinv_st(stats[row], 1.0f / 2048.0f);
;                 bf16_t* rowp = U + (size_t)row * FF + col0;
; #pragma unroll
;                 for (int bj = 0; bj < 2; ++bj) {
;                     f32x4 v0 = acc[ai][bj][m][0] * r, v1 = acc[ai][bj][m][1] * r;
; #pragma unroll
;                     for (int j = 0; j < 4; ++j) { const float a = fmaxf(v0[j], 0.f), b = fmaxf(v1[j], 0.f); v0[j] = a * a; v1[j] = b * b; }
;                     u32x4 w; w.x = cvt_pk_bf16(v0[0], v0[1]); w.y = cvt_pk_bf16(v0[2], v0[3]); w.z = cvt_pk_bf16(v1[0], v1[1]); w.w = cvt_pk_bf16(v1[2], v1[3]);
;                     *(u32x4*)(rowp + bj * HALF) = w;
	s_waitcnt lgkmcnt(0)
	s_setprio 1
	v_mfma_f32_16x16x32_bf16 v[60:63], v[138:141], v[166:169], v[60:63]
	v_mfma_f32_16x16x32_bf16 v[56:59], v[150:153], v[166:169], v[56:59]
	v_mfma_f32_16x16x32_bf16 v[44:47], v[138:141], v[174:177], v[44:47]
	v_mfma_f32_16x16x32_bf16 v[40:43], v[150:153], v[174:177], v[40:43]
	v_mfma_f32_16x16x32_bf16 v[28:31], v[138:141], v[182:185], v[28:31]
	v_mfma_f32_16x16x32_bf16 v[24:27], v[150:153], v[182:185], v[24:27]
	v_mfma_f32_16x16x32_bf16 v[12:15], v[138:141], v[208:211], v[12:15]
	v_mfma_f32_16x16x32_bf16 v[8:11], v[150:153], v[208:211], v[8:11]
	v_mfma_f32_16x16x32_bf16 v[60:63], v[142:145], v[170:173], v[60:63]
	v_mfma_f32_16x16x32_bf16 v[56:59], v[154:157], v[170:173], v[56:59]
	v_mfma_f32_16x16x32_bf16 v[44:47], v[142:145], v[178:181], v[44:47]
	v_mfma_f32_16x16x32_bf16 v[40:43], v[154:157], v[178:181], v[40:43]
	v_mfma_f32_16x16x32_bf16 v[28:31], v[142:145], v[196:199], v[28:31]
	v_mfma_f32_16x16x32_bf16 v[24:27], v[154:157], v[196:199], v[24:27]
	v_mfma_f32_16x16x32_bf16 v[12:15], v[142:145], v[212:215], v[12:15]
	v_mfma_f32_16x16x32_bf16 v[8:11], v[154:157], v[212:215], v[8:11]
	s_setprio 0
	s_barrier
	s_add_u32 s36, s36, 0x80080
	s_addc_u32 s37, s37, 0
	s_mov_b32 m0, s61
	v_lshl_add_u64 v[138:139], s[36:37], 0, v[160:161]
	global_load_lds_dwordx4 v[138:139], off
	s_mov_b32 m0, s62
	v_lshl_add_u64 v[138:139], s[36:37], 0, v[132:133]
	global_load_lds_dwordx4 v[138:139], off
	s_waitcnt vmcnt(6)
	s_barrier
	s_setprio 1
	v_mfma_f32_16x16x32_bf16 v[52:55], v[216:219], v[166:169], v[52:55]
	v_mfma_f32_16x16x32_bf16 v[48:51], v[224:227], v[166:169], v[48:51]
	v_mfma_f32_16x16x32_bf16 v[36:39], v[216:219], v[174:177], v[36:39]
	v_mfma_f32_16x16x32_bf16 v[32:35], v[224:227], v[174:177], v[32:35]
	v_mfma_f32_16x16x32_bf16 v[20:23], v[216:219], v[182:185], v[20:23]
	v_mfma_f32_16x16x32_bf16 v[16:19], v[224:227], v[182:185], v[16:19]
	v_mfma_f32_16x16x32_bf16 v[4:7], v[216:219], v[208:211], v[4:7]
	v_mfma_f32_16x16x32_bf16 v[0:3], v[224:227], v[208:211], v[0:3]
	v_mfma_f32_16x16x32_bf16 v[52:55], v[220:223], v[170:173], v[52:55]
	v_mfma_f32_16x16x32_bf16 v[48:51], v[228:231], v[170:173], v[48:51]
	v_mfma_f32_16x16x32_bf16 v[36:39], v[220:223], v[178:181], v[36:39]
	v_mfma_f32_16x16x32_bf16 v[32:35], v[228:231], v[178:181], v[32:35]
	v_mfma_f32_16x16x32_bf16 v[20:23], v[220:223], v[196:199], v[20:23]
	v_mfma_f32_16x16x32_bf16 v[16:19], v[228:231], v[196:199], v[16:19]
	v_mfma_f32_16x16x32_bf16 v[4:7], v[220:223], v[212:215], v[4:7]
	v_mfma_f32_16x16x32_bf16 v[0:3], v[228:231], v[212:215], v[0:3]
	s_setprio 0
	s_add_i32 s64, s64, 2
	s_add_u32 s34, s34, 0x100
	s_addc_u32 s35, s35, 0
	s_add_u32 s22, s22, 0x100
	s_addc_u32 s23, s23, 0
	s_add_u32 s36, s34, 0xfff80080
	s_addc_u32 s37, s35, -1
	s_cmp_eq_u32 s64, 28
	s_cselect_b32 s39, s1, s37
	s_cselect_b32 s38, s4, s36
	s_cselect_b32 s37, s17, s23
	s_cselect_b32 s36, s19, s22
	s_cmp_gt_u32 s64, 29
	s_cbranch_scc0 .Lrot_925
	s_barrier
	v_lshl_add_u32 v142, s30, 8, v146
	v_ashrrev_i32_e32 v143, 31, v142
	v_lshl_add_u64 v[138:139], v[142:143], 3, s[10:11]
	v_lshl_or_b32 v140, s0, 8, v148
	v_ashrrev_i32_e32 v141, 31, v140
	s_mov_b64 s[0:1], 0x200000
	s_mov_b32 s30, s18
	s_mov_b64 s[36:37], s[28:29]
	s_mov_b64 s[34:35], s[26:27]
	v_mov_b64_e32 v[144:145], v[236:237]
	v_cvt_f64_u32_e32 v[150:151], v145
	v_ldexp_f64 v[150:151], v[150:151], 32
	v_cvt_f64_u32_e32 v[144:145], v144
	v_add_f64 v[144:145], v[150:151], v[144:145]
	v_ldexp_f64 v[144:145], v[144:145], s93
	v_cvt_f32_f64_e32 v144, v[144:145]
	v_fmamk_f32 v144, v144, 0x3a000000, v189
	v_cmp_gt_f32_e32 vcc, s78, v144
	v_mul_f32_e32 v145, 0x4b800000, v144
	s_nop 0
	v_cndmask_b32_e32 v144, v144, v145, vcc
	v_rsq_f32_e32 v144, v144
	s_nop 0
	v_mul_f32_e32 v145, 0x45800000, v144
	v_cndmask_b32_e32 v150, v144, v145, vcc
	v_pk_mul_f32 v[120:121], v[120:121], v[150:151] op_sel_hi:[1,0]
	v_pk_mul_f32 v[124:125], v[124:125], v[150:151] op_sel_hi:[1,0]
	v_pk_mul_f32 v[122:123], v[122:123], v[150:151] op_sel_hi:[1,0]
	v_max_f32_e32 v120, 0, v120
	v_lshlrev_b64 v[144:145], 14, v[142:143]
	v_pk_mul_f32 v[126:127], v[126:127], v[150:151] op_sel_hi:[1,0]
	v_mul_f32_e32 v143, v120, v120
	v_max_f32_e32 v120, 0, v125
	v_max_f32_e32 v121, 0, v121
	v_max_f32_e32 v122, 0, v122
	v_lshl_add_u64 v[152:153], s[14:15], 0, v[144:145]
	v_lshlrev_b64 v[144:145], 1, v[140:141]
	v_max_f32_e32 v124, 0, v124
	v_mul_f32_e32 v120, v120, v120
	v_mul_f32_e32 v125, v121, v121
	v_max_f32_e32 v121, 0, v126
	v_mul_f32_e32 v126, v122, v122
	v_max_f32_e32 v122, 0, v127
	v_max_f32_e32 v123, 0, v123
	v_pk_mul_f32 v[114:115], v[114:115], v[150:151] op_sel_hi:[1,0]
	v_pk_mul_f32 v[112:113], v[112:113], v[150:151] op_sel_hi:[1,0]
	v_lshl_add_u64 v[140:141], v[152:153], 0, v[144:145]
	v_mul_f32_e32 v124, v124, v124
	v_mul_f32_e32 v121, v121, v121
	v_mul_f32_e32 v122, v122, v122
	v_mul_f32_e32 v123, v123, v123
	v_cvt_pk_bf16_f32 v120, v124, v120
	v_pk_mul_f32 v[118:119], v[118:119], v[150:151] op_sel_hi:[1,0]
	v_pk_mul_f32 v[116:117], v[116:117], v[150:151] op_sel_hi:[1,0]
	v_max_f32_e32 v112, 0, v112
	v_max_f32_e32 v113, 0, v113
	v_max_f32_e32 v114, 0, v114
	v_cvt_pk_bf16_f32 v121, v121, v122
	v_cvt_pk_bf16_f32 v122, v143, v125
	v_cvt_pk_bf16_f32 v123, v126, v123
	global_store_dwordx4 v[140:141], v[120:123], off
	v_max_f32_e32 v115, 0, v115
	v_max_f32_e32 v116, 0, v116
	v_mul_f32_e32 v120, v112, v112
	v_max_f32_e32 v112, 0, v117
	v_mul_f32_e32 v117, v113, v113
	v_max_f32_e32 v113, 0, v118
	v_mul_f32_e32 v118, v114, v114
	v_max_f32_e32 v114, 0, v119
	v_mul_f32_e32 v112, v112, v112
	v_mul_f32_e32 v113, v113, v113
	v_mul_f32_e32 v114, v114, v114
	v_mul_f32_e32 v115, v115, v115
; __device__ __forceinline__ unsigned cvt_pk_bf16(float lo, float hi) { unsigned r; asm volatile("v_cvt_pk_bf16_f32 %0, %1, %2" : "=v"(r) : "v"(lo), "v"(hi)); return r; }
; __device__ __forceinline__ float rinv_st(stat_t s, float invn) { return rsqrtf((float)((double)s * (1.0 / 4294967296.0)) * invn + 1e-6f); }
;     __device__ __forceinline__ void operator()(const f32x4 (&acc)[2][2][4][2], const Unit& u, int wr, int wc, int fr, int fq) const {
;     ...
;                 const int row = row0 + ai * HALF + m * 16; const float r = rinv_st(stats[row], 1.0f / 2048.0f);
;                 bf16_t* rowp = U + (size_t)row * FF + col0;
; #pragma unroll
;                 for (int bj = 0; bj < 2; ++bj) {
;                     f32x4 v0 = acc[ai][bj][m][0] * r, v1 = acc[ai][bj][m][1] * r;
; #pragma unroll
;                     for (int j = 0; j < 4; ++j) { const float a = fmaxf(v0[j], 0.f), b = fmaxf(v1[j], 0.f); v0[j] = a * a; v1[j] = b * b; }
;                     u32x4 w; w.x = cvt_pk_bf16(v0[0], v0[1]); w.y = cvt_pk_bf16(v0[2], v0[3]); w.z = cvt_pk_bf16(v1[0], v1[1]); w.w = cvt_pk_bf16(v1[2], v1[3]);
;                     *(u32x4*)(rowp + bj * HALF) = w;
	v_mul_f32_e32 v116, v116, v116
	v_cvt_pk_bf16_f32 v112, v116, v112
	v_cvt_pk_bf16_f32 v113, v113, v114
	v_cvt_pk_bf16_f32 v114, v120, v117
	v_cvt_pk_bf16_f32 v115, v118, v115
	global_store_dwordx4 v[140:141], v[112:115], off offset:256
	s_nop 1
	v_mov_b64_e32 v[114:115], v[238:239]
	v_cvt_f64_u32_e32 v[116:117], v115
	v_ldexp_f64 v[116:117], v[116:117], 32
	v_cvt_f64_u32_e32 v[114:115], v114
	v_add_f64 v[114:115], v[116:117], v[114:115]
	v_ldexp_f64 v[114:115], v[114:115], s93
	v_cvt_f32_f64_e32 v114, v[114:115]
	v_fmamk_f32 v114, v114, 0x3a000000, v189
	v_cmp_gt_f32_e32 vcc, s78, v114
	v_mul_f32_e32 v115, 0x4b800000, v114
	v_or_b32_e32 v112, 16, v142
	v_cndmask_b32_e32 v114, v114, v115, vcc
	v_rsq_f32_e32 v114, v114
	v_ashrrev_i32_e32 v113, 31, v112
	v_lshlrev_b64 v[112:113], 14, v[112:113]
	v_lshl_add_u64 v[112:113], s[14:15], 0, v[112:113]
	v_mul_f32_e32 v115, 0x45800000, v114
	v_cndmask_b32_e32 v114, v114, v115, vcc
	v_pk_mul_f32 v[104:105], v[104:105], v[114:115] op_sel_hi:[1,0]
	v_pk_mul_f32 v[108:109], v[108:109], v[114:115] op_sel_hi:[1,0]
	v_pk_mul_f32 v[106:107], v[106:107], v[114:115] op_sel_hi:[1,0]
	v_max_f32_e32 v104, 0, v104
	v_pk_mul_f32 v[110:111], v[110:111], v[114:115] op_sel_hi:[1,0]
	v_mul_f32_e32 v115, v104, v104
	v_max_f32_e32 v104, 0, v109
	v_max_f32_e32 v105, 0, v105
	v_max_f32_e32 v106, 0, v106
	v_max_f32_e32 v108, 0, v108
	v_mul_f32_e32 v104, v104, v104
	v_mul_f32_e32 v109, v105, v105
	v_max_f32_e32 v105, 0, v110
	v_mul_f32_e32 v110, v106, v106
	v_max_f32_e32 v106, 0, v111
	v_max_f32_e32 v107, 0, v107
	v_pk_mul_f32 v[98:99], v[98:99], v[114:115] op_sel_hi:[1,0]
	v_pk_mul_f32 v[96:97], v[96:97], v[114:115] op_sel_hi:[1,0]
	v_lshl_add_u64 v[112:113], v[112:113], 0, v[144:145]
	v_mul_f32_e32 v108, v108, v108
	v_mul_f32_e32 v105, v105, v105
	v_mul_f32_e32 v106, v106, v106
	v_mul_f32_e32 v107, v107, v107
	v_cvt_pk_bf16_f32 v104, v108, v104
	v_pk_mul_f32 v[102:103], v[102:103], v[114:115] op_sel_hi:[1,0]
	v_pk_mul_f32 v[100:101], v[100:101], v[114:115] op_sel_hi:[1,0]
	v_max_f32_e32 v96, 0, v96
	v_max_f32_e32 v97, 0, v97
	v_max_f32_e32 v98, 0, v98
	v_cvt_pk_bf16_f32 v105, v105, v106
	v_cvt_pk_bf16_f32 v106, v115, v109
	v_cvt_pk_bf16_f32 v107, v110, v107
	global_store_dwordx4 v[112:113], v[104:107], off
	v_max_f32_e32 v99, 0, v99
	v_max_f32_e32 v100, 0, v100
	v_mul_f32_e32 v104, v96, v96
	v_max_f32_e32 v96, 0, v101
	v_mul_f32_e32 v101, v97, v97
	v_max_f32_e32 v97, 0, v102
	v_mul_f32_e32 v102, v98, v98
	v_max_f32_e32 v98, 0, v103
	v_mul_f32_e32 v96, v96, v96
	v_mul_f32_e32 v97, v97, v97
	v_mul_f32_e32 v98, v98, v98
	v_mul_f32_e32 v99, v99, v99
	v_mul_f32_e32 v100, v100, v100
	v_cvt_pk_bf16_f32 v96, v100, v96
	v_cvt_pk_bf16_f32 v97, v97, v98
	v_cvt_pk_bf16_f32 v98, v104, v101
	v_cvt_pk_bf16_f32 v99, v102, v99
	global_store_dwordx4 v[112:113], v[96:99], off offset:256
	s_nop 1
	v_mov_b64_e32 v[98:99], v[240:241]
	v_cvt_f64_u32_e32 v[100:101], v99
	v_ldexp_f64 v[100:101], v[100:101], 32
	v_cvt_f64_u32_e32 v[98:99], v98
	v_add_f64 v[98:99], v[100:101], v[98:99]
	v_ldexp_f64 v[98:99], v[98:99], s93
	v_cvt_f32_f64_e32 v98, v[98:99]
	v_fmamk_f32 v98, v98, 0x3a000000, v189
	v_cmp_gt_f32_e32 vcc, s78, v98
	v_mul_f32_e32 v99, 0x4b800000, v98
	v_or_b32_e32 v96, 32, v142
	v_cndmask_b32_e32 v98, v98, v99, vcc
	v_rsq_f32_e32 v98, v98
	v_ashrrev_i32_e32 v97, 31, v96
	v_lshlrev_b64 v[96:97], 14, v[96:97]
	v_lshl_add_u64 v[96:97], s[14:15], 0, v[96:97]
	v_mul_f32_e32 v99, 0x45800000, v98
	v_cndmask_b32_e32 v98, v98, v99, vcc
	v_pk_mul_f32 v[88:89], v[88:89], v[98:99] op_sel_hi:[1,0]
	v_pk_mul_f32 v[92:93], v[92:93], v[98:99] op_sel_hi:[1,0]
	v_pk_mul_f32 v[90:91], v[90:91], v[98:99] op_sel_hi:[1,0]
	v_max_f32_e32 v88, 0, v88
	v_pk_mul_f32 v[94:95], v[94:95], v[98:99] op_sel_hi:[1,0]
	v_mul_f32_e32 v99, v88, v88
	v_max_f32_e32 v88, 0, v93
	v_max_f32_e32 v89, 0, v89
	v_max_f32_e32 v90, 0, v90
	v_max_f32_e32 v92, 0, v92
	v_mul_f32_e32 v88, v88, v88
	v_mul_f32_e32 v93, v89, v89
	v_max_f32_e32 v89, 0, v94
	v_mul_f32_e32 v94, v90, v90
	v_max_f32_e32 v90, 0, v95
	v_max_f32_e32 v91, 0, v91
	v_pk_mul_f32 v[82:83], v[82:83], v[98:99] op_sel_hi:[1,0]
	v_pk_mul_f32 v[80:81], v[80:81], v[98:99] op_sel_hi:[1,0]
	v_lshl_add_u64 v[96:97], v[96:97], 0, v[144:145]
	v_mul_f32_e32 v92, v92, v92
	v_mul_f32_e32 v89, v89, v89
	v_mul_f32_e32 v90, v90, v90
	v_mul_f32_e32 v91, v91, v91
	v_cvt_pk_bf16_f32 v88, v92, v88
	v_pk_mul_f32 v[86:87], v[86:87], v[98:99] op_sel_hi:[1,0]
	v_pk_mul_f32 v[84:85], v[84:85], v[98:99] op_sel_hi:[1,0]
	v_max_f32_e32 v80, 0, v80
	v_max_f32_e32 v81, 0, v81
	v_max_f32_e32 v82, 0, v82
	v_cvt_pk_bf16_f32 v89, v89, v90
	v_cvt_pk_bf16_f32 v90, v99, v93
	v_cvt_pk_bf16_f32 v91, v94, v91
	global_store_dwordx4 v[96:97], v[88:91], off
	v_max_f32_e32 v83, 0, v83
	v_max_f32_e32 v84, 0, v84
	v_mul_f32_e32 v88, v80, v80
	v_max_f32_e32 v80, 0, v85
	v_mul_f32_e32 v85, v81, v81
	v_max_f32_e32 v81, 0, v86
	v_mul_f32_e32 v86, v82, v82
	v_max_f32_e32 v82, 0, v87
	v_mul_f32_e32 v80, v80, v80
	v_mul_f32_e32 v81, v81, v81
	v_mul_f32_e32 v82, v82, v82
	v_mul_f32_e32 v83, v83, v83
	v_mul_f32_e32 v84, v84, v84
	v_cvt_pk_bf16_f32 v80, v84, v80
	v_cvt_pk_bf16_f32 v81, v81, v82
	v_cvt_pk_bf16_f32 v82, v88, v85
	v_cvt_pk_bf16_f32 v83, v86, v83
	global_store_dwordx4 v[96:97], v[80:83], off offset:256
	s_nop 1
	v_mov_b64_e32 v[82:83], v[242:243]
	v_cvt_f64_u32_e32 v[84:85], v83
	v_ldexp_f64 v[84:85], v[84:85], 32
	v_cvt_f64_u32_e32 v[82:83], v82
	v_add_f64 v[82:83], v[84:85], v[82:83]
	v_ldexp_f64 v[82:83], v[82:83], s93
	v_cvt_f32_f64_e32 v82, v[82:83]
	v_fmamk_f32 v82, v82, 0x3a000000, v189
	v_cmp_gt_f32_e32 vcc, s78, v82
	v_mul_f32_e32 v83, 0x4b800000, v82
; __device__ __forceinline__ unsigned cvt_pk_bf16(float lo, float hi) { unsigned r; asm volatile("v_cvt_pk_bf16_f32 %0, %1, %2" : "=v"(r) : "v"(lo), "v"(hi)); return r; }
; __device__ __forceinline__ float rinv_st(stat_t s, float invn) { return rsqrtf((float)((double)s * (1.0 / 4294967296.0)) * invn + 1e-6f); }
;     __device__ __forceinline__ void operator()(const f32x4 (&acc)[2][2][4][2], const Unit& u, int wr, int wc, int fr, int fq) const {
;     ...
;                 const int row = row0 + ai * HALF + m * 16; const float r = rinv_st(stats[row], 1.0f / 2048.0f);
;                 bf16_t* rowp = U + (size_t)row * FF + col0;
; #pragma unroll
;                 for (int bj = 0; bj < 2; ++bj) {
;                     f32x4 v0 = acc[ai][bj][m][0] * r, v1 = acc[ai][bj][m][1] * r;
; #pragma unroll
;                     for (int j = 0; j < 4; ++j) { const float a = fmaxf(v0[j], 0.f), b = fmaxf(v1[j], 0.f); v0[j] = a * a; v1[j] = b * b; }
;                     u32x4 w; w.x = cvt_pk_bf16(v0[0], v0[1]); w.y = cvt_pk_bf16(v0[2], v0[3]); w.z = cvt_pk_bf16(v1[0], v1[1]); w.w = cvt_pk_bf16(v1[2], v1[3]);
;                     *(u32x4*)(rowp + bj * HALF) = w;
	v_or_b32_e32 v80, 48, v142
	v_cndmask_b32_e32 v82, v82, v83, vcc
	v_rsq_f32_e32 v82, v82
	v_ashrrev_i32_e32 v81, 31, v80
	v_lshlrev_b64 v[80:81], 14, v[80:81]
	v_lshl_add_u64 v[80:81], s[14:15], 0, v[80:81]
	v_mul_f32_e32 v83, 0x45800000, v82
	v_cndmask_b32_e32 v82, v82, v83, vcc
	v_pk_mul_f32 v[72:73], v[72:73], v[82:83] op_sel_hi:[1,0]
	v_pk_mul_f32 v[76:77], v[76:77], v[82:83] op_sel_hi:[1,0]
	v_pk_mul_f32 v[74:75], v[74:75], v[82:83] op_sel_hi:[1,0]
	v_max_f32_e32 v72, 0, v72
	v_pk_mul_f32 v[78:79], v[78:79], v[82:83] op_sel_hi:[1,0]
	v_mul_f32_e32 v83, v72, v72
	v_max_f32_e32 v72, 0, v77
	v_max_f32_e32 v73, 0, v73
	v_max_f32_e32 v74, 0, v74
	v_max_f32_e32 v76, 0, v76
	v_mul_f32_e32 v72, v72, v72
	v_mul_f32_e32 v77, v73, v73
	v_max_f32_e32 v73, 0, v78
	v_mul_f32_e32 v78, v74, v74
	v_max_f32_e32 v74, 0, v79
	v_max_f32_e32 v75, 0, v75
	v_pk_mul_f32 v[66:67], v[66:67], v[82:83] op_sel_hi:[1,0]
	v_pk_mul_f32 v[64:65], v[64:65], v[82:83] op_sel_hi:[1,0]
	v_lshl_add_u64 v[80:81], v[80:81], 0, v[144:145]
	v_mul_f32_e32 v76, v76, v76
	v_mul_f32_e32 v73, v73, v73
	v_mul_f32_e32 v74, v74, v74
	v_mul_f32_e32 v75, v75, v75
	v_cvt_pk_bf16_f32 v72, v76, v72
	v_pk_mul_f32 v[70:71], v[70:71], v[82:83] op_sel_hi:[1,0]
	v_pk_mul_f32 v[68:69], v[68:69], v[82:83] op_sel_hi:[1,0]
	v_max_f32_e32 v64, 0, v64
	v_max_f32_e32 v65, 0, v65
	v_max_f32_e32 v66, 0, v66
	v_cvt_pk_bf16_f32 v73, v73, v74
	v_cvt_pk_bf16_f32 v74, v83, v77
	v_cvt_pk_bf16_f32 v75, v78, v75
	global_store_dwordx4 v[80:81], v[72:75], off
	v_max_f32_e32 v67, 0, v67
	v_max_f32_e32 v68, 0, v68
	v_mul_f32_e32 v72, v64, v64
	v_max_f32_e32 v64, 0, v69
	v_mul_f32_e32 v69, v65, v65
	v_max_f32_e32 v65, 0, v70
	v_mul_f32_e32 v70, v66, v66
	v_max_f32_e32 v66, 0, v71
	v_mul_f32_e32 v64, v64, v64
	v_mul_f32_e32 v65, v65, v65
	v_mul_f32_e32 v66, v66, v66
	v_mul_f32_e32 v67, v67, v67
	v_mul_f32_e32 v68, v68, v68
	v_cvt_pk_bf16_f32 v64, v68, v64
	v_cvt_pk_bf16_f32 v65, v65, v66
	v_cvt_pk_bf16_f32 v66, v72, v69
	v_cvt_pk_bf16_f32 v67, v70, v67
	global_store_dwordx4 v[80:81], v[64:67], off offset:256
	s_nop 1
	v_mov_b64_e32 v[64:65], v[244:245]
	v_cvt_f64_u32_e32 v[66:67], v65
	v_ldexp_f64 v[66:67], v[66:67], 32
	v_cvt_f64_u32_e32 v[64:65], v64
	v_add_f64 v[64:65], v[66:67], v[64:65]
	v_ldexp_f64 v[64:65], v[64:65], s93
	v_cvt_f32_f64_e32 v64, v[64:65]
	v_fmamk_f32 v64, v64, 0x3a000000, v189
	v_cmp_gt_f32_e32 vcc, s78, v64
	v_mul_f32_e32 v65, 0x4b800000, v64
	s_nop 0
	v_cndmask_b32_e32 v64, v64, v65, vcc
	v_rsq_f32_e32 v64, v64
	s_nop 0
	v_mul_f32_e32 v65, 0x45800000, v64
	v_cndmask_b32_e32 v66, v64, v65, vcc
	v_pk_mul_f32 v[56:57], v[56:57], v[66:67] op_sel_hi:[1,0]
	v_pk_mul_f32 v[60:61], v[60:61], v[66:67] op_sel_hi:[1,0]
	v_pk_mul_f32 v[58:59], v[58:59], v[66:67] op_sel_hi:[1,0]
	v_max_f32_e32 v56, 0, v56
	v_pk_mul_f32 v[62:63], v[62:63], v[66:67] op_sel_hi:[1,0]
	v_max_f32_e32 v60, 0, v60
	v_mul_f32_e32 v67, v56, v56
	v_max_f32_e32 v56, 0, v61
	v_max_f32_e32 v57, 0, v57
	v_max_f32_e32 v58, 0, v58
	v_lshl_add_u64 v[64:65], v[140:141], 0, s[0:1]
	v_mul_f32_e32 v60, v60, v60
	v_mul_f32_e32 v56, v56, v56
	v_mul_f32_e32 v61, v57, v57
	v_max_f32_e32 v57, 0, v62
	v_mul_f32_e32 v62, v58, v58
	v_max_f32_e32 v58, 0, v63
	s_mov_b32 s0, 0x200000
	v_mul_f32_e32 v57, v57, v57
	v_max_f32_e32 v59, 0, v59
	v_mul_f32_e32 v58, v58, v58
	v_cvt_pk_bf16_f32 v56, v60, v56
	v_add_co_u32_e32 v60, vcc, s0, v140
	v_pk_mul_f32 v[50:51], v[50:51], v[66:67] op_sel_hi:[1,0]
	v_pk_mul_f32 v[48:49], v[48:49], v[66:67] op_sel_hi:[1,0]
	v_mul_f32_e32 v59, v59, v59
	v_cvt_pk_bf16_f32 v57, v57, v58
	v_cvt_pk_bf16_f32 v58, v67, v61
	v_addc_co_u32_e32 v61, vcc, 0, v141, vcc
	v_pk_mul_f32 v[54:55], v[54:55], v[66:67] op_sel_hi:[1,0]
	v_pk_mul_f32 v[52:53], v[52:53], v[66:67] op_sel_hi:[1,0]
	v_max_f32_e32 v48, 0, v48
	v_max_f32_e32 v49, 0, v49
	v_max_f32_e32 v50, 0, v50
	v_cvt_pk_bf16_f32 v59, v62, v59
	global_store_dwordx4 v[60:61], v[56:59], off
	v_max_f32_e32 v51, 0, v51
	v_max_f32_e32 v52, 0, v52
	v_mul_f32_e32 v56, v48, v48
	v_max_f32_e32 v48, 0, v53
	v_mul_f32_e32 v53, v49, v49
	v_max_f32_e32 v49, 0, v54
	v_mul_f32_e32 v54, v50, v50
	v_max_f32_e32 v50, 0, v55
	v_mul_f32_e32 v48, v48, v48
	v_mul_f32_e32 v49, v49, v49
	v_mul_f32_e32 v50, v50, v50
	v_mul_f32_e32 v51, v51, v51
	v_mul_f32_e32 v52, v52, v52
	v_cvt_pk_bf16_f32 v48, v52, v48
	v_cvt_pk_bf16_f32 v49, v49, v50
	v_cvt_pk_bf16_f32 v50, v56, v53
	v_cvt_pk_bf16_f32 v51, v54, v51
	global_store_dwordx4 v[64:65], v[48:51], off offset:256
	s_nop 1
	v_mov_b64_e32 v[48:49], v[246:247]
	s_mov_b64 s[0:1], 0x240000
	v_cvt_f64_u32_e32 v[50:51], v49
	v_ldexp_f64 v[50:51], v[50:51], 32
	v_cvt_f64_u32_e32 v[48:49], v48
	v_add_f64 v[48:49], v[50:51], v[48:49]
	v_ldexp_f64 v[48:49], v[48:49], s93
	v_cvt_f32_f64_e32 v48, v[48:49]
	v_fmamk_f32 v48, v48, 0x3a000000, v189
	v_cmp_gt_f32_e32 vcc, s78, v48
	v_mul_f32_e32 v49, 0x4b800000, v48
	s_nop 0
	v_cndmask_b32_e32 v48, v48, v49, vcc
	v_rsq_f32_e32 v48, v48
	s_nop 0
	v_mul_f32_e32 v49, 0x45800000, v48
	v_cndmask_b32_e32 v50, v48, v49, vcc
	v_pk_mul_f32 v[40:41], v[40:41], v[50:51] op_sel_hi:[1,0]
	v_pk_mul_f32 v[44:45], v[44:45], v[50:51] op_sel_hi:[1,0]
	v_pk_mul_f32 v[42:43], v[42:43], v[50:51] op_sel_hi:[1,0]
	v_max_f32_e32 v40, 0, v40
	v_pk_mul_f32 v[46:47], v[46:47], v[50:51] op_sel_hi:[1,0]
	v_max_f32_e32 v44, 0, v44
	v_mul_f32_e32 v51, v40, v40
	v_max_f32_e32 v40, 0, v45
	v_max_f32_e32 v41, 0, v41
	v_max_f32_e32 v42, 0, v42
	v_lshl_add_u64 v[48:49], v[140:141], 0, s[0:1]
	v_mul_f32_e32 v44, v44, v44
	v_mul_f32_e32 v40, v40, v40
	v_mul_f32_e32 v45, v41, v41
	v_max_f32_e32 v41, 0, v46
	v_mul_f32_e32 v46, v42, v42
	v_max_f32_e32 v42, 0, v47
; __device__ __forceinline__ unsigned cvt_pk_bf16(float lo, float hi) { unsigned r; asm volatile("v_cvt_pk_bf16_f32 %0, %1, %2" : "=v"(r) : "v"(lo), "v"(hi)); return r; }
; __device__ __forceinline__ float rinv_st(stat_t s, float invn) { return rsqrtf((float)((double)s * (1.0 / 4294967296.0)) * invn + 1e-6f); }
; #define PG8_WAIT_V(n) asm volatile("s_waitcnt vmcnt(" #n ")" ::: "memory")
; #define PG8_BAR __builtin_amdgcn_s_barrier()
; template <class Epi>
; __device__ __forceinline__ void gemm_phase(const int TID, const int BID, LAS unsigned char* lds, const Gemm g, const StaticOrder& S, const Epi& E) {
;     ...
;         if (!has_next) break;
; #pragma unroll
;         for (int a = 0; a < 2; ++a)
; #pragma unroll
;             for (int b = 0; b < 2; ++b)
; #pragma unroll
;                 for (int m = 0; m < 4; ++m)
; #pragma unroll
;                     for (int n = 0; n < 2; ++n) acc[a][b][m][n] = (f32x4){0.f, 0.f, 0.f, 0.f};
;         cur = nxt; cA = nA; cB = nB; ++ui;
;     }
;     PG8_WAIT_V(0);
;     if (wr == 0) PG8_BAR;
;     PG8_BAR;
;     __device__ __forceinline__ void operator()(const f32x4 (&acc)[2][2][4][2], const Unit& u, int wr, int wc, int fr, int fq) const {
;         const int row0 = u.pm * BM + wr * 64 + fr, col0 = u.pn * BM + wc * 32 + 8 * fq;
; #pragma unroll
;         for (int ai = 0; ai < 2; ++ai)
; #pragma unroll
;             for (int m = 0; m < 4; ++m) {
;                 const int row = row0 + ai * HALF + m * 16; const float r = rinv_st(stats[row], 1.0f / 2048.0f);
;                 bf16_t* rowp = U + (size_t)row * FF + col0;
; #pragma unroll
;                 for (int bj = 0; bj < 2; ++bj) {
;                     f32x4 v0 = acc[ai][bj][m][0] * r, v1 = acc[ai][bj][m][1] * r;
; #pragma unroll
;                     for (int j = 0; j < 4; ++j) { const float a = fmaxf(v0[j], 0.f), b = fmaxf(v1[j], 0.f); v0[j] = a * a; v1[j] = b * b; }
;                     u32x4 w; w.x = cvt_pk_bf16(v0[0], v0[1]); w.y = cvt_pk_bf16(v0[2], v0[3]); w.z = cvt_pk_bf16(v1[0], v1[1]); w.w = cvt_pk_bf16(v1[2], v1[3]);
;                     *(u32x4*)(rowp + bj * HALF) = w;
	s_mov_b32 s0, 0x240000
	v_mul_f32_e32 v41, v41, v41
	v_max_f32_e32 v43, 0, v43
	v_mul_f32_e32 v42, v42, v42
	v_cvt_pk_bf16_f32 v40, v44, v40
	v_add_co_u32_e32 v44, vcc, s0, v140
	v_pk_mul_f32 v[34:35], v[34:35], v[50:51] op_sel_hi:[1,0]
	v_pk_mul_f32 v[32:33], v[32:33], v[50:51] op_sel_hi:[1,0]
	v_mul_f32_e32 v43, v43, v43
	v_cvt_pk_bf16_f32 v41, v41, v42
	v_cvt_pk_bf16_f32 v42, v51, v45
	v_addc_co_u32_e32 v45, vcc, 0, v141, vcc
	v_pk_mul_f32 v[38:39], v[38:39], v[50:51] op_sel_hi:[1,0]
	v_pk_mul_f32 v[36:37], v[36:37], v[50:51] op_sel_hi:[1,0]
	v_max_f32_e32 v32, 0, v32
	v_max_f32_e32 v33, 0, v33
	v_max_f32_e32 v34, 0, v34
	v_cvt_pk_bf16_f32 v43, v46, v43
	global_store_dwordx4 v[44:45], v[40:43], off
	v_max_f32_e32 v35, 0, v35
	v_max_f32_e32 v36, 0, v36
	v_mul_f32_e32 v40, v32, v32
	v_max_f32_e32 v32, 0, v37
	v_mul_f32_e32 v37, v33, v33
	v_max_f32_e32 v33, 0, v38
	v_mul_f32_e32 v38, v34, v34
	v_max_f32_e32 v34, 0, v39
	v_mul_f32_e32 v32, v32, v32
	v_mul_f32_e32 v33, v33, v33
	v_mul_f32_e32 v34, v34, v34
	v_mul_f32_e32 v35, v35, v35
	v_mul_f32_e32 v36, v36, v36
	v_cvt_pk_bf16_f32 v32, v36, v32
	v_cvt_pk_bf16_f32 v33, v33, v34
	v_cvt_pk_bf16_f32 v34, v40, v37
	v_cvt_pk_bf16_f32 v35, v38, v35
	global_store_dwordx4 v[48:49], v[32:35], off offset:256
	s_nop 1
	v_mov_b64_e32 v[32:33], v[248:249]
	s_mov_b64 s[0:1], 0x280000
	v_cvt_f64_u32_e32 v[34:35], v33
	v_ldexp_f64 v[34:35], v[34:35], 32
	v_cvt_f64_u32_e32 v[32:33], v32
	v_add_f64 v[32:33], v[34:35], v[32:33]
	v_ldexp_f64 v[32:33], v[32:33], s93
	v_cvt_f32_f64_e32 v32, v[32:33]
	v_fmamk_f32 v32, v32, 0x3a000000, v189
	v_cmp_gt_f32_e32 vcc, s78, v32
	v_mul_f32_e32 v33, 0x4b800000, v32
	s_nop 0
	v_cndmask_b32_e32 v32, v32, v33, vcc
	v_rsq_f32_e32 v32, v32
	s_nop 0
	v_mul_f32_e32 v33, 0x45800000, v32
	v_cndmask_b32_e32 v34, v32, v33, vcc
	v_pk_mul_f32 v[24:25], v[24:25], v[34:35] op_sel_hi:[1,0]
	v_pk_mul_f32 v[28:29], v[28:29], v[34:35] op_sel_hi:[1,0]
	v_pk_mul_f32 v[26:27], v[26:27], v[34:35] op_sel_hi:[1,0]
	v_max_f32_e32 v24, 0, v24
	v_pk_mul_f32 v[30:31], v[30:31], v[34:35] op_sel_hi:[1,0]
	v_max_f32_e32 v28, 0, v28
	v_mul_f32_e32 v35, v24, v24
	v_max_f32_e32 v24, 0, v29
	v_max_f32_e32 v25, 0, v25
	v_max_f32_e32 v26, 0, v26
	v_lshl_add_u64 v[32:33], v[140:141], 0, s[0:1]
	v_mul_f32_e32 v28, v28, v28
	v_mul_f32_e32 v24, v24, v24
	v_mul_f32_e32 v29, v25, v25
	v_max_f32_e32 v25, 0, v30
	v_mul_f32_e32 v30, v26, v26
	v_max_f32_e32 v26, 0, v31
	s_mov_b32 s0, 0x280000
	v_mul_f32_e32 v25, v25, v25
	v_max_f32_e32 v27, 0, v27
	v_mul_f32_e32 v26, v26, v26
	v_cvt_pk_bf16_f32 v24, v28, v24
	v_add_co_u32_e32 v28, vcc, s0, v140
	v_pk_mul_f32 v[18:19], v[18:19], v[34:35] op_sel_hi:[1,0]
	v_pk_mul_f32 v[16:17], v[16:17], v[34:35] op_sel_hi:[1,0]
	v_mul_f32_e32 v27, v27, v27
	v_cvt_pk_bf16_f32 v25, v25, v26
	v_cvt_pk_bf16_f32 v26, v35, v29
	v_addc_co_u32_e32 v29, vcc, 0, v141, vcc
	v_pk_mul_f32 v[22:23], v[22:23], v[34:35] op_sel_hi:[1,0]
	v_pk_mul_f32 v[20:21], v[20:21], v[34:35] op_sel_hi:[1,0]
	v_max_f32_e32 v16, 0, v16
	v_max_f32_e32 v17, 0, v17
	v_max_f32_e32 v18, 0, v18
	v_cvt_pk_bf16_f32 v27, v30, v27
	global_store_dwordx4 v[28:29], v[24:27], off
	v_max_f32_e32 v19, 0, v19
	v_max_f32_e32 v20, 0, v20
	v_mul_f32_e32 v24, v16, v16
	v_max_f32_e32 v16, 0, v21
	v_mul_f32_e32 v21, v17, v17
	v_max_f32_e32 v17, 0, v22
	v_mul_f32_e32 v22, v18, v18
	v_max_f32_e32 v18, 0, v23
	v_mul_f32_e32 v16, v16, v16
	v_mul_f32_e32 v17, v17, v17
	v_mul_f32_e32 v18, v18, v18
	v_mul_f32_e32 v19, v19, v19
	v_mul_f32_e32 v20, v20, v20
	v_cvt_pk_bf16_f32 v16, v20, v16
	v_cvt_pk_bf16_f32 v17, v17, v18
	v_cvt_pk_bf16_f32 v18, v24, v21
	v_cvt_pk_bf16_f32 v19, v22, v19
	global_store_dwordx4 v[32:33], v[16:19], off offset:256
	s_nop 1
	v_mov_b64_e32 v[16:17], v[250:251]
	s_mov_b64 s[0:1], 0x2c0000
	v_cvt_f64_u32_e32 v[18:19], v17
	v_ldexp_f64 v[18:19], v[18:19], 32
	v_cvt_f64_u32_e32 v[16:17], v16
	v_add_f64 v[16:17], v[18:19], v[16:17]
	v_ldexp_f64 v[16:17], v[16:17], s93
	v_cvt_f32_f64_e32 v16, v[16:17]
	v_fmamk_f32 v16, v16, 0x3a000000, v189
	v_cmp_gt_f32_e32 vcc, s78, v16
	v_mul_f32_e32 v17, 0x4b800000, v16
	v_lshl_add_u64 v[18:19], v[140:141], 0, s[0:1]
	v_cndmask_b32_e32 v16, v16, v17, vcc
	v_rsq_f32_e32 v16, v16
	s_mov_b32 s0, 0x2c0000
	v_mul_f32_e32 v17, 0x45800000, v16
	v_cndmask_b32_e32 v16, v16, v17, vcc
	v_pk_mul_f32 v[8:9], v[8:9], v[16:17] op_sel_hi:[1,0]
	v_pk_mul_f32 v[12:13], v[12:13], v[16:17] op_sel_hi:[1,0]
	v_pk_mul_f32 v[10:11], v[10:11], v[16:17] op_sel_hi:[1,0]
	v_max_f32_e32 v8, 0, v8
	v_pk_mul_f32 v[14:15], v[14:15], v[16:17] op_sel_hi:[1,0]
	v_max_f32_e32 v12, 0, v12
	v_mul_f32_e32 v17, v8, v8
	v_max_f32_e32 v8, 0, v13
	v_max_f32_e32 v9, 0, v9
	v_max_f32_e32 v10, 0, v10
	v_mul_f32_e32 v12, v12, v12
	v_mul_f32_e32 v8, v8, v8
	v_mul_f32_e32 v13, v9, v9
	v_max_f32_e32 v9, 0, v14
	v_mul_f32_e32 v14, v10, v10
	v_max_f32_e32 v10, 0, v15
	v_mul_f32_e32 v9, v9, v9
	v_max_f32_e32 v11, 0, v11
	v_mul_f32_e32 v10, v10, v10
	v_cvt_pk_bf16_f32 v8, v12, v8
	v_add_co_u32_e32 v12, vcc, s0, v140
	v_pk_mul_f32 v[2:3], v[2:3], v[16:17] op_sel_hi:[1,0]
	v_pk_mul_f32 v[0:1], v[0:1], v[16:17] op_sel_hi:[1,0]
	v_mul_f32_e32 v11, v11, v11
	v_cvt_pk_bf16_f32 v9, v9, v10
	v_cvt_pk_bf16_f32 v10, v17, v13
	v_addc_co_u32_e32 v13, vcc, 0, v141, vcc
	v_pk_mul_f32 v[6:7], v[6:7], v[16:17] op_sel_hi:[1,0]
	v_pk_mul_f32 v[4:5], v[4:5], v[16:17] op_sel_hi:[1,0]
	v_max_f32_e32 v0, 0, v0
	v_max_f32_e32 v1, 0, v1
	v_max_f32_e32 v2, 0, v2
	v_cvt_pk_bf16_f32 v11, v14, v11
	global_store_dwordx4 v[12:13], v[8:11], off
	v_max_f32_e32 v3, 0, v3
	v_max_f32_e32 v4, 0, v4
	v_mul_f32_e32 v8, v0, v0
	v_max_f32_e32 v0, 0, v5
	v_mul_f32_e32 v5, v1, v1
	v_max_f32_e32 v1, 0, v6
	v_mul_f32_e32 v6, v2, v2
	v_max_f32_e32 v2, 0, v7
	v_mul_f32_e32 v0, v0, v0
	v_mul_f32_e32 v1, v1, v1
	v_mul_f32_e32 v2, v2, v2
	v_mul_f32_e32 v3, v3, v3
	s_and_b64 vcc, exec, s[8:9]
	s_mov_b32 s0, s16
	v_mul_f32_e32 v4, v4, v4
	v_cvt_pk_bf16_f32 v0, v4, v0
	v_cvt_pk_bf16_f32 v1, v1, v2
	v_cvt_pk_bf16_f32 v2, v8, v5
	v_cvt_pk_bf16_f32 v3, v6, v3
	global_store_dwordx4 v[18:19], v[0:3], off offset:256
	s_cbranch_vccz .LBB0_918
	s_waitcnt vmcnt(0)
	s_cmpk_gt_u32 s42, 0xff
	s_cbranch_scc1 .LBB0_929
	s_barrier
